# GEMM loops: single-use 64-bit address adds folded into SGPR-base LDS-DMA loads (8 of 16 per K-iteration)
# speedup vs baseline: 1.0081x; 1.0081x over previous
; #define PG8_STAGE(bufoff, gbase, voff) do { _Pragma("unroll") for (int _i = 0; _i < 2; ++_i) \
;         __builtin_amdgcn_global_load_lds((const unsigned*)((const char*)(gbase) + (voff)[_i]), (LAS unsigned*)(lds + (bufoff) + ldsw + _i * 8192), 16, 0, 0); } while (0)
; #define PG8_LDA(dst, b, h) do { _Pragma("unroll") for (int m = 0; m < 4; ++m) _Pragma("unroll") for (int k = 0; k < 2; ++k) dst[m][k] = *(const LAS bf16x8*)(lds + PG8_SA(b, h) + aoff + m * 2048 + k * 1024); } while (0)
; #define PG8_LDB(dst, b, h) do { _Pragma("unroll") for (int n = 0; n < 2; ++n) _Pragma("unroll") for (int k = 0; k < 2; ++k) dst[n][k] = *(const LAS bf16x8*)(lds + PG8_SB(b, h) + boff + n * 2048 + k * 1024); } while (0)
; #define PG8_MMA(ai, bj, At, Bt) do { __builtin_amdgcn_s_setprio(1); _Pragma("unroll") for (int m = 0; m < 4; ++m) _Pragma("unroll") for (int n = 0; n < 2; ++n) _Pragma("unroll") for (int k = 0; k < 2; ++k) \
;         acc[ai][bj][m][n] = __builtin_amdgcn_mfma_f32_16x16x32_bf16(Bt[n][k], At[m][k], acc[ai][bj][m][n], 0, 0, 0); __builtin_amdgcn_s_setprio(0); } while (0)
; #define PG8_WAIT_V(n) asm volatile("s_waitcnt vmcnt(" #n ")" ::: "memory")
; #define PG8_WAIT_L(n) asm volatile("s_waitcnt lgkmcnt(" #n ")" ::: "memory")
; #define PG8_BAR __builtin_amdgcn_s_barrier()
; #define PG8_SCHED __builtin_amdgcn_sched_barrier(0)
; template <class Epi, class Sched, bool ALIGN_EPI = false, bool SP2 = false>
; __device__ __forceinline__ void gemm_phase(LAS unsigned char* lds, const Gemm g, const Sched S, const Epi E) {
;     ...
;             PG8_LDB(B0, 0, 0); PG8_LDB(B1, 0, 1); PG8_SCHED; PG8_LDA(At, 0, 0); PG8_STAGE(PG8_SA(1, 1), a1 + hstepA, voffA);
;             PG8_WAIT_V(8); PG8_WAIT_L(0); PG8_BAR; PG8_MMA(0, 0, At, B0); PG8_MMA(0, 1, At, B1); PG8_BAR; PG8_SCHED;
;             PG8_LDA(At, 0, 1); PG8_STAGE(PG8_SB(0, 0), b2, voffB); PG8_STAGE(PG8_SB(0, 1), b2 + hstepB, voffB); PG8_STAGE(PG8_SA(0, 0), a2, voffA);
;             PG8_WAIT_V(8); PG8_WAIT_L(0); PG8_BAR; PG8_MMA(1, 0, At, B0); PG8_MMA(1, 1, At, B1); PG8_BAR; PG8_SCHED;
.LBB0_623:
	ds_read_b128 v[152:155], v149
	ds_read_b128 v[156:159], v149 offset:1024
	ds_read_b128 v[160:163], v149 offset:2048
	ds_read_b128 v[164:167], v149 offset:3072
	ds_read_b128 v[168:171], v150
	ds_read_b128 v[172:175], v150 offset:1024
	ds_read_b128 v[176:179], v150 offset:2048
	ds_read_b128 v[180:183], v150 offset:3072
	s_add_u32 s34, s68, 0xfffc0080
	s_addc_u32 s35, s69, -1
	s_cmp_eq_u32 s84, 12
	s_cselect_b32 s73, s61, s35
	s_cselect_b32 s72, s80, s34
	s_cselect_b32 s71, s51, s83
	s_cselect_b32 s70, s81, s82
	s_add_i32 m0, s29, 0xc000
	ds_read_b128 v[184:187], v151
	ds_read_b128 v[188:191], v151 offset:1024
	ds_read_b128 v[192:195], v151 offset:2048
	ds_read_b128 v[196:199], v151 offset:3072
	ds_read_b128 v[200:203], v151 offset:4096
	ds_read_b128 v[204:207], v151 offset:5120
	ds_read_b128 v[208:211], v151 offset:6144
	ds_read_b128 v[212:215], v151 offset:7168
	global_load_lds_dwordx4 v136, s[68:69]
	s_add_i32 m0, s29, 0xe000
	s_nop 0
	global_load_lds_dwordx4 v138, s[68:69]
	s_waitcnt vmcnt(8)
	s_waitcnt lgkmcnt(0)
	s_barrier
	s_setprio 1
	s_waitcnt lgkmcnt(0)
	v_mfma_f32_16x16x32_bf16 v[124:127], v[152:155], v[184:187], v[124:127]
	v_mfma_f32_16x16x32_bf16 v[120:123], v[160:163], v[184:187], v[120:123]
	v_mfma_f32_16x16x32_bf16 v[108:111], v[152:155], v[192:195], v[108:111]
	v_mfma_f32_16x16x32_bf16 v[104:107], v[160:163], v[192:195], v[104:107]
	v_mfma_f32_16x16x32_bf16 v[92:95], v[152:155], v[200:203], v[92:95]
	v_mfma_f32_16x16x32_bf16 v[88:91], v[160:163], v[200:203], v[88:91]
	v_mfma_f32_16x16x32_bf16 v[76:79], v[152:155], v[208:211], v[76:79]
	v_mfma_f32_16x16x32_bf16 v[72:75], v[160:163], v[208:211], v[72:75]
	v_mfma_f32_16x16x32_bf16 v[124:127], v[156:159], v[188:191], v[124:127]
	v_mfma_f32_16x16x32_bf16 v[120:123], v[164:167], v[188:191], v[120:123]
	v_mfma_f32_16x16x32_bf16 v[108:111], v[156:159], v[196:199], v[108:111]
	v_mfma_f32_16x16x32_bf16 v[104:107], v[164:167], v[196:199], v[104:107]
	v_mfma_f32_16x16x32_bf16 v[92:95], v[156:159], v[204:207], v[92:95]
	v_mfma_f32_16x16x32_bf16 v[88:91], v[164:167], v[204:207], v[88:91]
	v_mfma_f32_16x16x32_bf16 v[76:79], v[156:159], v[212:215], v[76:79]
	v_mfma_f32_16x16x32_bf16 v[72:75], v[164:167], v[212:215], v[72:75]
	s_setprio 0
	s_setprio 1
	v_mfma_f32_16x16x32_bf16 v[116:119], v[168:171], v[184:187], v[116:119]
	v_mfma_f32_16x16x32_bf16 v[112:115], v[176:179], v[184:187], v[112:115]
	v_mfma_f32_16x16x32_bf16 v[100:103], v[168:171], v[192:195], v[100:103]
	v_mfma_f32_16x16x32_bf16 v[96:99], v[176:179], v[192:195], v[96:99]
	v_mfma_f32_16x16x32_bf16 v[84:87], v[168:171], v[200:203], v[84:87]
	v_mfma_f32_16x16x32_bf16 v[80:83], v[176:179], v[200:203], v[80:83]
	v_mfma_f32_16x16x32_bf16 v[68:71], v[168:171], v[208:211], v[68:71]
	v_mfma_f32_16x16x32_bf16 v[64:67], v[176:179], v[208:211], v[64:67]
	v_mfma_f32_16x16x32_bf16 v[116:119], v[172:175], v[188:191], v[116:119]
	v_mfma_f32_16x16x32_bf16 v[112:115], v[180:183], v[188:191], v[112:115]
	v_mfma_f32_16x16x32_bf16 v[100:103], v[172:175], v[196:199], v[100:103]
	v_mfma_f32_16x16x32_bf16 v[96:99], v[180:183], v[196:199], v[96:99]
	v_mfma_f32_16x16x32_bf16 v[84:87], v[172:175], v[204:207], v[84:87]
	v_mfma_f32_16x16x32_bf16 v[80:83], v[180:183], v[204:207], v[80:83]
	v_mfma_f32_16x16x32_bf16 v[68:71], v[172:175], v[212:215], v[68:71]
	v_mfma_f32_16x16x32_bf16 v[64:67], v[180:183], v[212:215], v[64:67]
	s_setprio 0
	s_barrier
	s_add_i32 s34, s76, s20
	v_lshl_add_u64 v[144:145], s[70:71], 0, v[132:133]
	s_mov_b32 m0, s34
	ds_read_b128 v[184:187], v151 offset:16384
	ds_read_b128 v[188:191], v151 offset:17408
	ds_read_b128 v[192:195], v151 offset:18432
	ds_read_b128 v[196:199], v151 offset:19456
	ds_read_b128 v[200:203], v151 offset:20480
	ds_read_b128 v[204:207], v151 offset:21504
	ds_read_b128 v[208:211], v151 offset:22528
	ds_read_b128 v[212:215], v151 offset:23552
	global_load_lds_dwordx4 v[144:145], off
	s_add_i32 m0, s34, 0x2000
	s_add_u32 s34, s70, 0x40000
	v_lshl_add_u64 v[216:217], s[70:71], 0, v[128:129]
	s_addc_u32 s35, s71, 0
	s_add_i32 s85, s77, s20
	global_load_lds_dwordx4 v[216:217], off
	s_mov_b32 m0, s85
	v_lshl_add_u64 v[220:221], s[72:73], 0, v[130:131]
	global_load_lds_dwordx4 v132, s[34:35]
	s_add_i32 m0, s85, 0x2000
	s_nop 0
	global_load_lds_dwordx4 v128, s[34:35]
	v_lshl_add_u64 v[218:219], s[72:73], 0, v[134:135]
	s_mov_b32 m0, s29
	s_nop 0
	global_load_lds_dwordx4 v[218:219], off
	s_mov_b32 m0, s30
	s_nop 0
	global_load_lds_dwordx4 v[220:221], off
	s_waitcnt vmcnt(8)
	s_waitcnt lgkmcnt(0)
	s_barrier
; #define PG8_STAGE(bufoff, gbase, voff) do { _Pragma("unroll") for (int _i = 0; _i < 2; ++_i) \
;         __builtin_amdgcn_global_load_lds((const unsigned*)((const char*)(gbase) + (voff)[_i]), (LAS unsigned*)(lds + (bufoff) + ldsw + _i * 8192), 16, 0, 0); } while (0)
; #define PG8_LDA(dst, b, h) do { _Pragma("unroll") for (int m = 0; m < 4; ++m) _Pragma("unroll") for (int k = 0; k < 2; ++k) dst[m][k] = *(const LAS bf16x8*)(lds + PG8_SA(b, h) + aoff + m * 2048 + k * 1024); } while (0)
; #define PG8_LDB(dst, b, h) do { _Pragma("unroll") for (int n = 0; n < 2; ++n) _Pragma("unroll") for (int k = 0; k < 2; ++k) dst[n][k] = *(const LAS bf16x8*)(lds + PG8_SB(b, h) + boff + n * 2048 + k * 1024); } while (0)
; #define PG8_MMA(ai, bj, At, Bt) do { __builtin_amdgcn_s_setprio(1); _Pragma("unroll") for (int m = 0; m < 4; ++m) _Pragma("unroll") for (int n = 0; n < 2; ++n) _Pragma("unroll") for (int k = 0; k < 2; ++k) \
;         acc[ai][bj][m][n] = __builtin_amdgcn_mfma_f32_16x16x32_bf16(Bt[n][k], At[m][k], acc[ai][bj][m][n], 0, 0, 0); __builtin_amdgcn_s_setprio(0); } while (0)
; #define PG8_WAIT_V(n) asm volatile("s_waitcnt vmcnt(" #n ")" ::: "memory")
; #define PG8_WAIT_L(n) asm volatile("s_waitcnt lgkmcnt(" #n ")" ::: "memory")
; #define PG8_BAR __builtin_amdgcn_s_barrier()
; #define PG8_SCHED __builtin_amdgcn_sched_barrier(0)
; template <class Epi, class Sched, bool ALIGN_EPI = false, bool SP2 = false>
; __device__ __forceinline__ void gemm_phase(LAS unsigned char* lds, const Gemm g, const Sched S, const Epi E) {
;     ...
;             PG8_WAIT_V(8); PG8_WAIT_L(0); PG8_BAR; PG8_MMA(1, 0, At, B0); PG8_MMA(1, 1, At, B1); PG8_BAR; PG8_SCHED;
;             PG8_LDB(B0, 1, 0); PG8_LDB(B1, 1, 1); PG8_SCHED; PG8_LDA(At, 1, 0); PG8_STAGE(PG8_SA(0, 1), a2 + hstepA, voffA);
;             PG8_WAIT_V(8); PG8_WAIT_L(0); PG8_BAR; PG8_MMA(0, 0, At, B0); PG8_MMA(0, 1, At, B1); PG8_BAR; PG8_SCHED;
	s_setprio 1
	s_waitcnt lgkmcnt(0)
	v_mfma_f32_16x16x32_bf16 v[60:63], v[152:155], v[184:187], v[60:63]
	v_mfma_f32_16x16x32_bf16 v[56:59], v[160:163], v[184:187], v[56:59]
	v_mfma_f32_16x16x32_bf16 v[44:47], v[152:155], v[192:195], v[44:47]
	v_mfma_f32_16x16x32_bf16 v[40:43], v[160:163], v[192:195], v[40:43]
	v_mfma_f32_16x16x32_bf16 v[28:31], v[152:155], v[200:203], v[28:31]
	v_mfma_f32_16x16x32_bf16 v[24:27], v[160:163], v[200:203], v[24:27]
	v_mfma_f32_16x16x32_bf16 v[12:15], v[152:155], v[208:211], v[12:15]
	v_mfma_f32_16x16x32_bf16 v[8:11], v[160:163], v[208:211], v[8:11]
	v_mfma_f32_16x16x32_bf16 v[60:63], v[156:159], v[188:191], v[60:63]
	v_mfma_f32_16x16x32_bf16 v[56:59], v[164:167], v[188:191], v[56:59]
	v_mfma_f32_16x16x32_bf16 v[44:47], v[156:159], v[196:199], v[44:47]
	v_mfma_f32_16x16x32_bf16 v[40:43], v[164:167], v[196:199], v[40:43]
	v_mfma_f32_16x16x32_bf16 v[28:31], v[156:159], v[204:207], v[28:31]
	v_mfma_f32_16x16x32_bf16 v[24:27], v[164:167], v[204:207], v[24:27]
	v_mfma_f32_16x16x32_bf16 v[12:15], v[156:159], v[212:215], v[12:15]
	v_mfma_f32_16x16x32_bf16 v[8:11], v[164:167], v[212:215], v[8:11]
	s_setprio 0
	s_setprio 1
	v_mfma_f32_16x16x32_bf16 v[52:55], v[168:171], v[184:187], v[52:55]
	v_mfma_f32_16x16x32_bf16 v[48:51], v[176:179], v[184:187], v[48:51]
	v_mfma_f32_16x16x32_bf16 v[36:39], v[168:171], v[192:195], v[36:39]
	v_mfma_f32_16x16x32_bf16 v[32:35], v[176:179], v[192:195], v[32:35]
	v_mfma_f32_16x16x32_bf16 v[20:23], v[168:171], v[200:203], v[20:23]
	v_mfma_f32_16x16x32_bf16 v[16:19], v[176:179], v[200:203], v[16:19]
	v_mfma_f32_16x16x32_bf16 v[4:7], v[168:171], v[208:211], v[4:7]
	v_mfma_f32_16x16x32_bf16 v[0:3], v[176:179], v[208:211], v[0:3]
	v_mfma_f32_16x16x32_bf16 v[52:55], v[172:175], v[188:191], v[52:55]
	v_mfma_f32_16x16x32_bf16 v[48:51], v[180:183], v[188:191], v[48:51]
	v_mfma_f32_16x16x32_bf16 v[36:39], v[172:175], v[196:199], v[36:39]
	v_mfma_f32_16x16x32_bf16 v[32:35], v[180:183], v[196:199], v[32:35]
	v_mfma_f32_16x16x32_bf16 v[20:23], v[172:175], v[204:207], v[20:23]
	v_mfma_f32_16x16x32_bf16 v[16:19], v[180:183], v[204:207], v[16:19]
	v_mfma_f32_16x16x32_bf16 v[4:7], v[172:175], v[212:215], v[4:7]
	v_mfma_f32_16x16x32_bf16 v[0:3], v[180:183], v[212:215], v[0:3]
	s_setprio 0
	s_barrier
	s_add_i32 s85, 0, 0x18000
	s_add_i32 s86, 0, 0x1c000
	v_add_u32_e32 v164, s85, v147
	v_add_u32_e32 v180, s86, v147
	ds_read_b128 v[152:155], v164
	ds_read_b128 v[156:159], v164 offset:1024
	ds_read_b128 v[160:163], v164 offset:2048
	ds_read_b128 v[164:167], v164 offset:3072
	ds_read_b128 v[168:171], v180
	ds_read_b128 v[172:175], v180 offset:1024
	ds_read_b128 v[176:179], v180 offset:2048
	ds_read_b128 v[180:183], v180 offset:3072
	s_add_u32 s34, s72, 0x40000
	s_addc_u32 s35, s73, 0
	s_mov_b32 m0, s31
	ds_read_b128 v[184:187], v151 offset:32768
	ds_read_b128 v[188:191], v151 offset:33792
	ds_read_b128 v[192:195], v151 offset:34816
	ds_read_b128 v[196:199], v151 offset:35840
	ds_read_b128 v[200:203], v151 offset:36864
	ds_read_b128 v[204:207], v151 offset:37888
	ds_read_b128 v[208:211], v151 offset:38912
	ds_read_b128 v[212:215], v151 offset:39936
	global_load_lds_dwordx4 v134, s[34:35]
	s_mov_b32 m0, s33
	s_nop 0
	global_load_lds_dwordx4 v130, s[34:35]
	s_waitcnt vmcnt(8)
	s_waitcnt lgkmcnt(0)
	s_barrier
	s_setprio 1
	s_waitcnt lgkmcnt(0)
	v_mfma_f32_16x16x32_bf16 v[124:127], v[152:155], v[184:187], v[124:127]
	v_mfma_f32_16x16x32_bf16 v[120:123], v[160:163], v[184:187], v[120:123]
	v_mfma_f32_16x16x32_bf16 v[108:111], v[152:155], v[192:195], v[108:111]
	v_mfma_f32_16x16x32_bf16 v[104:107], v[160:163], v[192:195], v[104:107]
	v_mfma_f32_16x16x32_bf16 v[92:95], v[152:155], v[200:203], v[92:95]
	v_mfma_f32_16x16x32_bf16 v[88:91], v[160:163], v[200:203], v[88:91]
	v_mfma_f32_16x16x32_bf16 v[76:79], v[152:155], v[208:211], v[76:79]
	v_mfma_f32_16x16x32_bf16 v[72:75], v[160:163], v[208:211], v[72:75]
	v_mfma_f32_16x16x32_bf16 v[124:127], v[156:159], v[188:191], v[124:127]
	v_mfma_f32_16x16x32_bf16 v[120:123], v[164:167], v[188:191], v[120:123]
	v_mfma_f32_16x16x32_bf16 v[108:111], v[156:159], v[196:199], v[108:111]
	v_mfma_f32_16x16x32_bf16 v[104:107], v[164:167], v[196:199], v[104:107]
	v_mfma_f32_16x16x32_bf16 v[92:95], v[156:159], v[204:207], v[92:95]
	v_mfma_f32_16x16x32_bf16 v[88:91], v[164:167], v[204:207], v[88:91]
	v_mfma_f32_16x16x32_bf16 v[76:79], v[156:159], v[212:215], v[76:79]
	v_mfma_f32_16x16x32_bf16 v[72:75], v[164:167], v[212:215], v[72:75]
	s_setprio 0
	s_setprio 1
	v_mfma_f32_16x16x32_bf16 v[116:119], v[168:171], v[184:187], v[116:119]
	v_mfma_f32_16x16x32_bf16 v[112:115], v[176:179], v[184:187], v[112:115]
	v_mfma_f32_16x16x32_bf16 v[100:103], v[168:171], v[192:195], v[100:103]
	v_mfma_f32_16x16x32_bf16 v[96:99], v[176:179], v[192:195], v[96:99]
	v_mfma_f32_16x16x32_bf16 v[84:87], v[168:171], v[200:203], v[84:87]
	v_mfma_f32_16x16x32_bf16 v[80:83], v[176:179], v[200:203], v[80:83]
	v_mfma_f32_16x16x32_bf16 v[68:71], v[168:171], v[208:211], v[68:71]
	v_mfma_f32_16x16x32_bf16 v[64:67], v[176:179], v[208:211], v[64:67]
	v_mfma_f32_16x16x32_bf16 v[116:119], v[172:175], v[188:191], v[116:119]
	v_mfma_f32_16x16x32_bf16 v[112:115], v[180:183], v[188:191], v[112:115]
	v_mfma_f32_16x16x32_bf16 v[100:103], v[172:175], v[196:199], v[100:103]
	v_mfma_f32_16x16x32_bf16 v[96:99], v[180:183], v[196:199], v[96:99]
	v_mfma_f32_16x16x32_bf16 v[84:87], v[172:175], v[204:207], v[84:87]
	v_mfma_f32_16x16x32_bf16 v[80:83], v[180:183], v[204:207], v[80:83]
	v_mfma_f32_16x16x32_bf16 v[68:71], v[172:175], v[212:215], v[68:71]
	v_mfma_f32_16x16x32_bf16 v[64:67], v[180:183], v[212:215], v[64:67]
	s_setprio 0
	s_barrier
; #define PG8_STAGE(bufoff, gbase, voff) do { _Pragma("unroll") for (int _i = 0; _i < 2; ++_i) \
;         __builtin_amdgcn_global_load_lds((const unsigned*)((const char*)(gbase) + (voff)[_i]), (LAS unsigned*)(lds + (bufoff) + ldsw + _i * 8192), 16, 0, 0); } while (0)
; #define PG8_LDA(dst, b, h) do { _Pragma("unroll") for (int m = 0; m < 4; ++m) _Pragma("unroll") for (int k = 0; k < 2; ++k) dst[m][k] = *(const LAS bf16x8*)(lds + PG8_SA(b, h) + aoff + m * 2048 + k * 1024); } while (0)
; #define PG8_MMA(ai, bj, At, Bt) do { __builtin_amdgcn_s_setprio(1); _Pragma("unroll") for (int m = 0; m < 4; ++m) _Pragma("unroll") for (int n = 0; n < 2; ++n) _Pragma("unroll") for (int k = 0; k < 2; ++k) \
;         acc[ai][bj][m][n] = __builtin_amdgcn_mfma_f32_16x16x32_bf16(Bt[n][k], At[m][k], acc[ai][bj][m][n], 0, 0, 0); __builtin_amdgcn_s_setprio(0); } while (0)
; #define PG8_WAIT_V(n) asm volatile("s_waitcnt vmcnt(" #n ")" ::: "memory")
; #define PG8_WAIT_L(n) asm volatile("s_waitcnt lgkmcnt(" #n ")" ::: "memory")
; #define PG8_BAR __builtin_amdgcn_s_barrier()
; #define PG8_SCHED __builtin_amdgcn_sched_barrier(0)
; template <class Epi, class Sched, bool ALIGN_EPI = false, bool SP2 = false>
; __device__ __forceinline__ void gemm_phase(LAS unsigned char* lds, const Gemm g, const Sched S, const Epi E) {
;     ...
;         for (int t = 0; t < nt; t += 2) {
;     ...
;             PG8_LDA(At, 1, 1); PG8_STAGE(PG8_SB(1, 0), b3, voffB); PG8_STAGE(PG8_SB(1, 1), b3 + hstepB, voffB); PG8_STAGE(PG8_SA(1, 0), a3, voffA);
;             PG8_WAIT_V(8); PG8_WAIT_L(0); PG8_BAR; PG8_MMA(1, 0, At, B0); PG8_MMA(1, 1, At, B1); PG8_BAR; PG8_SCHED;
	s_add_i32 s34, s85, s20
	v_lshl_add_u64 v[144:145], v[144:145], 0, s[10:11]
	s_mov_b32 m0, s34
	ds_read_b128 v[184:187], v151 offset:49152
	ds_read_b128 v[188:191], v151 offset:50176
	ds_read_b128 v[192:195], v151 offset:51200
	ds_read_b128 v[196:199], v151 offset:52224
	ds_read_b128 v[200:203], v151 offset:53248
	ds_read_b128 v[204:207], v151 offset:54272
	ds_read_b128 v[208:211], v151 offset:55296
	ds_read_b128 v[212:215], v151 offset:56320
	global_load_lds_dwordx4 v[144:145], off
	s_add_i32 m0, s34, 0x2000
	s_add_u32 s34, s70, 0x40080
	v_lshl_add_u64 v[144:145], v[216:217], 0, s[10:11]
	s_addc_u32 s35, s71, 0
	s_add_i32 s70, s86, s20
	global_load_lds_dwordx4 v[144:145], off
	s_mov_b32 m0, s70
	s_nop 0
	global_load_lds_dwordx4 v132, s[34:35]
	s_add_i32 m0, s70, 0x2000
	s_nop 0
	global_load_lds_dwordx4 v128, s[34:35]
	v_lshl_add_u64 v[144:145], v[218:219], 0, s[10:11]
	s_mov_b32 m0, s45
	s_nop 0
	global_load_lds_dwordx4 v[144:145], off
	v_lshl_add_u64 v[144:145], v[220:221], 0, s[10:11]
	s_mov_b32 m0, s67
	s_nop 0
	global_load_lds_dwordx4 v[144:145], off
	s_waitcnt vmcnt(8)
	s_waitcnt lgkmcnt(0)
	s_barrier
	s_setprio 1
	s_waitcnt lgkmcnt(0)
	v_mfma_f32_16x16x32_bf16 v[60:63], v[152:155], v[184:187], v[60:63]
	v_mfma_f32_16x16x32_bf16 v[56:59], v[160:163], v[184:187], v[56:59]
	v_mfma_f32_16x16x32_bf16 v[44:47], v[152:155], v[192:195], v[44:47]
	v_mfma_f32_16x16x32_bf16 v[40:43], v[160:163], v[192:195], v[40:43]
	v_mfma_f32_16x16x32_bf16 v[28:31], v[152:155], v[200:203], v[28:31]
	v_mfma_f32_16x16x32_bf16 v[24:27], v[160:163], v[200:203], v[24:27]
	v_mfma_f32_16x16x32_bf16 v[12:15], v[152:155], v[208:211], v[12:15]
	v_mfma_f32_16x16x32_bf16 v[8:11], v[160:163], v[208:211], v[8:11]
	v_mfma_f32_16x16x32_bf16 v[60:63], v[156:159], v[188:191], v[60:63]
	v_mfma_f32_16x16x32_bf16 v[56:59], v[164:167], v[188:191], v[56:59]
	v_mfma_f32_16x16x32_bf16 v[44:47], v[156:159], v[196:199], v[44:47]
	v_mfma_f32_16x16x32_bf16 v[40:43], v[164:167], v[196:199], v[40:43]
	v_mfma_f32_16x16x32_bf16 v[28:31], v[156:159], v[204:207], v[28:31]
	v_mfma_f32_16x16x32_bf16 v[24:27], v[164:167], v[204:207], v[24:27]
	v_mfma_f32_16x16x32_bf16 v[12:15], v[156:159], v[212:215], v[12:15]
	v_mfma_f32_16x16x32_bf16 v[8:11], v[164:167], v[212:215], v[8:11]
	s_setprio 0
	s_setprio 1
	v_mfma_f32_16x16x32_bf16 v[52:55], v[168:171], v[184:187], v[52:55]
	v_mfma_f32_16x16x32_bf16 v[48:51], v[176:179], v[184:187], v[48:51]
	v_mfma_f32_16x16x32_bf16 v[36:39], v[168:171], v[192:195], v[36:39]
	v_mfma_f32_16x16x32_bf16 v[32:35], v[176:179], v[192:195], v[32:35]
	v_mfma_f32_16x16x32_bf16 v[20:23], v[168:171], v[200:203], v[20:23]
	v_mfma_f32_16x16x32_bf16 v[16:19], v[176:179], v[200:203], v[16:19]
	v_mfma_f32_16x16x32_bf16 v[4:7], v[168:171], v[208:211], v[4:7]
	v_mfma_f32_16x16x32_bf16 v[0:3], v[176:179], v[208:211], v[0:3]
	v_mfma_f32_16x16x32_bf16 v[52:55], v[172:175], v[188:191], v[52:55]
	v_mfma_f32_16x16x32_bf16 v[48:51], v[180:183], v[188:191], v[48:51]
	v_mfma_f32_16x16x32_bf16 v[36:39], v[172:175], v[196:199], v[36:39]
	v_mfma_f32_16x16x32_bf16 v[32:35], v[180:183], v[196:199], v[32:35]
	v_mfma_f32_16x16x32_bf16 v[20:23], v[172:175], v[204:207], v[20:23]
	v_mfma_f32_16x16x32_bf16 v[16:19], v[180:183], v[204:207], v[16:19]
	v_mfma_f32_16x16x32_bf16 v[4:7], v[172:175], v[212:215], v[4:7]
	v_mfma_f32_16x16x32_bf16 v[0:3], v[180:183], v[212:215], v[0:3]
	s_setprio 0
	s_barrier
	s_add_i32 s84, s84, 2
	s_add_u32 s68, s68, 0x100
	s_addc_u32 s69, s69, 0
	s_add_u32 s82, s82, 0x100
	s_addc_u32 s83, s83, 0
	s_cmp_gt_u32 s84, 13
	s_cbranch_scc0 .LBB0_623
	s_and_b64 vcc, exec, s[14:15]
	s_cbranch_vccz .LBB0_626
	s_barrier

; #define PG8_STAGE(bufoff, gbase, voff) do { _Pragma("unroll") for (int _i = 0; _i < 2; ++_i) \
;         __builtin_amdgcn_global_load_lds((const unsigned*)((const char*)(gbase) + (voff)[_i]), (LAS unsigned*)(lds + (bufoff) + ldsw + _i * 8192), 16, 0, 0); } while (0)
; #define PG8_LDA(dst, b, h) do { _Pragma("unroll") for (int m = 0; m < 4; ++m) _Pragma("unroll") for (int k = 0; k < 2; ++k) dst[m][k] = *(const LAS bf16x8*)(lds + PG8_SA(b, h) + aoff + m * 2048 + k * 1024); } while (0)
; #define PG8_LDB(dst, b, h) do { _Pragma("unroll") for (int n = 0; n < 2; ++n) _Pragma("unroll") for (int k = 0; k < 2; ++k) dst[n][k] = *(const LAS bf16x8*)(lds + PG8_SB(b, h) + boff + n * 2048 + k * 1024); } while (0)
; #define PG8_MMA(ai, bj, At, Bt) do { __builtin_amdgcn_s_setprio(1); _Pragma("unroll") for (int m = 0; m < 4; ++m) _Pragma("unroll") for (int n = 0; n < 2; ++n) _Pragma("unroll") for (int k = 0; k < 2; ++k) \
;         acc[ai][bj][m][n] = __builtin_amdgcn_mfma_f32_16x16x32_bf16(Bt[n][k], At[m][k], acc[ai][bj][m][n], 0, 0, 0); __builtin_amdgcn_s_setprio(0); } while (0)
; #define PG8_WAIT_V(n) asm volatile("s_waitcnt vmcnt(" #n ")" ::: "memory")
; #define PG8_WAIT_L(n) asm volatile("s_waitcnt lgkmcnt(" #n ")" ::: "memory")
; #define PG8_BAR __builtin_amdgcn_s_barrier()
; #define PG8_SCHED __builtin_amdgcn_sched_barrier(0)
; template <class Epi, class Sched, bool ALIGN_EPI = false, bool SP2 = false>
; __device__ __forceinline__ void gemm_phase(LAS unsigned char* lds, const Gemm g, const Sched S, const Epi E) {
;     ...
;             PG8_LDB(B0, 0, 0); PG8_LDB(B1, 0, 1); PG8_SCHED; PG8_LDA(At, 0, 0); PG8_STAGE(PG8_SA(1, 1), a1 + hstepA, voffA);
;             PG8_WAIT_V(8); PG8_WAIT_L(0); PG8_BAR; PG8_MMA(0, 0, At, B0); PG8_MMA(0, 1, At, B1); PG8_BAR; PG8_SCHED;
;             PG8_LDA(At, 0, 1); PG8_STAGE(PG8_SB(0, 0), b2, voffB); PG8_STAGE(PG8_SB(0, 1), b2 + hstepB, voffB); PG8_STAGE(PG8_SA(0, 0), a2, voffA);
;             PG8_WAIT_V(8); PG8_WAIT_L(0); PG8_BAR; PG8_MMA(1, 0, At, B0); PG8_MMA(1, 1, At, B1); PG8_BAR; PG8_SCHED;
.LBB0_705:
	ds_read_b128 v[128:131], v173
	ds_read_b128 v[132:135], v173 offset:1024
	ds_read_b128 v[136:139], v173 offset:2048
	ds_read_b128 v[140:143], v173 offset:3072
	ds_read_b128 v[160:163], v174
	ds_read_b128 v[164:167], v174 offset:1024
	ds_read_b128 v[178:181], v174 offset:2048
	ds_read_b128 v[182:185], v174 offset:3072
	s_add_u32 s74, s72, 0x100
	s_addc_u32 s75, s73, 0
	s_cmp_eq_u32 s88, 40
	s_cselect_b32 s79, s11, s75
	s_cselect_b32 s78, s10, s74
	s_cselect_b32 s77, s71, s87
	s_cselect_b32 s76, s70, s86
	s_add_i32 m0, s5, 0xc000
	ds_read_b128 v[186:189], v175
	ds_read_b128 v[190:193], v175 offset:1024
	ds_read_b128 v[194:197], v175 offset:2048
	ds_read_b128 v[198:201], v175 offset:3072
	ds_read_b128 v[202:205], v175 offset:4096
	ds_read_b128 v[206:209], v175 offset:5120
	ds_read_b128 v[210:213], v175 offset:6144
	ds_read_b128 v[214:217], v175 offset:7168
	global_load_lds_dwordx4 v152, s[72:73]
	s_add_i32 m0, s5, 0xe000
	s_nop 0
	global_load_lds_dwordx4 v154, s[72:73]
	s_waitcnt vmcnt(8)
	s_waitcnt lgkmcnt(0)
	s_barrier
	s_setprio 1
	s_waitcnt lgkmcnt(0)
	v_mfma_f32_16x16x32_bf16 v[124:127], v[128:131], v[186:189], v[124:127]
	v_mfma_f32_16x16x32_bf16 v[120:123], v[136:139], v[186:189], v[120:123]
	v_mfma_f32_16x16x32_bf16 v[108:111], v[128:131], v[194:197], v[108:111]
	v_mfma_f32_16x16x32_bf16 v[104:107], v[136:139], v[194:197], v[104:107]
	v_mfma_f32_16x16x32_bf16 v[92:95], v[128:131], v[202:205], v[92:95]
	v_mfma_f32_16x16x32_bf16 v[88:91], v[136:139], v[202:205], v[88:91]
	v_mfma_f32_16x16x32_bf16 v[76:79], v[128:131], v[210:213], v[76:79]
	v_mfma_f32_16x16x32_bf16 v[72:75], v[136:139], v[210:213], v[72:75]
	v_mfma_f32_16x16x32_bf16 v[124:127], v[132:135], v[190:193], v[124:127]
	v_mfma_f32_16x16x32_bf16 v[120:123], v[140:143], v[190:193], v[120:123]
	v_mfma_f32_16x16x32_bf16 v[108:111], v[132:135], v[198:201], v[108:111]
	v_mfma_f32_16x16x32_bf16 v[104:107], v[140:143], v[198:201], v[104:107]
	v_mfma_f32_16x16x32_bf16 v[92:95], v[132:135], v[206:209], v[92:95]
	v_mfma_f32_16x16x32_bf16 v[88:91], v[140:143], v[206:209], v[88:91]
	v_mfma_f32_16x16x32_bf16 v[76:79], v[132:135], v[214:217], v[76:79]
	v_mfma_f32_16x16x32_bf16 v[72:75], v[140:143], v[214:217], v[72:75]
	s_setprio 0
	s_setprio 1
	v_mfma_f32_16x16x32_bf16 v[116:119], v[160:163], v[186:189], v[116:119]
	v_mfma_f32_16x16x32_bf16 v[112:115], v[178:181], v[186:189], v[112:115]
	v_mfma_f32_16x16x32_bf16 v[100:103], v[160:163], v[194:197], v[100:103]
	v_mfma_f32_16x16x32_bf16 v[96:99], v[178:181], v[194:197], v[96:99]
	v_mfma_f32_16x16x32_bf16 v[84:87], v[160:163], v[202:205], v[84:87]
	v_mfma_f32_16x16x32_bf16 v[80:83], v[178:181], v[202:205], v[80:83]
	v_mfma_f32_16x16x32_bf16 v[68:71], v[160:163], v[210:213], v[68:71]
	v_mfma_f32_16x16x32_bf16 v[64:67], v[178:181], v[210:213], v[64:67]
	v_mfma_f32_16x16x32_bf16 v[116:119], v[164:167], v[190:193], v[116:119]
	v_mfma_f32_16x16x32_bf16 v[112:115], v[182:185], v[190:193], v[112:115]
	v_mfma_f32_16x16x32_bf16 v[100:103], v[164:167], v[198:201], v[100:103]
	v_mfma_f32_16x16x32_bf16 v[96:99], v[182:185], v[198:201], v[96:99]
	v_mfma_f32_16x16x32_bf16 v[84:87], v[164:167], v[206:209], v[84:87]
	v_mfma_f32_16x16x32_bf16 v[80:83], v[182:185], v[206:209], v[80:83]
	v_mfma_f32_16x16x32_bf16 v[68:71], v[164:167], v[214:217], v[68:71]
	v_mfma_f32_16x16x32_bf16 v[64:67], v[182:185], v[214:217], v[64:67]
	s_setprio 0
	s_barrier
	s_add_i32 s34, s80, s4
	v_lshl_add_u64 v[168:169], s[76:77], 0, v[146:147]
	s_mov_b32 m0, s34
	ds_read_b128 v[186:189], v175 offset:16384
	ds_read_b128 v[190:193], v175 offset:17408
	ds_read_b128 v[194:197], v175 offset:18432
	ds_read_b128 v[198:201], v175 offset:19456
	ds_read_b128 v[202:205], v175 offset:20480
	ds_read_b128 v[206:209], v175 offset:21504
	ds_read_b128 v[210:213], v175 offset:22528
	ds_read_b128 v[214:217], v175 offset:23552
	global_load_lds_dwordx4 v[168:169], off
	s_add_i32 m0, s34, 0x2000
	s_add_u32 s34, s76, 0xb0000
	v_lshl_add_u64 v[218:219], s[76:77], 0, v[150:151]
	s_addc_u32 s35, s77, 0
	s_add_i32 s72, s81, s4
	global_load_lds_dwordx4 v[218:219], off
	s_mov_b32 m0, s72
	v_lshl_add_u64 v[222:223], s[78:79], 0, v[148:149]
	global_load_lds_dwordx4 v146, s[34:35]
	s_add_i32 m0, s72, 0x2000
	s_nop 0
	global_load_lds_dwordx4 v150, s[34:35]
	v_lshl_add_u64 v[220:221], s[78:79], 0, v[144:145]
	s_mov_b32 m0, s5
	s_nop 0
	global_load_lds_dwordx4 v[220:221], off
	s_mov_b32 m0, s20
	s_nop 0
	global_load_lds_dwordx4 v[222:223], off
	s_waitcnt vmcnt(8)
	s_waitcnt lgkmcnt(0)
	s_barrier
; #define PG8_STAGE(bufoff, gbase, voff) do { _Pragma("unroll") for (int _i = 0; _i < 2; ++_i) \
;         __builtin_amdgcn_global_load_lds((const unsigned*)((const char*)(gbase) + (voff)[_i]), (LAS unsigned*)(lds + (bufoff) + ldsw + _i * 8192), 16, 0, 0); } while (0)
; #define PG8_LDA(dst, b, h) do { _Pragma("unroll") for (int m = 0; m < 4; ++m) _Pragma("unroll") for (int k = 0; k < 2; ++k) dst[m][k] = *(const LAS bf16x8*)(lds + PG8_SA(b, h) + aoff + m * 2048 + k * 1024); } while (0)
; #define PG8_LDB(dst, b, h) do { _Pragma("unroll") for (int n = 0; n < 2; ++n) _Pragma("unroll") for (int k = 0; k < 2; ++k) dst[n][k] = *(const LAS bf16x8*)(lds + PG8_SB(b, h) + boff + n * 2048 + k * 1024); } while (0)
; #define PG8_MMA(ai, bj, At, Bt) do { __builtin_amdgcn_s_setprio(1); _Pragma("unroll") for (int m = 0; m < 4; ++m) _Pragma("unroll") for (int n = 0; n < 2; ++n) _Pragma("unroll") for (int k = 0; k < 2; ++k) \
;         acc[ai][bj][m][n] = __builtin_amdgcn_mfma_f32_16x16x32_bf16(Bt[n][k], At[m][k], acc[ai][bj][m][n], 0, 0, 0); __builtin_amdgcn_s_setprio(0); } while (0)
; #define PG8_WAIT_V(n) asm volatile("s_waitcnt vmcnt(" #n ")" ::: "memory")
; #define PG8_WAIT_L(n) asm volatile("s_waitcnt lgkmcnt(" #n ")" ::: "memory")
; #define PG8_BAR __builtin_amdgcn_s_barrier()
; #define PG8_SCHED __builtin_amdgcn_sched_barrier(0)
; template <class Epi, class Sched, bool ALIGN_EPI = false, bool SP2 = false>
; __device__ __forceinline__ void gemm_phase(LAS unsigned char* lds, const Gemm g, const Sched S, const Epi E) {
;     ...
;             PG8_WAIT_V(8); PG8_WAIT_L(0); PG8_BAR; PG8_MMA(1, 0, At, B0); PG8_MMA(1, 1, At, B1); PG8_BAR; PG8_SCHED;
;             PG8_LDB(B0, 1, 0); PG8_LDB(B1, 1, 1); PG8_SCHED; PG8_LDA(At, 1, 0); PG8_STAGE(PG8_SA(0, 1), a2 + hstepA, voffA);
;             PG8_WAIT_V(8); PG8_WAIT_L(0); PG8_BAR; PG8_MMA(0, 0, At, B0); PG8_MMA(0, 1, At, B1); PG8_BAR; PG8_SCHED;
	s_setprio 1
	s_waitcnt lgkmcnt(0)
	v_mfma_f32_16x16x32_bf16 v[60:63], v[128:131], v[186:189], v[60:63]
	v_mfma_f32_16x16x32_bf16 v[56:59], v[136:139], v[186:189], v[56:59]
	v_mfma_f32_16x16x32_bf16 v[44:47], v[128:131], v[194:197], v[44:47]
	v_mfma_f32_16x16x32_bf16 v[40:43], v[136:139], v[194:197], v[40:43]
	v_mfma_f32_16x16x32_bf16 v[28:31], v[128:131], v[202:205], v[28:31]
	v_mfma_f32_16x16x32_bf16 v[24:27], v[136:139], v[202:205], v[24:27]
	v_mfma_f32_16x16x32_bf16 v[12:15], v[128:131], v[210:213], v[12:15]
	v_mfma_f32_16x16x32_bf16 v[8:11], v[136:139], v[210:213], v[8:11]
	v_mfma_f32_16x16x32_bf16 v[60:63], v[132:135], v[190:193], v[60:63]
	v_mfma_f32_16x16x32_bf16 v[56:59], v[140:143], v[190:193], v[56:59]
	v_mfma_f32_16x16x32_bf16 v[44:47], v[132:135], v[198:201], v[44:47]
	v_mfma_f32_16x16x32_bf16 v[40:43], v[140:143], v[198:201], v[40:43]
	v_mfma_f32_16x16x32_bf16 v[28:31], v[132:135], v[206:209], v[28:31]
	v_mfma_f32_16x16x32_bf16 v[24:27], v[140:143], v[206:209], v[24:27]
	v_mfma_f32_16x16x32_bf16 v[12:15], v[132:135], v[214:217], v[12:15]
	v_mfma_f32_16x16x32_bf16 v[8:11], v[140:143], v[214:217], v[8:11]
	s_setprio 0
	s_setprio 1
	v_mfma_f32_16x16x32_bf16 v[52:55], v[160:163], v[186:189], v[52:55]
	v_mfma_f32_16x16x32_bf16 v[48:51], v[178:181], v[186:189], v[48:51]
	v_mfma_f32_16x16x32_bf16 v[36:39], v[160:163], v[194:197], v[36:39]
	v_mfma_f32_16x16x32_bf16 v[32:35], v[178:181], v[194:197], v[32:35]
	v_mfma_f32_16x16x32_bf16 v[20:23], v[160:163], v[202:205], v[20:23]
	v_mfma_f32_16x16x32_bf16 v[16:19], v[178:181], v[202:205], v[16:19]
	v_mfma_f32_16x16x32_bf16 v[4:7], v[160:163], v[210:213], v[4:7]
	v_mfma_f32_16x16x32_bf16 v[0:3], v[178:181], v[210:213], v[0:3]
	v_mfma_f32_16x16x32_bf16 v[52:55], v[164:167], v[190:193], v[52:55]
	v_mfma_f32_16x16x32_bf16 v[48:51], v[182:185], v[190:193], v[48:51]
	v_mfma_f32_16x16x32_bf16 v[36:39], v[164:167], v[198:201], v[36:39]
	v_mfma_f32_16x16x32_bf16 v[32:35], v[182:185], v[198:201], v[32:35]
	v_mfma_f32_16x16x32_bf16 v[20:23], v[164:167], v[206:209], v[20:23]
	v_mfma_f32_16x16x32_bf16 v[16:19], v[182:185], v[206:209], v[16:19]
	v_mfma_f32_16x16x32_bf16 v[4:7], v[164:167], v[214:217], v[4:7]
	v_mfma_f32_16x16x32_bf16 v[0:3], v[182:185], v[214:217], v[0:3]
	s_setprio 0
	s_barrier
	s_add_i32 s72, 0, 0x18000
	s_add_i32 s73, 0, 0x1c000
	v_add_u32_e32 v140, s72, v171
	v_add_u32_e32 v177, s73, v171
	ds_read_b128 v[128:131], v140
	ds_read_b128 v[132:135], v140 offset:1024
	ds_read_b128 v[136:139], v140 offset:2048
	ds_read_b128 v[140:143], v140 offset:3072
	ds_read_b128 v[160:163], v177
	ds_read_b128 v[164:167], v177 offset:1024
	ds_read_b128 v[178:181], v177 offset:2048
	ds_read_b128 v[182:185], v177 offset:3072
	s_add_u32 s34, s78, 0xb0000
	s_addc_u32 s35, s79, 0
	s_mov_b32 m0, s21
	ds_read_b128 v[186:189], v175 offset:32768
	ds_read_b128 v[190:193], v175 offset:33792
	ds_read_b128 v[194:197], v175 offset:34816
	ds_read_b128 v[198:201], v175 offset:35840
	ds_read_b128 v[202:205], v175 offset:36864
	ds_read_b128 v[206:209], v175 offset:37888
	ds_read_b128 v[210:213], v175 offset:38912
	ds_read_b128 v[214:217], v175 offset:39936
	global_load_lds_dwordx4 v144, s[34:35]
	s_mov_b32 m0, s29
	s_nop 0
	global_load_lds_dwordx4 v148, s[34:35]
	s_waitcnt vmcnt(8)
	s_waitcnt lgkmcnt(0)
	s_barrier
	s_setprio 1
	s_waitcnt lgkmcnt(0)
	v_mfma_f32_16x16x32_bf16 v[124:127], v[128:131], v[186:189], v[124:127]
	v_mfma_f32_16x16x32_bf16 v[120:123], v[136:139], v[186:189], v[120:123]
	v_mfma_f32_16x16x32_bf16 v[108:111], v[128:131], v[194:197], v[108:111]
	v_mfma_f32_16x16x32_bf16 v[104:107], v[136:139], v[194:197], v[104:107]
	v_mfma_f32_16x16x32_bf16 v[92:95], v[128:131], v[202:205], v[92:95]
	v_mfma_f32_16x16x32_bf16 v[88:91], v[136:139], v[202:205], v[88:91]
	v_mfma_f32_16x16x32_bf16 v[76:79], v[128:131], v[210:213], v[76:79]
	v_mfma_f32_16x16x32_bf16 v[72:75], v[136:139], v[210:213], v[72:75]
	v_mfma_f32_16x16x32_bf16 v[124:127], v[132:135], v[190:193], v[124:127]
	v_mfma_f32_16x16x32_bf16 v[120:123], v[140:143], v[190:193], v[120:123]
	v_mfma_f32_16x16x32_bf16 v[108:111], v[132:135], v[198:201], v[108:111]
	v_mfma_f32_16x16x32_bf16 v[104:107], v[140:143], v[198:201], v[104:107]
	v_mfma_f32_16x16x32_bf16 v[92:95], v[132:135], v[206:209], v[92:95]
	v_mfma_f32_16x16x32_bf16 v[88:91], v[140:143], v[206:209], v[88:91]
	v_mfma_f32_16x16x32_bf16 v[76:79], v[132:135], v[214:217], v[76:79]
	v_mfma_f32_16x16x32_bf16 v[72:75], v[140:143], v[214:217], v[72:75]
	s_setprio 0
	s_setprio 1
	v_mfma_f32_16x16x32_bf16 v[116:119], v[160:163], v[186:189], v[116:119]
	v_mfma_f32_16x16x32_bf16 v[112:115], v[178:181], v[186:189], v[112:115]
	v_mfma_f32_16x16x32_bf16 v[100:103], v[160:163], v[194:197], v[100:103]
	v_mfma_f32_16x16x32_bf16 v[96:99], v[178:181], v[194:197], v[96:99]
	v_mfma_f32_16x16x32_bf16 v[84:87], v[160:163], v[202:205], v[84:87]
	v_mfma_f32_16x16x32_bf16 v[80:83], v[178:181], v[202:205], v[80:83]
	v_mfma_f32_16x16x32_bf16 v[68:71], v[160:163], v[210:213], v[68:71]
	v_mfma_f32_16x16x32_bf16 v[64:67], v[178:181], v[210:213], v[64:67]
	v_mfma_f32_16x16x32_bf16 v[116:119], v[164:167], v[190:193], v[116:119]
	v_mfma_f32_16x16x32_bf16 v[112:115], v[182:185], v[190:193], v[112:115]
	v_mfma_f32_16x16x32_bf16 v[100:103], v[164:167], v[198:201], v[100:103]
	v_mfma_f32_16x16x32_bf16 v[96:99], v[182:185], v[198:201], v[96:99]
	v_mfma_f32_16x16x32_bf16 v[84:87], v[164:167], v[206:209], v[84:87]
	v_mfma_f32_16x16x32_bf16 v[80:83], v[182:185], v[206:209], v[80:83]
	v_mfma_f32_16x16x32_bf16 v[68:71], v[164:167], v[214:217], v[68:71]
	v_mfma_f32_16x16x32_bf16 v[64:67], v[182:185], v[214:217], v[64:67]
	s_setprio 0
	s_barrier
; #define PG8_STAGE(bufoff, gbase, voff) do { _Pragma("unroll") for (int _i = 0; _i < 2; ++_i) \
;         __builtin_amdgcn_global_load_lds((const unsigned*)((const char*)(gbase) + (voff)[_i]), (LAS unsigned*)(lds + (bufoff) + ldsw + _i * 8192), 16, 0, 0); } while (0)
; #define PG8_LDA(dst, b, h) do { _Pragma("unroll") for (int m = 0; m < 4; ++m) _Pragma("unroll") for (int k = 0; k < 2; ++k) dst[m][k] = *(const LAS bf16x8*)(lds + PG8_SA(b, h) + aoff + m * 2048 + k * 1024); } while (0)
; #define PG8_MMA(ai, bj, At, Bt) do { __builtin_amdgcn_s_setprio(1); _Pragma("unroll") for (int m = 0; m < 4; ++m) _Pragma("unroll") for (int n = 0; n < 2; ++n) _Pragma("unroll") for (int k = 0; k < 2; ++k) \
;         acc[ai][bj][m][n] = __builtin_amdgcn_mfma_f32_16x16x32_bf16(Bt[n][k], At[m][k], acc[ai][bj][m][n], 0, 0, 0); __builtin_amdgcn_s_setprio(0); } while (0)
; #define PG8_WAIT_V(n) asm volatile("s_waitcnt vmcnt(" #n ")" ::: "memory")
; #define PG8_WAIT_L(n) asm volatile("s_waitcnt lgkmcnt(" #n ")" ::: "memory")
; #define PG8_BAR __builtin_amdgcn_s_barrier()
; #define PG8_SCHED __builtin_amdgcn_sched_barrier(0)
; template <class Epi, class Sched, bool ALIGN_EPI = false, bool SP2 = false>
; __device__ __forceinline__ void gemm_phase(LAS unsigned char* lds, const Gemm g, const Sched S, const Epi E) {
;     ...
;         for (int t = 0; t < nt; t += 2) {
;     ...
;             PG8_LDA(At, 1, 1); PG8_STAGE(PG8_SB(1, 0), b3, voffB); PG8_STAGE(PG8_SB(1, 1), b3 + hstepB, voffB); PG8_STAGE(PG8_SA(1, 0), a3, voffA);
;             PG8_WAIT_V(8); PG8_WAIT_L(0); PG8_BAR; PG8_MMA(1, 0, At, B0); PG8_MMA(1, 1, At, B1); PG8_BAR; PG8_SCHED;
	s_add_i32 s34, s72, s4
	v_lshl_add_u64 v[168:169], v[168:169], 0, s[60:61]
	s_mov_b32 m0, s34
	ds_read_b128 v[186:189], v175 offset:49152
	ds_read_b128 v[190:193], v175 offset:50176
	ds_read_b128 v[194:197], v175 offset:51200
	ds_read_b128 v[198:201], v175 offset:52224
	ds_read_b128 v[202:205], v175 offset:53248
	ds_read_b128 v[206:209], v175 offset:54272
	ds_read_b128 v[210:213], v175 offset:55296
	ds_read_b128 v[214:217], v175 offset:56320
	global_load_lds_dwordx4 v[168:169], off
	s_add_i32 m0, s34, 0x2000
	s_add_u32 s34, s76, 0xb0080
	v_lshl_add_u64 v[168:169], v[218:219], 0, s[60:61]
	s_addc_u32 s35, s77, 0
	s_add_i32 s72, s73, s4
	global_load_lds_dwordx4 v[168:169], off
	s_mov_b32 m0, s72
	s_nop 0
	global_load_lds_dwordx4 v146, s[34:35]
	s_add_i32 m0, s72, 0x2000
	s_nop 0
	global_load_lds_dwordx4 v150, s[34:35]
	v_lshl_add_u64 v[168:169], v[220:221], 0, s[60:61]
	s_mov_b32 m0, s31
	s_nop 0
	global_load_lds_dwordx4 v[168:169], off
	v_lshl_add_u64 v[168:169], v[222:223], 0, s[60:61]
	s_mov_b32 m0, s33
	s_nop 0
	global_load_lds_dwordx4 v[168:169], off
	s_waitcnt vmcnt(8)
	s_waitcnt lgkmcnt(0)
	s_barrier
	s_setprio 1
	s_waitcnt lgkmcnt(0)
	v_mfma_f32_16x16x32_bf16 v[60:63], v[128:131], v[186:189], v[60:63]
	v_mfma_f32_16x16x32_bf16 v[56:59], v[136:139], v[186:189], v[56:59]
	v_mfma_f32_16x16x32_bf16 v[44:47], v[128:131], v[194:197], v[44:47]
	v_mfma_f32_16x16x32_bf16 v[40:43], v[136:139], v[194:197], v[40:43]
	v_mfma_f32_16x16x32_bf16 v[28:31], v[128:131], v[202:205], v[28:31]
	v_mfma_f32_16x16x32_bf16 v[24:27], v[136:139], v[202:205], v[24:27]
	v_mfma_f32_16x16x32_bf16 v[12:15], v[128:131], v[210:213], v[12:15]
	v_mfma_f32_16x16x32_bf16 v[8:11], v[136:139], v[210:213], v[8:11]
	v_mfma_f32_16x16x32_bf16 v[60:63], v[132:135], v[190:193], v[60:63]
	v_mfma_f32_16x16x32_bf16 v[56:59], v[140:143], v[190:193], v[56:59]
	v_mfma_f32_16x16x32_bf16 v[44:47], v[132:135], v[198:201], v[44:47]
	v_mfma_f32_16x16x32_bf16 v[40:43], v[140:143], v[198:201], v[40:43]
	v_mfma_f32_16x16x32_bf16 v[28:31], v[132:135], v[206:209], v[28:31]
	v_mfma_f32_16x16x32_bf16 v[24:27], v[140:143], v[206:209], v[24:27]
	v_mfma_f32_16x16x32_bf16 v[12:15], v[132:135], v[214:217], v[12:15]
	v_mfma_f32_16x16x32_bf16 v[8:11], v[140:143], v[214:217], v[8:11]
	s_setprio 0
	s_setprio 1
	v_mfma_f32_16x16x32_bf16 v[52:55], v[160:163], v[186:189], v[52:55]
	v_mfma_f32_16x16x32_bf16 v[48:51], v[178:181], v[186:189], v[48:51]
	v_mfma_f32_16x16x32_bf16 v[36:39], v[160:163], v[194:197], v[36:39]
	v_mfma_f32_16x16x32_bf16 v[32:35], v[178:181], v[194:197], v[32:35]
	v_mfma_f32_16x16x32_bf16 v[20:23], v[160:163], v[202:205], v[20:23]
	v_mfma_f32_16x16x32_bf16 v[16:19], v[178:181], v[202:205], v[16:19]
	v_mfma_f32_16x16x32_bf16 v[4:7], v[160:163], v[210:213], v[4:7]
	v_mfma_f32_16x16x32_bf16 v[0:3], v[178:181], v[210:213], v[0:3]
	v_mfma_f32_16x16x32_bf16 v[52:55], v[164:167], v[190:193], v[52:55]
	v_mfma_f32_16x16x32_bf16 v[48:51], v[182:185], v[190:193], v[48:51]
	v_mfma_f32_16x16x32_bf16 v[36:39], v[164:167], v[198:201], v[36:39]
	v_mfma_f32_16x16x32_bf16 v[32:35], v[182:185], v[198:201], v[32:35]
	v_mfma_f32_16x16x32_bf16 v[20:23], v[164:167], v[206:209], v[20:23]
	v_mfma_f32_16x16x32_bf16 v[16:19], v[182:185], v[206:209], v[16:19]
	v_mfma_f32_16x16x32_bf16 v[4:7], v[164:167], v[214:217], v[4:7]
	v_mfma_f32_16x16x32_bf16 v[0:3], v[182:185], v[214:217], v[0:3]
	s_setprio 0
	s_barrier
	s_add_i32 s88, s88, 2
	s_add_u32 s86, s86, 0x100
	s_addc_u32 s87, s87, 0
	s_cmp_gt_u32 s88, 41
	s_mov_b64 s[72:73], s[74:75]
	s_cbranch_scc0 .LBB0_705
	s_and_b64 vcc, exec, s[62:63]
	s_cbranch_vccz .LBB0_708
	s_barrier

; #define PG8_STAGE(bufoff, gbase, voff) do { _Pragma("unroll") for (int _i = 0; _i < 2; ++_i) \
;         __builtin_amdgcn_global_load_lds((const unsigned*)((const char*)(gbase) + (voff)[_i]), (LAS unsigned*)(lds + (bufoff) + ldsw + _i * 8192), 16, 0, 0); } while (0)
; #define PG8_LDA(dst, b, h) do { _Pragma("unroll") for (int m = 0; m < 4; ++m) _Pragma("unroll") for (int k = 0; k < 2; ++k) dst[m][k] = *(const LAS bf16x8*)(lds + PG8_SA(b, h) + aoff + m * 2048 + k * 1024); } while (0)
; #define PG8_LDB(dst, b, h) do { _Pragma("unroll") for (int n = 0; n < 2; ++n) _Pragma("unroll") for (int k = 0; k < 2; ++k) dst[n][k] = *(const LAS bf16x8*)(lds + PG8_SB(b, h) + boff + n * 2048 + k * 1024); } while (0)
; #define PG8_MMA(ai, bj, At, Bt) do { __builtin_amdgcn_s_setprio(1); _Pragma("unroll") for (int m = 0; m < 4; ++m) _Pragma("unroll") for (int n = 0; n < 2; ++n) _Pragma("unroll") for (int k = 0; k < 2; ++k) \
;         acc[ai][bj][m][n] = __builtin_amdgcn_mfma_f32_16x16x32_bf16(Bt[n][k], At[m][k], acc[ai][bj][m][n], 0, 0, 0); __builtin_amdgcn_s_setprio(0); } while (0)
; #define PG8_WAIT_V(n) asm volatile("s_waitcnt vmcnt(" #n ")" ::: "memory")
; #define PG8_WAIT_L(n) asm volatile("s_waitcnt lgkmcnt(" #n ")" ::: "memory")
; #define PG8_BAR __builtin_amdgcn_s_barrier()
; #define PG8_SCHED __builtin_amdgcn_sched_barrier(0)
; template <class Epi, class Sched, bool ALIGN_EPI = false, bool SP2 = false>
; __device__ __forceinline__ void gemm_phase(LAS unsigned char* lds, const Gemm g, const Sched S, const Epi E) {
;     ...
;             PG8_LDB(B0, 0, 0); PG8_LDB(B1, 0, 1); PG8_SCHED; PG8_LDA(At, 0, 0); PG8_STAGE(PG8_SA(1, 1), a1 + hstepA, voffA);
;             PG8_WAIT_V(8); PG8_WAIT_L(0); PG8_BAR; PG8_MMA(0, 0, At, B0); PG8_MMA(0, 1, At, B1); PG8_BAR; PG8_SCHED;
;             PG8_LDA(At, 0, 1); PG8_STAGE(PG8_SB(0, 0), b2, voffB); PG8_STAGE(PG8_SB(0, 1), b2 + hstepB, voffB); PG8_STAGE(PG8_SA(0, 0), a2, voffA);
;             PG8_WAIT_V(8); PG8_WAIT_L(0); PG8_BAR; PG8_MMA(1, 0, At, B0); PG8_MMA(1, 1, At, B1); PG8_BAR; PG8_SCHED;
.LBB0_791:
	ds_read_b128 v[146:149], v153
	ds_read_b128 v[158:161], v153 offset:1024
	ds_read_b128 v[162:165], v153 offset:2048
	ds_read_b128 v[166:169], v153 offset:3072
	ds_read_b128 v[170:173], v154
	ds_read_b128 v[174:177], v154 offset:1024
	ds_read_b128 v[178:181], v154 offset:2048
	ds_read_b128 v[182:185], v154 offset:3072
	s_add_u32 s34, s72, 0xfff80080
	s_addc_u32 s35, s73, -1
	s_cmp_eq_u32 s88, 12
	s_cselect_b32 s77, s11, s35
	s_cselect_b32 s76, s63, s34
	s_cselect_b32 s75, s61, s87
	s_cselect_b32 s74, s71, s86
	s_add_i32 m0, s5, 0xc000
	ds_read_b128 v[186:189], v155
	ds_read_b128 v[190:193], v155 offset:1024
	ds_read_b128 v[194:197], v155 offset:2048
	ds_read_b128 v[198:201], v155 offset:3072
	ds_read_b128 v[202:205], v155 offset:4096
	ds_read_b128 v[206:209], v155 offset:5120
	ds_read_b128 v[210:213], v155 offset:6144
	ds_read_b128 v[214:217], v155 offset:7168
	global_load_lds_dwordx4 v138, s[72:73]
	s_add_i32 m0, s5, 0xe000
	s_nop 0
	global_load_lds_dwordx4 v140, s[72:73]
	s_waitcnt vmcnt(8)
	s_waitcnt lgkmcnt(0)
	s_barrier
	s_setprio 1
	s_waitcnt lgkmcnt(0)
	v_mfma_f32_16x16x32_bf16 v[124:127], v[146:149], v[186:189], v[124:127]
	v_mfma_f32_16x16x32_bf16 v[120:123], v[162:165], v[186:189], v[120:123]
	v_mfma_f32_16x16x32_bf16 v[108:111], v[146:149], v[194:197], v[108:111]
	v_mfma_f32_16x16x32_bf16 v[104:107], v[162:165], v[194:197], v[104:107]
	v_mfma_f32_16x16x32_bf16 v[92:95], v[146:149], v[202:205], v[92:95]
	v_mfma_f32_16x16x32_bf16 v[88:91], v[162:165], v[202:205], v[88:91]
	v_mfma_f32_16x16x32_bf16 v[76:79], v[146:149], v[210:213], v[76:79]
	v_mfma_f32_16x16x32_bf16 v[72:75], v[162:165], v[210:213], v[72:75]
	v_mfma_f32_16x16x32_bf16 v[124:127], v[158:161], v[190:193], v[124:127]
	v_mfma_f32_16x16x32_bf16 v[120:123], v[166:169], v[190:193], v[120:123]
	v_mfma_f32_16x16x32_bf16 v[108:111], v[158:161], v[198:201], v[108:111]
	v_mfma_f32_16x16x32_bf16 v[104:107], v[166:169], v[198:201], v[104:107]
	v_mfma_f32_16x16x32_bf16 v[92:95], v[158:161], v[206:209], v[92:95]
	v_mfma_f32_16x16x32_bf16 v[88:91], v[166:169], v[206:209], v[88:91]
	v_mfma_f32_16x16x32_bf16 v[76:79], v[158:161], v[214:217], v[76:79]
	v_mfma_f32_16x16x32_bf16 v[72:75], v[166:169], v[214:217], v[72:75]
	s_setprio 0
	s_setprio 1
	v_mfma_f32_16x16x32_bf16 v[116:119], v[170:173], v[186:189], v[116:119]
	v_mfma_f32_16x16x32_bf16 v[112:115], v[178:181], v[186:189], v[112:115]
	v_mfma_f32_16x16x32_bf16 v[100:103], v[170:173], v[194:197], v[100:103]
	v_mfma_f32_16x16x32_bf16 v[96:99], v[178:181], v[194:197], v[96:99]
	v_mfma_f32_16x16x32_bf16 v[84:87], v[170:173], v[202:205], v[84:87]
	v_mfma_f32_16x16x32_bf16 v[80:83], v[178:181], v[202:205], v[80:83]
	v_mfma_f32_16x16x32_bf16 v[68:71], v[170:173], v[210:213], v[68:71]
	v_mfma_f32_16x16x32_bf16 v[64:67], v[178:181], v[210:213], v[64:67]
	v_mfma_f32_16x16x32_bf16 v[116:119], v[174:177], v[190:193], v[116:119]
	v_mfma_f32_16x16x32_bf16 v[112:115], v[182:185], v[190:193], v[112:115]
	v_mfma_f32_16x16x32_bf16 v[100:103], v[174:177], v[198:201], v[100:103]
	v_mfma_f32_16x16x32_bf16 v[96:99], v[182:185], v[198:201], v[96:99]
	v_mfma_f32_16x16x32_bf16 v[84:87], v[174:177], v[206:209], v[84:87]
	v_mfma_f32_16x16x32_bf16 v[80:83], v[182:185], v[206:209], v[80:83]
	v_mfma_f32_16x16x32_bf16 v[68:71], v[174:177], v[214:217], v[68:71]
	v_mfma_f32_16x16x32_bf16 v[64:67], v[182:185], v[214:217], v[64:67]
	s_setprio 0
	s_barrier
	s_add_i32 s34, s80, s4
	v_lshl_add_u64 v[218:219], s[74:75], 0, v[130:131]
	s_mov_b32 m0, s34
	ds_read_b128 v[186:189], v155 offset:16384
	ds_read_b128 v[190:193], v155 offset:17408
	ds_read_b128 v[194:197], v155 offset:18432
	ds_read_b128 v[198:201], v155 offset:19456
	ds_read_b128 v[202:205], v155 offset:20480
	ds_read_b128 v[206:209], v155 offset:21504
	ds_read_b128 v[210:213], v155 offset:22528
	ds_read_b128 v[214:217], v155 offset:23552
	global_load_lds_dwordx4 v[218:219], off
	s_add_i32 m0, s34, 0x2000
	s_add_u32 s34, s74, 0x40000
	v_lshl_add_u64 v[220:221], s[74:75], 0, v[134:135]
	s_addc_u32 s35, s75, 0
	s_add_i32 s89, s81, s4
	global_load_lds_dwordx4 v[220:221], off
	s_mov_b32 m0, s89
	v_lshl_add_u64 v[224:225], s[76:77], 0, v[132:133]
	global_load_lds_dwordx4 v130, s[34:35]
	s_add_i32 m0, s89, 0x2000
	s_nop 0
	global_load_lds_dwordx4 v134, s[34:35]
	v_lshl_add_u64 v[222:223], s[76:77], 0, v[128:129]
	s_mov_b32 m0, s5
	s_nop 0
	global_load_lds_dwordx4 v[222:223], off
	s_mov_b32 m0, s20
	s_nop 0
	global_load_lds_dwordx4 v[224:225], off
	s_waitcnt vmcnt(8)
	s_waitcnt lgkmcnt(0)
	s_barrier
; #define PG8_STAGE(bufoff, gbase, voff) do { _Pragma("unroll") for (int _i = 0; _i < 2; ++_i) \
;         __builtin_amdgcn_global_load_lds((const unsigned*)((const char*)(gbase) + (voff)[_i]), (LAS unsigned*)(lds + (bufoff) + ldsw + _i * 8192), 16, 0, 0); } while (0)
; #define PG8_LDA(dst, b, h) do { _Pragma("unroll") for (int m = 0; m < 4; ++m) _Pragma("unroll") for (int k = 0; k < 2; ++k) dst[m][k] = *(const LAS bf16x8*)(lds + PG8_SA(b, h) + aoff + m * 2048 + k * 1024); } while (0)
; #define PG8_LDB(dst, b, h) do { _Pragma("unroll") for (int n = 0; n < 2; ++n) _Pragma("unroll") for (int k = 0; k < 2; ++k) dst[n][k] = *(const LAS bf16x8*)(lds + PG8_SB(b, h) + boff + n * 2048 + k * 1024); } while (0)
; #define PG8_MMA(ai, bj, At, Bt) do { __builtin_amdgcn_s_setprio(1); _Pragma("unroll") for (int m = 0; m < 4; ++m) _Pragma("unroll") for (int n = 0; n < 2; ++n) _Pragma("unroll") for (int k = 0; k < 2; ++k) \
;         acc[ai][bj][m][n] = __builtin_amdgcn_mfma_f32_16x16x32_bf16(Bt[n][k], At[m][k], acc[ai][bj][m][n], 0, 0, 0); __builtin_amdgcn_s_setprio(0); } while (0)
; #define PG8_WAIT_V(n) asm volatile("s_waitcnt vmcnt(" #n ")" ::: "memory")
; #define PG8_WAIT_L(n) asm volatile("s_waitcnt lgkmcnt(" #n ")" ::: "memory")
; #define PG8_BAR __builtin_amdgcn_s_barrier()
; #define PG8_SCHED __builtin_amdgcn_sched_barrier(0)
; template <class Epi, class Sched, bool ALIGN_EPI = false, bool SP2 = false>
; __device__ __forceinline__ void gemm_phase(LAS unsigned char* lds, const Gemm g, const Sched S, const Epi E) {
;     ...
;             PG8_WAIT_V(8); PG8_WAIT_L(0); PG8_BAR; PG8_MMA(1, 0, At, B0); PG8_MMA(1, 1, At, B1); PG8_BAR; PG8_SCHED;
;             PG8_LDB(B0, 1, 0); PG8_LDB(B1, 1, 1); PG8_SCHED; PG8_LDA(At, 1, 0); PG8_STAGE(PG8_SA(0, 1), a2 + hstepA, voffA);
;             PG8_WAIT_V(8); PG8_WAIT_L(0); PG8_BAR; PG8_MMA(0, 0, At, B0); PG8_MMA(0, 1, At, B1); PG8_BAR; PG8_SCHED;
	s_setprio 1
	s_waitcnt lgkmcnt(0)
	v_mfma_f32_16x16x32_bf16 v[60:63], v[146:149], v[186:189], v[60:63]
	v_mfma_f32_16x16x32_bf16 v[56:59], v[162:165], v[186:189], v[56:59]
	v_mfma_f32_16x16x32_bf16 v[44:47], v[146:149], v[194:197], v[44:47]
	v_mfma_f32_16x16x32_bf16 v[40:43], v[162:165], v[194:197], v[40:43]
	v_mfma_f32_16x16x32_bf16 v[28:31], v[146:149], v[202:205], v[28:31]
	v_mfma_f32_16x16x32_bf16 v[24:27], v[162:165], v[202:205], v[24:27]
	v_mfma_f32_16x16x32_bf16 v[12:15], v[146:149], v[210:213], v[12:15]
	v_mfma_f32_16x16x32_bf16 v[8:11], v[162:165], v[210:213], v[8:11]
	v_mfma_f32_16x16x32_bf16 v[60:63], v[158:161], v[190:193], v[60:63]
	v_mfma_f32_16x16x32_bf16 v[56:59], v[166:169], v[190:193], v[56:59]
	v_mfma_f32_16x16x32_bf16 v[44:47], v[158:161], v[198:201], v[44:47]
	v_mfma_f32_16x16x32_bf16 v[40:43], v[166:169], v[198:201], v[40:43]
	v_mfma_f32_16x16x32_bf16 v[28:31], v[158:161], v[206:209], v[28:31]
	v_mfma_f32_16x16x32_bf16 v[24:27], v[166:169], v[206:209], v[24:27]
	v_mfma_f32_16x16x32_bf16 v[12:15], v[158:161], v[214:217], v[12:15]
	v_mfma_f32_16x16x32_bf16 v[8:11], v[166:169], v[214:217], v[8:11]
	s_setprio 0
	s_setprio 1
	v_mfma_f32_16x16x32_bf16 v[52:55], v[170:173], v[186:189], v[52:55]
	v_mfma_f32_16x16x32_bf16 v[48:51], v[178:181], v[186:189], v[48:51]
	v_mfma_f32_16x16x32_bf16 v[36:39], v[170:173], v[194:197], v[36:39]
	v_mfma_f32_16x16x32_bf16 v[32:35], v[178:181], v[194:197], v[32:35]
	v_mfma_f32_16x16x32_bf16 v[20:23], v[170:173], v[202:205], v[20:23]
	v_mfma_f32_16x16x32_bf16 v[16:19], v[178:181], v[202:205], v[16:19]
	v_mfma_f32_16x16x32_bf16 v[4:7], v[170:173], v[210:213], v[4:7]
	v_mfma_f32_16x16x32_bf16 v[0:3], v[178:181], v[210:213], v[0:3]
	v_mfma_f32_16x16x32_bf16 v[52:55], v[174:177], v[190:193], v[52:55]
	v_mfma_f32_16x16x32_bf16 v[48:51], v[182:185], v[190:193], v[48:51]
	v_mfma_f32_16x16x32_bf16 v[36:39], v[174:177], v[198:201], v[36:39]
	v_mfma_f32_16x16x32_bf16 v[32:35], v[182:185], v[198:201], v[32:35]
	v_mfma_f32_16x16x32_bf16 v[20:23], v[174:177], v[206:209], v[20:23]
	v_mfma_f32_16x16x32_bf16 v[16:19], v[182:185], v[206:209], v[16:19]
	v_mfma_f32_16x16x32_bf16 v[4:7], v[174:177], v[214:217], v[4:7]
	v_mfma_f32_16x16x32_bf16 v[0:3], v[182:185], v[214:217], v[0:3]
	s_setprio 0
	s_barrier
	s_add_i32 s89, 0, 0x18000
	s_add_i32 s90, 0, 0x1c000
	v_add_u32_e32 v166, s89, v151
	v_add_u32_e32 v182, s90, v151
	ds_read_b128 v[146:149], v166
	ds_read_b128 v[158:161], v166 offset:1024
	ds_read_b128 v[162:165], v166 offset:2048
	ds_read_b128 v[166:169], v166 offset:3072
	ds_read_b128 v[170:173], v182
	ds_read_b128 v[174:177], v182 offset:1024
	ds_read_b128 v[178:181], v182 offset:2048
	ds_read_b128 v[182:185], v182 offset:3072
	s_add_u32 s34, s76, 0x80000
	s_addc_u32 s35, s77, 0
	s_mov_b32 m0, s21
	ds_read_b128 v[186:189], v155 offset:32768
	ds_read_b128 v[190:193], v155 offset:33792
	ds_read_b128 v[194:197], v155 offset:34816
	ds_read_b128 v[198:201], v155 offset:35840
	ds_read_b128 v[202:205], v155 offset:36864
	ds_read_b128 v[206:209], v155 offset:37888
	ds_read_b128 v[210:213], v155 offset:38912
	ds_read_b128 v[214:217], v155 offset:39936
	global_load_lds_dwordx4 v128, s[34:35]
	s_mov_b32 m0, s29
	s_nop 0
	global_load_lds_dwordx4 v132, s[34:35]
	s_waitcnt vmcnt(8)
	s_waitcnt lgkmcnt(0)
	s_barrier
	s_setprio 1
	s_waitcnt lgkmcnt(0)
	v_mfma_f32_16x16x32_bf16 v[124:127], v[146:149], v[186:189], v[124:127]
	v_mfma_f32_16x16x32_bf16 v[120:123], v[162:165], v[186:189], v[120:123]
	v_mfma_f32_16x16x32_bf16 v[108:111], v[146:149], v[194:197], v[108:111]
	v_mfma_f32_16x16x32_bf16 v[104:107], v[162:165], v[194:197], v[104:107]
	v_mfma_f32_16x16x32_bf16 v[92:95], v[146:149], v[202:205], v[92:95]
	v_mfma_f32_16x16x32_bf16 v[88:91], v[162:165], v[202:205], v[88:91]
	v_mfma_f32_16x16x32_bf16 v[76:79], v[146:149], v[210:213], v[76:79]
	v_mfma_f32_16x16x32_bf16 v[72:75], v[162:165], v[210:213], v[72:75]
	v_mfma_f32_16x16x32_bf16 v[124:127], v[158:161], v[190:193], v[124:127]
	v_mfma_f32_16x16x32_bf16 v[120:123], v[166:169], v[190:193], v[120:123]
	v_mfma_f32_16x16x32_bf16 v[108:111], v[158:161], v[198:201], v[108:111]
	v_mfma_f32_16x16x32_bf16 v[104:107], v[166:169], v[198:201], v[104:107]
	v_mfma_f32_16x16x32_bf16 v[92:95], v[158:161], v[206:209], v[92:95]
	v_mfma_f32_16x16x32_bf16 v[88:91], v[166:169], v[206:209], v[88:91]
	v_mfma_f32_16x16x32_bf16 v[76:79], v[158:161], v[214:217], v[76:79]
	v_mfma_f32_16x16x32_bf16 v[72:75], v[166:169], v[214:217], v[72:75]
	s_setprio 0
	s_setprio 1
	v_mfma_f32_16x16x32_bf16 v[116:119], v[170:173], v[186:189], v[116:119]
	v_mfma_f32_16x16x32_bf16 v[112:115], v[178:181], v[186:189], v[112:115]
	v_mfma_f32_16x16x32_bf16 v[100:103], v[170:173], v[194:197], v[100:103]
	v_mfma_f32_16x16x32_bf16 v[96:99], v[178:181], v[194:197], v[96:99]
	v_mfma_f32_16x16x32_bf16 v[84:87], v[170:173], v[202:205], v[84:87]
	v_mfma_f32_16x16x32_bf16 v[80:83], v[178:181], v[202:205], v[80:83]
	v_mfma_f32_16x16x32_bf16 v[68:71], v[170:173], v[210:213], v[68:71]
	v_mfma_f32_16x16x32_bf16 v[64:67], v[178:181], v[210:213], v[64:67]
	v_mfma_f32_16x16x32_bf16 v[116:119], v[174:177], v[190:193], v[116:119]
	v_mfma_f32_16x16x32_bf16 v[112:115], v[182:185], v[190:193], v[112:115]
	v_mfma_f32_16x16x32_bf16 v[100:103], v[174:177], v[198:201], v[100:103]
	v_mfma_f32_16x16x32_bf16 v[96:99], v[182:185], v[198:201], v[96:99]
	v_mfma_f32_16x16x32_bf16 v[84:87], v[174:177], v[206:209], v[84:87]
	v_mfma_f32_16x16x32_bf16 v[80:83], v[182:185], v[206:209], v[80:83]
	v_mfma_f32_16x16x32_bf16 v[68:71], v[174:177], v[214:217], v[68:71]
	v_mfma_f32_16x16x32_bf16 v[64:67], v[182:185], v[214:217], v[64:67]
	s_setprio 0
	s_barrier
; #define PG8_STAGE(bufoff, gbase, voff) do { _Pragma("unroll") for (int _i = 0; _i < 2; ++_i) \
;         __builtin_amdgcn_global_load_lds((const unsigned*)((const char*)(gbase) + (voff)[_i]), (LAS unsigned*)(lds + (bufoff) + ldsw + _i * 8192), 16, 0, 0); } while (0)
; #define PG8_LDA(dst, b, h) do { _Pragma("unroll") for (int m = 0; m < 4; ++m) _Pragma("unroll") for (int k = 0; k < 2; ++k) dst[m][k] = *(const LAS bf16x8*)(lds + PG8_SA(b, h) + aoff + m * 2048 + k * 1024); } while (0)
; #define PG8_MMA(ai, bj, At, Bt) do { __builtin_amdgcn_s_setprio(1); _Pragma("unroll") for (int m = 0; m < 4; ++m) _Pragma("unroll") for (int n = 0; n < 2; ++n) _Pragma("unroll") for (int k = 0; k < 2; ++k) \
;         acc[ai][bj][m][n] = __builtin_amdgcn_mfma_f32_16x16x32_bf16(Bt[n][k], At[m][k], acc[ai][bj][m][n], 0, 0, 0); __builtin_amdgcn_s_setprio(0); } while (0)
; #define PG8_WAIT_V(n) asm volatile("s_waitcnt vmcnt(" #n ")" ::: "memory")
; #define PG8_WAIT_L(n) asm volatile("s_waitcnt lgkmcnt(" #n ")" ::: "memory")
; #define PG8_BAR __builtin_amdgcn_s_barrier()
; #define PG8_SCHED __builtin_amdgcn_sched_barrier(0)
; template <class Epi, class Sched, bool ALIGN_EPI = false, bool SP2 = false>
; __device__ __forceinline__ void gemm_phase(LAS unsigned char* lds, const Gemm g, const Sched S, const Epi E) {
;     ...
;             PG8_LDA(At, 1, 1); PG8_STAGE(PG8_SB(1, 0), b3, voffB); PG8_STAGE(PG8_SB(1, 1), b3 + hstepB, voffB); PG8_STAGE(PG8_SA(1, 0), a3, voffA);
;             PG8_WAIT_V(8); PG8_WAIT_L(0); PG8_BAR; PG8_MMA(1, 0, At, B0); PG8_MMA(1, 1, At, B1); PG8_BAR; PG8_SCHED;
	s_add_i32 s34, s89, s4
	v_lshl_add_u64 v[218:219], v[218:219], 0, s[14:15]
	s_mov_b32 m0, s34
	ds_read_b128 v[186:189], v155 offset:49152
	ds_read_b128 v[190:193], v155 offset:50176
	ds_read_b128 v[194:197], v155 offset:51200
	ds_read_b128 v[198:201], v155 offset:52224
	ds_read_b128 v[202:205], v155 offset:53248
	ds_read_b128 v[206:209], v155 offset:54272
	ds_read_b128 v[210:213], v155 offset:55296
	ds_read_b128 v[214:217], v155 offset:56320
	global_load_lds_dwordx4 v[218:219], off
	s_add_i32 m0, s34, 0x2000
	s_add_u32 s34, s74, 0x40080
	v_lshl_add_u64 v[218:219], v[220:221], 0, s[14:15]
	s_addc_u32 s35, s75, 0
	s_add_i32 s74, s90, s4
	global_load_lds_dwordx4 v[218:219], off
	s_mov_b32 m0, s74
	s_nop 0
	global_load_lds_dwordx4 v130, s[34:35]
	s_add_i32 m0, s74, 0x2000
	s_nop 0
	global_load_lds_dwordx4 v134, s[34:35]
	v_lshl_add_u64 v[218:219], v[222:223], 0, s[14:15]
	s_mov_b32 m0, s33
	s_nop 0
	global_load_lds_dwordx4 v[218:219], off
	v_lshl_add_u64 v[218:219], v[224:225], 0, s[14:15]
	s_mov_b32 m0, s44
	s_nop 0
	global_load_lds_dwordx4 v[218:219], off
	s_waitcnt vmcnt(8)
	s_waitcnt lgkmcnt(0)
	s_barrier
	s_setprio 1
	s_waitcnt lgkmcnt(0)
	v_mfma_f32_16x16x32_bf16 v[60:63], v[146:149], v[186:189], v[60:63]
	v_mfma_f32_16x16x32_bf16 v[56:59], v[162:165], v[186:189], v[56:59]
	v_mfma_f32_16x16x32_bf16 v[44:47], v[146:149], v[194:197], v[44:47]
	v_mfma_f32_16x16x32_bf16 v[40:43], v[162:165], v[194:197], v[40:43]
	v_mfma_f32_16x16x32_bf16 v[28:31], v[146:149], v[202:205], v[28:31]
	v_mfma_f32_16x16x32_bf16 v[24:27], v[162:165], v[202:205], v[24:27]
	v_mfma_f32_16x16x32_bf16 v[12:15], v[146:149], v[210:213], v[12:15]
	v_mfma_f32_16x16x32_bf16 v[8:11], v[162:165], v[210:213], v[8:11]
	v_mfma_f32_16x16x32_bf16 v[60:63], v[158:161], v[190:193], v[60:63]
	v_mfma_f32_16x16x32_bf16 v[56:59], v[166:169], v[190:193], v[56:59]
	v_mfma_f32_16x16x32_bf16 v[44:47], v[158:161], v[198:201], v[44:47]
	v_mfma_f32_16x16x32_bf16 v[40:43], v[166:169], v[198:201], v[40:43]
	v_mfma_f32_16x16x32_bf16 v[28:31], v[158:161], v[206:209], v[28:31]
	v_mfma_f32_16x16x32_bf16 v[24:27], v[166:169], v[206:209], v[24:27]
	v_mfma_f32_16x16x32_bf16 v[12:15], v[158:161], v[214:217], v[12:15]
	v_mfma_f32_16x16x32_bf16 v[8:11], v[166:169], v[214:217], v[8:11]
	s_setprio 0
	s_setprio 1
	v_mfma_f32_16x16x32_bf16 v[52:55], v[170:173], v[186:189], v[52:55]
	v_mfma_f32_16x16x32_bf16 v[48:51], v[178:181], v[186:189], v[48:51]
	v_mfma_f32_16x16x32_bf16 v[36:39], v[170:173], v[194:197], v[36:39]
	v_mfma_f32_16x16x32_bf16 v[32:35], v[178:181], v[194:197], v[32:35]
	v_mfma_f32_16x16x32_bf16 v[20:23], v[170:173], v[202:205], v[20:23]
	v_mfma_f32_16x16x32_bf16 v[16:19], v[178:181], v[202:205], v[16:19]
	v_mfma_f32_16x16x32_bf16 v[4:7], v[170:173], v[210:213], v[4:7]
	v_mfma_f32_16x16x32_bf16 v[0:3], v[178:181], v[210:213], v[0:3]
	v_mfma_f32_16x16x32_bf16 v[52:55], v[174:177], v[190:193], v[52:55]
	v_mfma_f32_16x16x32_bf16 v[48:51], v[182:185], v[190:193], v[48:51]
	v_mfma_f32_16x16x32_bf16 v[36:39], v[174:177], v[198:201], v[36:39]
	v_mfma_f32_16x16x32_bf16 v[32:35], v[182:185], v[198:201], v[32:35]
	v_mfma_f32_16x16x32_bf16 v[20:23], v[174:177], v[206:209], v[20:23]
	v_mfma_f32_16x16x32_bf16 v[16:19], v[182:185], v[206:209], v[16:19]
	v_mfma_f32_16x16x32_bf16 v[4:7], v[174:177], v[214:217], v[4:7]
	v_mfma_f32_16x16x32_bf16 v[0:3], v[182:185], v[214:217], v[0:3]
	s_setprio 0
	s_barrier
	s_add_i32 s88, s88, 2
	s_add_u32 s72, s72, 0x100
	s_addc_u32 s73, s73, 0
	s_add_u32 s86, s86, 0x100
	s_addc_u32 s87, s87, 0
	s_cmp_gt_u32 s88, 13
	s_cbranch_scc0 .LBB0_791
	s_and_b64 vcc, exec, s[50:51]
	s_cbranch_vccz .LBB0_794
	s_barrier

; #define PG8_STAGE(bufoff, gbase, voff) do { _Pragma("unroll") for (int _i = 0; _i < 2; ++_i) \
;         __builtin_amdgcn_global_load_lds((const unsigned*)((const char*)(gbase) + (voff)[_i]), (LAS unsigned*)(lds + (bufoff) + ldsw + _i * 8192), 16, 0, 0); } while (0)
; #define PG8_LDA(dst, b, h) do { _Pragma("unroll") for (int m = 0; m < 4; ++m) _Pragma("unroll") for (int k = 0; k < 2; ++k) dst[m][k] = *(const LAS bf16x8*)(lds + PG8_SA(b, h) + aoff + m * 2048 + k * 1024); } while (0)
; #define PG8_LDB(dst, b, h) do { _Pragma("unroll") for (int n = 0; n < 2; ++n) _Pragma("unroll") for (int k = 0; k < 2; ++k) dst[n][k] = *(const LAS bf16x8*)(lds + PG8_SB(b, h) + boff + n * 2048 + k * 1024); } while (0)
; #define PG8_MMA(ai, bj, At, Bt) do { __builtin_amdgcn_s_setprio(1); _Pragma("unroll") for (int m = 0; m < 4; ++m) _Pragma("unroll") for (int n = 0; n < 2; ++n) _Pragma("unroll") for (int k = 0; k < 2; ++k) \
;         acc[ai][bj][m][n] = __builtin_amdgcn_mfma_f32_16x16x32_bf16(Bt[n][k], At[m][k], acc[ai][bj][m][n], 0, 0, 0); __builtin_amdgcn_s_setprio(0); } while (0)
; #define PG8_WAIT_V(n) asm volatile("s_waitcnt vmcnt(" #n ")" ::: "memory")
; #define PG8_WAIT_L(n) asm volatile("s_waitcnt lgkmcnt(" #n ")" ::: "memory")
; #define PG8_BAR __builtin_amdgcn_s_barrier()
; template <class Epi, class Sched, bool ALIGN_EPI = false, bool SP2 = false>
; __device__ __forceinline__ void gemm_phase(LAS unsigned char* lds, const Gemm g, const Sched S, const Epi E) {
;     ...
;             const bool last = (t == nt - 2);
;             const char* a1 = cA + (size_t)(t + 1) * kstep;
;             const char* a2 = last ? nA : cA + (size_t)(t + 2) * kstep; const char* b2 = last ? nB : cB + (size_t)(t + 2) * kstep;
;             const char* a3 = a2 + kstep; const char* b3 = b2 + kstep;
;             if (last && has_next) S.a_ready(nxt);
;             if constexpr (SP2) {
;             PG8_LDB(B0, 0, 0); PG8_LDB(B1, 0, 1); PG8_SCHED; PG8_LDA(At, 0, 0); PG8_STAGE(PG8_SA(1, 1), a1 + hstepA, voffA);
;             PG8_WAIT_V(8); PG8_WAIT_L(0); PG8_BAR; PG8_MMA(0, 0, At, B0); PG8_MMA(0, 1, At, B1); PG8_BAR; PG8_SCHED;
;             PG8_LDA(At, 0, 1); PG8_STAGE(PG8_SB(0, 0), b2, voffB); PG8_STAGE(PG8_SB(0, 1), b2 + hstepB, voffB); PG8_STAGE(PG8_SA(0, 0), a2, voffA);
;             PG8_WAIT_V(8); PG8_WAIT_L(0); PG8_BAR; PG8_MMA(1, 0, At, B0); PG8_MMA(1, 1, At, B1); PG8_BAR; PG8_SCHED;
.LBB0_1407:
	ds_read_b128 v[150:153], v180
	ds_read_b128 v[154:157], v180 offset:1024
	ds_read_b128 v[158:161], v180 offset:2048
	ds_read_b128 v[162:165], v180 offset:3072
	ds_read_b128 v[166:169], v181
	ds_read_b128 v[170:173], v181 offset:1024
	ds_read_b128 v[184:187], v181 offset:2048
	ds_read_b128 v[188:191], v181 offset:3072
	s_add_u32 s56, s64, 0x100
	s_addc_u32 s57, s65, 0
	s_cmp_eq_u32 s80, 2
	s_cselect_b32 s67, s9, s57
	s_cselect_b32 s66, s8, s56
	s_cselect_b32 s59, s19, s79
	s_cselect_b32 s58, s18, s78
	s_add_i32 m0, s29, 0xc000
	ds_read_b128 v[192:195], v182
	ds_read_b128 v[196:199], v182 offset:1024
	ds_read_b128 v[200:203], v182 offset:2048
	ds_read_b128 v[204:207], v182 offset:3072
	ds_read_b128 v[208:211], v182 offset:4096
	ds_read_b128 v[212:215], v182 offset:5120
	ds_read_b128 v[216:219], v182 offset:6144
	ds_read_b128 v[220:223], v182 offset:7168
	global_load_lds_dwordx4 v142, s[64:65]
	s_add_i32 m0, s29, 0xe000
	s_nop 0
	global_load_lds_dwordx4 v144, s[64:65]
	s_waitcnt vmcnt(8)
	s_waitcnt lgkmcnt(0)
	s_barrier
	s_setprio 1
	s_waitcnt lgkmcnt(0)
	v_mfma_f32_16x16x32_bf16 v[124:127], v[150:153], v[192:195], v[124:127]
	v_mfma_f32_16x16x32_bf16 v[120:123], v[158:161], v[192:195], v[120:123]
	v_mfma_f32_16x16x32_bf16 v[108:111], v[150:153], v[200:203], v[108:111]
	v_mfma_f32_16x16x32_bf16 v[104:107], v[158:161], v[200:203], v[104:107]
	v_mfma_f32_16x16x32_bf16 v[92:95], v[150:153], v[208:211], v[92:95]
	v_mfma_f32_16x16x32_bf16 v[88:91], v[158:161], v[208:211], v[88:91]
	v_mfma_f32_16x16x32_bf16 v[76:79], v[150:153], v[216:219], v[76:79]
	v_mfma_f32_16x16x32_bf16 v[72:75], v[158:161], v[216:219], v[72:75]
	v_mfma_f32_16x16x32_bf16 v[124:127], v[154:157], v[196:199], v[124:127]
	v_mfma_f32_16x16x32_bf16 v[120:123], v[162:165], v[196:199], v[120:123]
	v_mfma_f32_16x16x32_bf16 v[108:111], v[154:157], v[204:207], v[108:111]
	v_mfma_f32_16x16x32_bf16 v[104:107], v[162:165], v[204:207], v[104:107]
	v_mfma_f32_16x16x32_bf16 v[92:95], v[154:157], v[212:215], v[92:95]
	v_mfma_f32_16x16x32_bf16 v[88:91], v[162:165], v[212:215], v[88:91]
	v_mfma_f32_16x16x32_bf16 v[76:79], v[154:157], v[220:223], v[76:79]
	v_mfma_f32_16x16x32_bf16 v[72:75], v[162:165], v[220:223], v[72:75]
	s_setprio 0
	s_setprio 1
	v_mfma_f32_16x16x32_bf16 v[116:119], v[166:169], v[192:195], v[116:119]
	v_mfma_f32_16x16x32_bf16 v[112:115], v[184:187], v[192:195], v[112:115]
	v_mfma_f32_16x16x32_bf16 v[100:103], v[166:169], v[200:203], v[100:103]
	v_mfma_f32_16x16x32_bf16 v[96:99], v[184:187], v[200:203], v[96:99]
	v_mfma_f32_16x16x32_bf16 v[84:87], v[166:169], v[208:211], v[84:87]
	v_mfma_f32_16x16x32_bf16 v[80:83], v[184:187], v[208:211], v[80:83]
	v_mfma_f32_16x16x32_bf16 v[68:71], v[166:169], v[216:219], v[68:71]
	v_mfma_f32_16x16x32_bf16 v[64:67], v[184:187], v[216:219], v[64:67]
	v_mfma_f32_16x16x32_bf16 v[116:119], v[170:173], v[196:199], v[116:119]
	v_mfma_f32_16x16x32_bf16 v[112:115], v[188:191], v[196:199], v[112:115]
	v_mfma_f32_16x16x32_bf16 v[100:103], v[170:173], v[204:207], v[100:103]
	v_mfma_f32_16x16x32_bf16 v[96:99], v[188:191], v[204:207], v[96:99]
	v_mfma_f32_16x16x32_bf16 v[84:87], v[170:173], v[212:215], v[84:87]
	v_mfma_f32_16x16x32_bf16 v[80:83], v[188:191], v[212:215], v[80:83]
	v_mfma_f32_16x16x32_bf16 v[68:71], v[170:173], v[220:223], v[68:71]
	v_mfma_f32_16x16x32_bf16 v[64:67], v[188:191], v[220:223], v[64:67]
	s_setprio 0
	s_barrier
	s_add_i32 s34, s71, s20
	v_lshl_add_u64 v[176:177], s[58:59], 0, v[132:133]
	s_mov_b32 m0, s34
	ds_read_b128 v[192:195], v182 offset:16384
	ds_read_b128 v[196:199], v182 offset:17408
	ds_read_b128 v[200:203], v182 offset:18432
	ds_read_b128 v[204:207], v182 offset:19456
	ds_read_b128 v[208:211], v182 offset:20480
	ds_read_b128 v[212:215], v182 offset:21504
	ds_read_b128 v[216:219], v182 offset:22528
	ds_read_b128 v[220:223], v182 offset:23552
	global_load_lds_dwordx4 v[176:177], off
	s_add_i32 m0, s34, 0x2000
	s_add_u32 s34, s58, 0x18000
	v_lshl_add_u64 v[224:225], s[58:59], 0, v[128:129]
	s_addc_u32 s35, s59, 0
	s_add_i32 s64, s72, s20
	global_load_lds_dwordx4 v[224:225], off
	s_mov_b32 m0, s64
	v_lshl_add_u64 v[228:229], s[66:67], 0, v[130:131]
	global_load_lds_dwordx4 v132, s[34:35]
	s_add_i32 m0, s64, 0x2000
	s_nop 0
	global_load_lds_dwordx4 v128, s[34:35]
	v_lshl_add_u64 v[226:227], s[66:67], 0, v[134:135]
	s_mov_b32 m0, s29
	s_nop 0
	global_load_lds_dwordx4 v[226:227], off
	s_mov_b32 m0, s30
	s_nop 0
	global_load_lds_dwordx4 v[228:229], off
	s_waitcnt vmcnt(8)
	s_waitcnt lgkmcnt(0)
	s_barrier
; #define PG8_STAGE(bufoff, gbase, voff) do { _Pragma("unroll") for (int _i = 0; _i < 2; ++_i) \
;         __builtin_amdgcn_global_load_lds((const unsigned*)((const char*)(gbase) + (voff)[_i]), (LAS unsigned*)(lds + (bufoff) + ldsw + _i * 8192), 16, 0, 0); } while (0)
; #define PG8_LDA(dst, b, h) do { _Pragma("unroll") for (int m = 0; m < 4; ++m) _Pragma("unroll") for (int k = 0; k < 2; ++k) dst[m][k] = *(const LAS bf16x8*)(lds + PG8_SA(b, h) + aoff + m * 2048 + k * 1024); } while (0)
; #define PG8_LDB(dst, b, h) do { _Pragma("unroll") for (int n = 0; n < 2; ++n) _Pragma("unroll") for (int k = 0; k < 2; ++k) dst[n][k] = *(const LAS bf16x8*)(lds + PG8_SB(b, h) + boff + n * 2048 + k * 1024); } while (0)
; #define PG8_MMA(ai, bj, At, Bt) do { __builtin_amdgcn_s_setprio(1); _Pragma("unroll") for (int m = 0; m < 4; ++m) _Pragma("unroll") for (int n = 0; n < 2; ++n) _Pragma("unroll") for (int k = 0; k < 2; ++k) \
;         acc[ai][bj][m][n] = __builtin_amdgcn_mfma_f32_16x16x32_bf16(Bt[n][k], At[m][k], acc[ai][bj][m][n], 0, 0, 0); __builtin_amdgcn_s_setprio(0); } while (0)
; #define PG8_WAIT_V(n) asm volatile("s_waitcnt vmcnt(" #n ")" ::: "memory")
; #define PG8_WAIT_L(n) asm volatile("s_waitcnt lgkmcnt(" #n ")" ::: "memory")
; #define PG8_BAR __builtin_amdgcn_s_barrier()
; #define PG8_SCHED __builtin_amdgcn_sched_barrier(0)
; template <class Epi, class Sched, bool ALIGN_EPI = false, bool SP2 = false>
; __device__ __forceinline__ void gemm_phase(LAS unsigned char* lds, const Gemm g, const Sched S, const Epi E) {
;     ...
;             PG8_WAIT_V(8); PG8_WAIT_L(0); PG8_BAR; PG8_MMA(1, 0, At, B0); PG8_MMA(1, 1, At, B1); PG8_BAR; PG8_SCHED;
;             PG8_LDB(B0, 1, 0); PG8_LDB(B1, 1, 1); PG8_SCHED; PG8_LDA(At, 1, 0); PG8_STAGE(PG8_SA(0, 1), a2 + hstepA, voffA);
;             PG8_WAIT_V(8); PG8_WAIT_L(0); PG8_BAR; PG8_MMA(0, 0, At, B0); PG8_MMA(0, 1, At, B1); PG8_BAR; PG8_SCHED;
	s_setprio 1
	s_waitcnt lgkmcnt(0)
	v_mfma_f32_16x16x32_bf16 v[60:63], v[150:153], v[192:195], v[60:63]
	v_mfma_f32_16x16x32_bf16 v[56:59], v[158:161], v[192:195], v[56:59]
	v_mfma_f32_16x16x32_bf16 v[44:47], v[150:153], v[200:203], v[44:47]
	v_mfma_f32_16x16x32_bf16 v[40:43], v[158:161], v[200:203], v[40:43]
	v_mfma_f32_16x16x32_bf16 v[28:31], v[150:153], v[208:211], v[28:31]
	v_mfma_f32_16x16x32_bf16 v[24:27], v[158:161], v[208:211], v[24:27]
	v_mfma_f32_16x16x32_bf16 v[12:15], v[150:153], v[216:219], v[12:15]
	v_mfma_f32_16x16x32_bf16 v[8:11], v[158:161], v[216:219], v[8:11]
	v_mfma_f32_16x16x32_bf16 v[60:63], v[154:157], v[196:199], v[60:63]
	v_mfma_f32_16x16x32_bf16 v[56:59], v[162:165], v[196:199], v[56:59]
	v_mfma_f32_16x16x32_bf16 v[44:47], v[154:157], v[204:207], v[44:47]
	v_mfma_f32_16x16x32_bf16 v[40:43], v[162:165], v[204:207], v[40:43]
	v_mfma_f32_16x16x32_bf16 v[28:31], v[154:157], v[212:215], v[28:31]
	v_mfma_f32_16x16x32_bf16 v[24:27], v[162:165], v[212:215], v[24:27]
	v_mfma_f32_16x16x32_bf16 v[12:15], v[154:157], v[220:223], v[12:15]
	v_mfma_f32_16x16x32_bf16 v[8:11], v[162:165], v[220:223], v[8:11]
	s_setprio 0
	s_setprio 1
	v_mfma_f32_16x16x32_bf16 v[52:55], v[166:169], v[192:195], v[52:55]
	v_mfma_f32_16x16x32_bf16 v[48:51], v[184:187], v[192:195], v[48:51]
	v_mfma_f32_16x16x32_bf16 v[36:39], v[166:169], v[200:203], v[36:39]
	v_mfma_f32_16x16x32_bf16 v[32:35], v[184:187], v[200:203], v[32:35]
	v_mfma_f32_16x16x32_bf16 v[20:23], v[166:169], v[208:211], v[20:23]
	v_mfma_f32_16x16x32_bf16 v[16:19], v[184:187], v[208:211], v[16:19]
	v_mfma_f32_16x16x32_bf16 v[4:7], v[166:169], v[216:219], v[4:7]
	v_mfma_f32_16x16x32_bf16 v[0:3], v[184:187], v[216:219], v[0:3]
	v_mfma_f32_16x16x32_bf16 v[52:55], v[170:173], v[196:199], v[52:55]
	v_mfma_f32_16x16x32_bf16 v[48:51], v[188:191], v[196:199], v[48:51]
	v_mfma_f32_16x16x32_bf16 v[36:39], v[170:173], v[204:207], v[36:39]
	v_mfma_f32_16x16x32_bf16 v[32:35], v[188:191], v[204:207], v[32:35]
	v_mfma_f32_16x16x32_bf16 v[20:23], v[170:173], v[212:215], v[20:23]
	v_mfma_f32_16x16x32_bf16 v[16:19], v[188:191], v[212:215], v[16:19]
	v_mfma_f32_16x16x32_bf16 v[4:7], v[170:173], v[220:223], v[4:7]
	v_mfma_f32_16x16x32_bf16 v[0:3], v[188:191], v[220:223], v[0:3]
	s_setprio 0
	s_barrier
	s_add_i32 s64, 0, 0x18000
	s_add_i32 s65, 0, 0x1c000
	v_add_u32_e32 v162, s64, v178
	v_add_u32_e32 v174, s65, v178
	ds_read_b128 v[150:153], v162
	ds_read_b128 v[154:157], v162 offset:1024
	ds_read_b128 v[158:161], v162 offset:2048
	ds_read_b128 v[162:165], v162 offset:3072
	ds_read_b128 v[166:169], v174
	ds_read_b128 v[170:173], v174 offset:1024
	ds_read_b128 v[184:187], v174 offset:2048
	ds_read_b128 v[188:191], v174 offset:3072
	s_add_u32 s34, s66, 0x130000
	s_addc_u32 s35, s67, 0
	s_mov_b32 m0, s31
	ds_read_b128 v[192:195], v182 offset:32768
	ds_read_b128 v[196:199], v182 offset:33792
	ds_read_b128 v[200:203], v182 offset:34816
	ds_read_b128 v[204:207], v182 offset:35840
	ds_read_b128 v[208:211], v182 offset:36864
	ds_read_b128 v[212:215], v182 offset:37888
	ds_read_b128 v[216:219], v182 offset:38912
	ds_read_b128 v[220:223], v182 offset:39936
	global_load_lds_dwordx4 v134, s[34:35]
	s_mov_b32 m0, s33
	s_nop 0
	global_load_lds_dwordx4 v130, s[34:35]
	s_waitcnt vmcnt(8)
	s_waitcnt lgkmcnt(0)
	s_barrier
	s_setprio 1
	s_waitcnt lgkmcnt(0)
	v_mfma_f32_16x16x32_bf16 v[124:127], v[150:153], v[192:195], v[124:127]
	v_mfma_f32_16x16x32_bf16 v[120:123], v[158:161], v[192:195], v[120:123]
	v_mfma_f32_16x16x32_bf16 v[108:111], v[150:153], v[200:203], v[108:111]
	v_mfma_f32_16x16x32_bf16 v[104:107], v[158:161], v[200:203], v[104:107]
	v_mfma_f32_16x16x32_bf16 v[92:95], v[150:153], v[208:211], v[92:95]
	v_mfma_f32_16x16x32_bf16 v[88:91], v[158:161], v[208:211], v[88:91]
	v_mfma_f32_16x16x32_bf16 v[76:79], v[150:153], v[216:219], v[76:79]
	v_mfma_f32_16x16x32_bf16 v[72:75], v[158:161], v[216:219], v[72:75]
	v_mfma_f32_16x16x32_bf16 v[124:127], v[154:157], v[196:199], v[124:127]
	v_mfma_f32_16x16x32_bf16 v[120:123], v[162:165], v[196:199], v[120:123]
	v_mfma_f32_16x16x32_bf16 v[108:111], v[154:157], v[204:207], v[108:111]
	v_mfma_f32_16x16x32_bf16 v[104:107], v[162:165], v[204:207], v[104:107]
	v_mfma_f32_16x16x32_bf16 v[92:95], v[154:157], v[212:215], v[92:95]
	v_mfma_f32_16x16x32_bf16 v[88:91], v[162:165], v[212:215], v[88:91]
	v_mfma_f32_16x16x32_bf16 v[76:79], v[154:157], v[220:223], v[76:79]
	v_mfma_f32_16x16x32_bf16 v[72:75], v[162:165], v[220:223], v[72:75]
	s_setprio 0
	s_setprio 1
	v_mfma_f32_16x16x32_bf16 v[116:119], v[166:169], v[192:195], v[116:119]
	v_mfma_f32_16x16x32_bf16 v[112:115], v[184:187], v[192:195], v[112:115]
	v_mfma_f32_16x16x32_bf16 v[100:103], v[166:169], v[200:203], v[100:103]
	v_mfma_f32_16x16x32_bf16 v[96:99], v[184:187], v[200:203], v[96:99]
	v_mfma_f32_16x16x32_bf16 v[84:87], v[166:169], v[208:211], v[84:87]
	v_mfma_f32_16x16x32_bf16 v[80:83], v[184:187], v[208:211], v[80:83]
	v_mfma_f32_16x16x32_bf16 v[68:71], v[166:169], v[216:219], v[68:71]
	v_mfma_f32_16x16x32_bf16 v[64:67], v[184:187], v[216:219], v[64:67]
	v_mfma_f32_16x16x32_bf16 v[116:119], v[170:173], v[196:199], v[116:119]
	v_mfma_f32_16x16x32_bf16 v[112:115], v[188:191], v[196:199], v[112:115]
	v_mfma_f32_16x16x32_bf16 v[100:103], v[170:173], v[204:207], v[100:103]
	v_mfma_f32_16x16x32_bf16 v[96:99], v[188:191], v[204:207], v[96:99]
	v_mfma_f32_16x16x32_bf16 v[84:87], v[170:173], v[212:215], v[84:87]
	v_mfma_f32_16x16x32_bf16 v[80:83], v[188:191], v[212:215], v[80:83]
	v_mfma_f32_16x16x32_bf16 v[68:71], v[170:173], v[220:223], v[68:71]
	v_mfma_f32_16x16x32_bf16 v[64:67], v[188:191], v[220:223], v[64:67]
	s_setprio 0
	s_barrier
; #define PG8_STAGE(bufoff, gbase, voff) do { _Pragma("unroll") for (int _i = 0; _i < 2; ++_i) \
;         __builtin_amdgcn_global_load_lds((const unsigned*)((const char*)(gbase) + (voff)[_i]), (LAS unsigned*)(lds + (bufoff) + ldsw + _i * 8192), 16, 0, 0); } while (0)
; #define PG8_LDA(dst, b, h) do { _Pragma("unroll") for (int m = 0; m < 4; ++m) _Pragma("unroll") for (int k = 0; k < 2; ++k) dst[m][k] = *(const LAS bf16x8*)(lds + PG8_SA(b, h) + aoff + m * 2048 + k * 1024); } while (0)
; #define PG8_MMA(ai, bj, At, Bt) do { __builtin_amdgcn_s_setprio(1); _Pragma("unroll") for (int m = 0; m < 4; ++m) _Pragma("unroll") for (int n = 0; n < 2; ++n) _Pragma("unroll") for (int k = 0; k < 2; ++k) \
;         acc[ai][bj][m][n] = __builtin_amdgcn_mfma_f32_16x16x32_bf16(Bt[n][k], At[m][k], acc[ai][bj][m][n], 0, 0, 0); __builtin_amdgcn_s_setprio(0); } while (0)
; #define PG8_WAIT_V(n) asm volatile("s_waitcnt vmcnt(" #n ")" ::: "memory")
; #define PG8_WAIT_L(n) asm volatile("s_waitcnt lgkmcnt(" #n ")" ::: "memory")
; #define PG8_BAR __builtin_amdgcn_s_barrier()
; #define PG8_SCHED __builtin_amdgcn_sched_barrier(0)
; template <class Epi, class Sched, bool ALIGN_EPI = false, bool SP2 = false>
; __device__ __forceinline__ void gemm_phase(LAS unsigned char* lds, const Gemm g, const Sched S, const Epi E) {
;     ...
;             PG8_LDA(At, 1, 1); PG8_STAGE(PG8_SB(1, 0), b3, voffB); PG8_STAGE(PG8_SB(1, 1), b3 + hstepB, voffB); PG8_STAGE(PG8_SA(1, 0), a3, voffA);
;             PG8_WAIT_V(8); PG8_WAIT_L(0); PG8_BAR; PG8_MMA(1, 0, At, B0); PG8_MMA(1, 1, At, B1); PG8_BAR; PG8_SCHED;
	s_add_i32 s34, s64, s20
	v_lshl_add_u64 v[176:177], v[176:177], 0, s[14:15]
	s_mov_b32 m0, s34
	ds_read_b128 v[192:195], v182 offset:49152
	ds_read_b128 v[196:199], v182 offset:50176
	ds_read_b128 v[200:203], v182 offset:51200
	ds_read_b128 v[204:207], v182 offset:52224
	ds_read_b128 v[208:211], v182 offset:53248
	ds_read_b128 v[212:215], v182 offset:54272
	ds_read_b128 v[216:219], v182 offset:55296
	ds_read_b128 v[220:223], v182 offset:56320
	global_load_lds_dwordx4 v[176:177], off
	s_add_i32 m0, s34, 0x2000
	s_add_u32 s34, s58, 0x18080
	v_lshl_add_u64 v[176:177], v[224:225], 0, s[14:15]
	s_addc_u32 s35, s59, 0
	s_add_i32 s58, s65, s20
	global_load_lds_dwordx4 v[176:177], off
	s_mov_b32 m0, s58
	s_nop 0
	global_load_lds_dwordx4 v132, s[34:35]
	s_add_i32 m0, s58, 0x2000
	s_nop 0
	global_load_lds_dwordx4 v128, s[34:35]
	v_lshl_add_u64 v[176:177], v[226:227], 0, s[14:15]
	s_mov_b32 m0, s44
	s_nop 0
	global_load_lds_dwordx4 v[176:177], off
	v_lshl_add_u64 v[176:177], v[228:229], 0, s[14:15]
	s_mov_b32 m0, s45
	s_nop 0
	global_load_lds_dwordx4 v[176:177], off
	s_waitcnt vmcnt(8)
	s_waitcnt lgkmcnt(0)
	s_barrier
	s_setprio 1
	s_waitcnt lgkmcnt(0)
	v_mfma_f32_16x16x32_bf16 v[60:63], v[150:153], v[192:195], v[60:63]
	v_mfma_f32_16x16x32_bf16 v[56:59], v[158:161], v[192:195], v[56:59]
	v_mfma_f32_16x16x32_bf16 v[44:47], v[150:153], v[200:203], v[44:47]
	v_mfma_f32_16x16x32_bf16 v[40:43], v[158:161], v[200:203], v[40:43]
	v_mfma_f32_16x16x32_bf16 v[28:31], v[150:153], v[208:211], v[28:31]
	v_mfma_f32_16x16x32_bf16 v[24:27], v[158:161], v[208:211], v[24:27]
	v_mfma_f32_16x16x32_bf16 v[12:15], v[150:153], v[216:219], v[12:15]
	v_mfma_f32_16x16x32_bf16 v[8:11], v[158:161], v[216:219], v[8:11]
	v_mfma_f32_16x16x32_bf16 v[60:63], v[154:157], v[196:199], v[60:63]
	v_mfma_f32_16x16x32_bf16 v[56:59], v[162:165], v[196:199], v[56:59]
	v_mfma_f32_16x16x32_bf16 v[44:47], v[154:157], v[204:207], v[44:47]
	v_mfma_f32_16x16x32_bf16 v[40:43], v[162:165], v[204:207], v[40:43]
	v_mfma_f32_16x16x32_bf16 v[28:31], v[154:157], v[212:215], v[28:31]
	v_mfma_f32_16x16x32_bf16 v[24:27], v[162:165], v[212:215], v[24:27]
	v_mfma_f32_16x16x32_bf16 v[12:15], v[154:157], v[220:223], v[12:15]
	v_mfma_f32_16x16x32_bf16 v[8:11], v[162:165], v[220:223], v[8:11]
	s_setprio 0
	s_setprio 1
	v_mfma_f32_16x16x32_bf16 v[52:55], v[166:169], v[192:195], v[52:55]
	v_mfma_f32_16x16x32_bf16 v[48:51], v[184:187], v[192:195], v[48:51]
	v_mfma_f32_16x16x32_bf16 v[36:39], v[166:169], v[200:203], v[36:39]
	v_mfma_f32_16x16x32_bf16 v[32:35], v[184:187], v[200:203], v[32:35]
	v_mfma_f32_16x16x32_bf16 v[20:23], v[166:169], v[208:211], v[20:23]
	v_mfma_f32_16x16x32_bf16 v[16:19], v[184:187], v[208:211], v[16:19]
	v_mfma_f32_16x16x32_bf16 v[4:7], v[166:169], v[216:219], v[4:7]
	v_mfma_f32_16x16x32_bf16 v[0:3], v[184:187], v[216:219], v[0:3]
	v_mfma_f32_16x16x32_bf16 v[52:55], v[170:173], v[196:199], v[52:55]
	v_mfma_f32_16x16x32_bf16 v[48:51], v[188:191], v[196:199], v[48:51]
	v_mfma_f32_16x16x32_bf16 v[36:39], v[170:173], v[204:207], v[36:39]
	v_mfma_f32_16x16x32_bf16 v[32:35], v[188:191], v[204:207], v[32:35]
	v_mfma_f32_16x16x32_bf16 v[20:23], v[170:173], v[212:215], v[20:23]
	v_mfma_f32_16x16x32_bf16 v[16:19], v[188:191], v[212:215], v[16:19]
	v_mfma_f32_16x16x32_bf16 v[4:7], v[170:173], v[220:223], v[4:7]
	v_mfma_f32_16x16x32_bf16 v[0:3], v[188:191], v[220:223], v[0:3]
	s_setprio 0
	s_barrier
	s_add_i32 s80, s80, 2
	s_add_u32 s78, s78, 0x100
	s_addc_u32 s79, s79, 0
	s_cmp_gt_u32 s80, 3
	s_mov_b64 s[64:65], s[56:57]
	s_cbranch_scc0 .LBB0_1407
	s_and_b64 vcc, exec, s[16:17]
	s_cbranch_vccz .LBB0_1410
	s_barrier

; #define PG8_STAGE(bufoff, gbase, voff) do { _Pragma("unroll") for (int _i = 0; _i < 2; ++_i) \
;         __builtin_amdgcn_global_load_lds((const unsigned*)((const char*)(gbase) + (voff)[_i]), (LAS unsigned*)(lds + (bufoff) + ldsw + _i * 8192), 16, 0, 0); } while (0)
; #define PG8_LDA(dst, b, h) do { _Pragma("unroll") for (int m = 0; m < 4; ++m) _Pragma("unroll") for (int k = 0; k < 2; ++k) dst[m][k] = *(const LAS bf16x8*)(lds + PG8_SA(b, h) + aoff + m * 2048 + k * 1024); } while (0)
; #define PG8_LDB(dst, b, h) do { _Pragma("unroll") for (int n = 0; n < 2; ++n) _Pragma("unroll") for (int k = 0; k < 2; ++k) dst[n][k] = *(const LAS bf16x8*)(lds + PG8_SB(b, h) + boff + n * 2048 + k * 1024); } while (0)
; #define PG8_MMA(ai, bj, At, Bt) do { __builtin_amdgcn_s_setprio(1); _Pragma("unroll") for (int m = 0; m < 4; ++m) _Pragma("unroll") for (int n = 0; n < 2; ++n) _Pragma("unroll") for (int k = 0; k < 2; ++k) \
;         acc[ai][bj][m][n] = __builtin_amdgcn_mfma_f32_16x16x32_bf16(Bt[n][k], At[m][k], acc[ai][bj][m][n], 0, 0, 0); __builtin_amdgcn_s_setprio(0); } while (0)
; #define PG8_WAIT_V(n) asm volatile("s_waitcnt vmcnt(" #n ")" ::: "memory")
; #define PG8_WAIT_L(n) asm volatile("s_waitcnt lgkmcnt(" #n ")" ::: "memory")
; #define PG8_BAR __builtin_amdgcn_s_barrier()
; template <class Epi, class Sched, bool ALIGN_EPI = false, bool SP2 = false>
; __device__ __forceinline__ void gemm_phase(LAS unsigned char* lds, const Gemm g, const Sched S, const Epi E) {
;     ...
;             const bool last = (t == nt - 2);
;             const char* a1 = cA + (size_t)(t + 1) * kstep;
;             const char* a2 = last ? nA : cA + (size_t)(t + 2) * kstep; const char* b2 = last ? nB : cB + (size_t)(t + 2) * kstep;
;             const char* a3 = a2 + kstep; const char* b3 = b2 + kstep;
;             if (last && has_next) S.a_ready(nxt);
;             if constexpr (SP2) {
;             PG8_LDB(B0, 0, 0); PG8_LDB(B1, 0, 1); PG8_SCHED; PG8_LDA(At, 0, 0); PG8_STAGE(PG8_SA(1, 1), a1 + hstepA, voffA);
;             PG8_WAIT_V(8); PG8_WAIT_L(0); PG8_BAR; PG8_MMA(0, 0, At, B0); PG8_MMA(0, 1, At, B1); PG8_BAR; PG8_SCHED;
;             PG8_LDA(At, 0, 1); PG8_STAGE(PG8_SB(0, 0), b2, voffB); PG8_STAGE(PG8_SB(0, 1), b2 + hstepB, voffB); PG8_STAGE(PG8_SA(0, 0), a2, voffA);
;             PG8_WAIT_V(8); PG8_WAIT_L(0); PG8_BAR; PG8_MMA(1, 0, At, B0); PG8_MMA(1, 1, At, B1); PG8_BAR; PG8_SCHED;
.LBB0_1612:
	ds_read_b128 v[152:155], v149
	ds_read_b128 v[156:159], v149 offset:1024
	ds_read_b128 v[160:163], v149 offset:2048
	ds_read_b128 v[164:167], v149 offset:3072
	ds_read_b128 v[168:171], v150
	ds_read_b128 v[172:175], v150 offset:1024
	ds_read_b128 v[176:179], v150 offset:2048
	ds_read_b128 v[180:183], v150 offset:3072
	s_add_u32 s10, s54, 0x100
	s_addc_u32 s11, s55, 0
	s_cmp_eq_u32 s71, 12
	s_cselect_b32 s59, s49, s11
	s_cselect_b32 s58, s48, s10
	s_cselect_b32 s57, s19, s70
	s_cselect_b32 s56, s68, s69
	s_add_i32 m0, s21, 0xc000
	ds_read_b128 v[184:187], v151
	ds_read_b128 v[188:191], v151 offset:1024
	ds_read_b128 v[192:195], v151 offset:2048
	ds_read_b128 v[196:199], v151 offset:3072
	ds_read_b128 v[200:203], v151 offset:4096
	ds_read_b128 v[204:207], v151 offset:5120
	ds_read_b128 v[208:211], v151 offset:6144
	ds_read_b128 v[212:215], v151 offset:7168
	global_load_lds_dwordx4 v138, s[54:55]
	s_add_i32 m0, s21, 0xe000
	s_nop 0
	global_load_lds_dwordx4 v140, s[54:55]
	s_waitcnt vmcnt(8)
	s_waitcnt lgkmcnt(0)
	s_barrier
	s_setprio 1
	s_waitcnt lgkmcnt(0)
	v_mfma_f32_16x16x32_bf16 v[124:127], v[152:155], v[184:187], v[124:127]
	v_mfma_f32_16x16x32_bf16 v[120:123], v[160:163], v[184:187], v[120:123]
	v_mfma_f32_16x16x32_bf16 v[116:119], v[152:155], v[192:195], v[116:119]
	v_mfma_f32_16x16x32_bf16 v[112:115], v[160:163], v[192:195], v[112:115]
	v_mfma_f32_16x16x32_bf16 v[100:103], v[152:155], v[200:203], v[100:103]
	v_mfma_f32_16x16x32_bf16 v[96:99], v[160:163], v[200:203], v[96:99]
	v_mfma_f32_16x16x32_bf16 v[84:87], v[152:155], v[208:211], v[84:87]
	v_mfma_f32_16x16x32_bf16 v[80:83], v[160:163], v[208:211], v[80:83]
	v_mfma_f32_16x16x32_bf16 v[124:127], v[156:159], v[188:191], v[124:127]
	v_mfma_f32_16x16x32_bf16 v[120:123], v[164:167], v[188:191], v[120:123]
	v_mfma_f32_16x16x32_bf16 v[116:119], v[156:159], v[196:199], v[116:119]
	v_mfma_f32_16x16x32_bf16 v[112:115], v[164:167], v[196:199], v[112:115]
	v_mfma_f32_16x16x32_bf16 v[100:103], v[156:159], v[204:207], v[100:103]
	v_mfma_f32_16x16x32_bf16 v[96:99], v[164:167], v[204:207], v[96:99]
	v_mfma_f32_16x16x32_bf16 v[84:87], v[156:159], v[212:215], v[84:87]
	v_mfma_f32_16x16x32_bf16 v[80:83], v[164:167], v[212:215], v[80:83]
	s_setprio 0
	s_setprio 1
	v_mfma_f32_16x16x32_bf16 v[108:111], v[168:171], v[184:187], v[108:111]
	v_mfma_f32_16x16x32_bf16 v[104:107], v[176:179], v[184:187], v[104:107]
	v_mfma_f32_16x16x32_bf16 v[92:95], v[168:171], v[192:195], v[92:95]
	v_mfma_f32_16x16x32_bf16 v[88:91], v[176:179], v[192:195], v[88:91]
	v_mfma_f32_16x16x32_bf16 v[76:79], v[168:171], v[200:203], v[76:79]
	v_mfma_f32_16x16x32_bf16 v[72:75], v[176:179], v[200:203], v[72:75]
	v_mfma_f32_16x16x32_bf16 v[68:71], v[168:171], v[208:211], v[68:71]
	v_mfma_f32_16x16x32_bf16 v[64:67], v[176:179], v[208:211], v[64:67]
	v_mfma_f32_16x16x32_bf16 v[108:111], v[172:175], v[188:191], v[108:111]
	v_mfma_f32_16x16x32_bf16 v[104:107], v[180:183], v[188:191], v[104:107]
	v_mfma_f32_16x16x32_bf16 v[92:95], v[172:175], v[196:199], v[92:95]
	v_mfma_f32_16x16x32_bf16 v[88:91], v[180:183], v[196:199], v[88:91]
	v_mfma_f32_16x16x32_bf16 v[76:79], v[172:175], v[204:207], v[76:79]
	v_mfma_f32_16x16x32_bf16 v[72:75], v[180:183], v[204:207], v[72:75]
	v_mfma_f32_16x16x32_bf16 v[68:71], v[172:175], v[212:215], v[68:71]
	v_mfma_f32_16x16x32_bf16 v[64:67], v[180:183], v[212:215], v[64:67]
	s_setprio 0
	s_barrier
	s_add_i32 s34, s63, s20
	v_lshl_add_u64 v[216:217], s[56:57], 0, v[130:131]
	s_mov_b32 m0, s34
	ds_read_b128 v[184:187], v151 offset:16384
	ds_read_b128 v[188:191], v151 offset:17408
	ds_read_b128 v[192:195], v151 offset:18432
	ds_read_b128 v[196:199], v151 offset:19456
	ds_read_b128 v[200:203], v151 offset:20480
	ds_read_b128 v[204:207], v151 offset:21504
	ds_read_b128 v[208:211], v151 offset:22528
	ds_read_b128 v[212:215], v151 offset:23552
	global_load_lds_dwordx4 v[216:217], off
	s_add_i32 m0, s34, 0x2000
	s_add_u32 s34, s56, 0x40000
	v_lshl_add_u64 v[218:219], s[56:57], 0, v[134:135]
	s_addc_u32 s35, s57, 0
	s_add_i32 s54, s64, s20
	global_load_lds_dwordx4 v[218:219], off
	s_mov_b32 m0, s54
	v_lshl_add_u64 v[222:223], s[58:59], 0, v[132:133]
	global_load_lds_dwordx4 v130, s[34:35]
	s_add_i32 m0, s54, 0x2000
	s_nop 0
	global_load_lds_dwordx4 v134, s[34:35]
	v_lshl_add_u64 v[220:221], s[58:59], 0, v[128:129]
	s_mov_b32 m0, s21
	s_nop 0
	global_load_lds_dwordx4 v[220:221], off
	s_mov_b32 m0, s29
	s_nop 0
	global_load_lds_dwordx4 v[222:223], off
	s_waitcnt vmcnt(8)
	s_waitcnt lgkmcnt(0)
	s_barrier
; #define PG8_STAGE(bufoff, gbase, voff) do { _Pragma("unroll") for (int _i = 0; _i < 2; ++_i) \
;         __builtin_amdgcn_global_load_lds((const unsigned*)((const char*)(gbase) + (voff)[_i]), (LAS unsigned*)(lds + (bufoff) + ldsw + _i * 8192), 16, 0, 0); } while (0)
; #define PG8_LDA(dst, b, h) do { _Pragma("unroll") for (int m = 0; m < 4; ++m) _Pragma("unroll") for (int k = 0; k < 2; ++k) dst[m][k] = *(const LAS bf16x8*)(lds + PG8_SA(b, h) + aoff + m * 2048 + k * 1024); } while (0)
; #define PG8_LDB(dst, b, h) do { _Pragma("unroll") for (int n = 0; n < 2; ++n) _Pragma("unroll") for (int k = 0; k < 2; ++k) dst[n][k] = *(const LAS bf16x8*)(lds + PG8_SB(b, h) + boff + n * 2048 + k * 1024); } while (0)
; #define PG8_MMA(ai, bj, At, Bt) do { __builtin_amdgcn_s_setprio(1); _Pragma("unroll") for (int m = 0; m < 4; ++m) _Pragma("unroll") for (int n = 0; n < 2; ++n) _Pragma("unroll") for (int k = 0; k < 2; ++k) \
;         acc[ai][bj][m][n] = __builtin_amdgcn_mfma_f32_16x16x32_bf16(Bt[n][k], At[m][k], acc[ai][bj][m][n], 0, 0, 0); __builtin_amdgcn_s_setprio(0); } while (0)
; #define PG8_WAIT_V(n) asm volatile("s_waitcnt vmcnt(" #n ")" ::: "memory")
; #define PG8_WAIT_L(n) asm volatile("s_waitcnt lgkmcnt(" #n ")" ::: "memory")
; #define PG8_BAR __builtin_amdgcn_s_barrier()
; #define PG8_SCHED __builtin_amdgcn_sched_barrier(0)
; template <class Epi, class Sched, bool ALIGN_EPI = false, bool SP2 = false>
; __device__ __forceinline__ void gemm_phase(LAS unsigned char* lds, const Gemm g, const Sched S, const Epi E) {
;     ...
;             PG8_WAIT_V(8); PG8_WAIT_L(0); PG8_BAR; PG8_MMA(1, 0, At, B0); PG8_MMA(1, 1, At, B1); PG8_BAR; PG8_SCHED;
;             PG8_LDB(B0, 1, 0); PG8_LDB(B1, 1, 1); PG8_SCHED; PG8_LDA(At, 1, 0); PG8_STAGE(PG8_SA(0, 1), a2 + hstepA, voffA);
;             PG8_WAIT_V(8); PG8_WAIT_L(0); PG8_BAR; PG8_MMA(0, 0, At, B0); PG8_MMA(0, 1, At, B1); PG8_BAR; PG8_SCHED;
	s_setprio 1
	s_waitcnt lgkmcnt(0)
	v_mfma_f32_16x16x32_bf16 v[60:63], v[152:155], v[184:187], v[60:63]
	v_mfma_f32_16x16x32_bf16 v[56:59], v[160:163], v[184:187], v[56:59]
	v_mfma_f32_16x16x32_bf16 v[52:55], v[152:155], v[192:195], v[52:55]
	v_mfma_f32_16x16x32_bf16 v[48:51], v[160:163], v[192:195], v[48:51]
	v_mfma_f32_16x16x32_bf16 v[36:39], v[152:155], v[200:203], v[36:39]
	v_mfma_f32_16x16x32_bf16 v[32:35], v[160:163], v[200:203], v[32:35]
	v_mfma_f32_16x16x32_bf16 v[20:23], v[152:155], v[208:211], v[20:23]
	v_mfma_f32_16x16x32_bf16 v[16:19], v[160:163], v[208:211], v[16:19]
	v_mfma_f32_16x16x32_bf16 v[60:63], v[156:159], v[188:191], v[60:63]
	v_mfma_f32_16x16x32_bf16 v[56:59], v[164:167], v[188:191], v[56:59]
	v_mfma_f32_16x16x32_bf16 v[52:55], v[156:159], v[196:199], v[52:55]
	v_mfma_f32_16x16x32_bf16 v[48:51], v[164:167], v[196:199], v[48:51]
	v_mfma_f32_16x16x32_bf16 v[36:39], v[156:159], v[204:207], v[36:39]
	v_mfma_f32_16x16x32_bf16 v[32:35], v[164:167], v[204:207], v[32:35]
	v_mfma_f32_16x16x32_bf16 v[20:23], v[156:159], v[212:215], v[20:23]
	v_mfma_f32_16x16x32_bf16 v[16:19], v[164:167], v[212:215], v[16:19]
	s_setprio 0
	s_setprio 1
	v_mfma_f32_16x16x32_bf16 v[44:47], v[168:171], v[184:187], v[44:47]
	v_mfma_f32_16x16x32_bf16 v[40:43], v[176:179], v[184:187], v[40:43]
	v_mfma_f32_16x16x32_bf16 v[28:31], v[168:171], v[192:195], v[28:31]
	v_mfma_f32_16x16x32_bf16 v[24:27], v[176:179], v[192:195], v[24:27]
	v_mfma_f32_16x16x32_bf16 v[12:15], v[168:171], v[200:203], v[12:15]
	v_mfma_f32_16x16x32_bf16 v[8:11], v[176:179], v[200:203], v[8:11]
	v_mfma_f32_16x16x32_bf16 v[4:7], v[168:171], v[208:211], v[4:7]
	v_mfma_f32_16x16x32_bf16 v[0:3], v[176:179], v[208:211], v[0:3]
	v_mfma_f32_16x16x32_bf16 v[44:47], v[172:175], v[188:191], v[44:47]
	v_mfma_f32_16x16x32_bf16 v[40:43], v[180:183], v[188:191], v[40:43]
	v_mfma_f32_16x16x32_bf16 v[28:31], v[172:175], v[196:199], v[28:31]
	v_mfma_f32_16x16x32_bf16 v[24:27], v[180:183], v[196:199], v[24:27]
	v_mfma_f32_16x16x32_bf16 v[12:15], v[172:175], v[204:207], v[12:15]
	v_mfma_f32_16x16x32_bf16 v[8:11], v[180:183], v[204:207], v[8:11]
	v_mfma_f32_16x16x32_bf16 v[4:7], v[172:175], v[212:215], v[4:7]
	v_mfma_f32_16x16x32_bf16 v[0:3], v[180:183], v[212:215], v[0:3]
	s_setprio 0
	s_barrier
	s_add_i32 s54, 0, 0x18000
	v_add_u32_e32 v136, s54, v147
	s_add_i32 s55, 0, 0x1c000
	ds_read_b128 v[152:155], v136
	ds_read_b128 v[156:159], v136 offset:1024
	ds_read_b128 v[160:163], v136 offset:2048
	ds_read_b128 v[164:167], v136 offset:3072
	v_add_u32_e32 v136, s55, v147
	ds_read_b128 v[168:171], v136
	ds_read_b128 v[172:175], v136 offset:1024
	ds_read_b128 v[176:179], v136 offset:2048
	ds_read_b128 v[180:183], v136 offset:3072
	s_add_u32 s34, s58, 0x130000
	s_addc_u32 s35, s59, 0
	s_mov_b32 m0, s30
	ds_read_b128 v[184:187], v151 offset:32768
	ds_read_b128 v[188:191], v151 offset:33792
	ds_read_b128 v[192:195], v151 offset:34816
	ds_read_b128 v[196:199], v151 offset:35840
	ds_read_b128 v[200:203], v151 offset:36864
	ds_read_b128 v[204:207], v151 offset:37888
	ds_read_b128 v[208:211], v151 offset:38912
	ds_read_b128 v[212:215], v151 offset:39936
	global_load_lds_dwordx4 v128, s[34:35]
	s_mov_b32 m0, s31
	s_nop 0
	global_load_lds_dwordx4 v132, s[34:35]
	s_waitcnt vmcnt(8)
	s_waitcnt lgkmcnt(0)
	s_barrier
	s_setprio 1
	s_waitcnt lgkmcnt(0)
	v_mfma_f32_16x16x32_bf16 v[124:127], v[152:155], v[184:187], v[124:127]
	v_mfma_f32_16x16x32_bf16 v[120:123], v[160:163], v[184:187], v[120:123]
	v_mfma_f32_16x16x32_bf16 v[116:119], v[152:155], v[192:195], v[116:119]
	v_mfma_f32_16x16x32_bf16 v[112:115], v[160:163], v[192:195], v[112:115]
	v_mfma_f32_16x16x32_bf16 v[100:103], v[152:155], v[200:203], v[100:103]
	v_mfma_f32_16x16x32_bf16 v[96:99], v[160:163], v[200:203], v[96:99]
	v_mfma_f32_16x16x32_bf16 v[84:87], v[152:155], v[208:211], v[84:87]
	v_mfma_f32_16x16x32_bf16 v[80:83], v[160:163], v[208:211], v[80:83]
	v_mfma_f32_16x16x32_bf16 v[124:127], v[156:159], v[188:191], v[124:127]
	v_mfma_f32_16x16x32_bf16 v[120:123], v[164:167], v[188:191], v[120:123]
	v_mfma_f32_16x16x32_bf16 v[116:119], v[156:159], v[196:199], v[116:119]
	v_mfma_f32_16x16x32_bf16 v[112:115], v[164:167], v[196:199], v[112:115]
	v_mfma_f32_16x16x32_bf16 v[100:103], v[156:159], v[204:207], v[100:103]
	v_mfma_f32_16x16x32_bf16 v[96:99], v[164:167], v[204:207], v[96:99]
	v_mfma_f32_16x16x32_bf16 v[84:87], v[156:159], v[212:215], v[84:87]
	v_mfma_f32_16x16x32_bf16 v[80:83], v[164:167], v[212:215], v[80:83]
	s_setprio 0
	s_setprio 1
	v_mfma_f32_16x16x32_bf16 v[108:111], v[168:171], v[184:187], v[108:111]
	v_mfma_f32_16x16x32_bf16 v[104:107], v[176:179], v[184:187], v[104:107]
	v_mfma_f32_16x16x32_bf16 v[92:95], v[168:171], v[192:195], v[92:95]
	v_mfma_f32_16x16x32_bf16 v[88:91], v[176:179], v[192:195], v[88:91]
	v_mfma_f32_16x16x32_bf16 v[76:79], v[168:171], v[200:203], v[76:79]
	v_mfma_f32_16x16x32_bf16 v[72:75], v[176:179], v[200:203], v[72:75]
	v_mfma_f32_16x16x32_bf16 v[68:71], v[168:171], v[208:211], v[68:71]
	v_mfma_f32_16x16x32_bf16 v[64:67], v[176:179], v[208:211], v[64:67]
	v_mfma_f32_16x16x32_bf16 v[108:111], v[172:175], v[188:191], v[108:111]
	v_mfma_f32_16x16x32_bf16 v[104:107], v[180:183], v[188:191], v[104:107]
	v_mfma_f32_16x16x32_bf16 v[92:95], v[172:175], v[196:199], v[92:95]
	v_mfma_f32_16x16x32_bf16 v[88:91], v[180:183], v[196:199], v[88:91]
	v_mfma_f32_16x16x32_bf16 v[76:79], v[172:175], v[204:207], v[76:79]
	v_mfma_f32_16x16x32_bf16 v[72:75], v[180:183], v[204:207], v[72:75]
	v_mfma_f32_16x16x32_bf16 v[68:71], v[172:175], v[212:215], v[68:71]
	v_mfma_f32_16x16x32_bf16 v[64:67], v[180:183], v[212:215], v[64:67]
	s_setprio 0
	s_barrier
; #define PG8_STAGE(bufoff, gbase, voff) do { _Pragma("unroll") for (int _i = 0; _i < 2; ++_i) \
;         __builtin_amdgcn_global_load_lds((const unsigned*)((const char*)(gbase) + (voff)[_i]), (LAS unsigned*)(lds + (bufoff) + ldsw + _i * 8192), 16, 0, 0); } while (0)
; #define PG8_LDA(dst, b, h) do { _Pragma("unroll") for (int m = 0; m < 4; ++m) _Pragma("unroll") for (int k = 0; k < 2; ++k) dst[m][k] = *(const LAS bf16x8*)(lds + PG8_SA(b, h) + aoff + m * 2048 + k * 1024); } while (0)
; #define PG8_MMA(ai, bj, At, Bt) do { __builtin_amdgcn_s_setprio(1); _Pragma("unroll") for (int m = 0; m < 4; ++m) _Pragma("unroll") for (int n = 0; n < 2; ++n) _Pragma("unroll") for (int k = 0; k < 2; ++k) \
;         acc[ai][bj][m][n] = __builtin_amdgcn_mfma_f32_16x16x32_bf16(Bt[n][k], At[m][k], acc[ai][bj][m][n], 0, 0, 0); __builtin_amdgcn_s_setprio(0); } while (0)
; #define PG8_WAIT_V(n) asm volatile("s_waitcnt vmcnt(" #n ")" ::: "memory")
; #define PG8_WAIT_L(n) asm volatile("s_waitcnt lgkmcnt(" #n ")" ::: "memory")
; #define PG8_BAR __builtin_amdgcn_s_barrier()
; #define PG8_SCHED __builtin_amdgcn_sched_barrier(0)
; template <class Epi, class Sched, bool ALIGN_EPI = false, bool SP2 = false>
; __device__ __forceinline__ void gemm_phase(LAS unsigned char* lds, const Gemm g, const Sched S, const Epi E) {
;     ...
;             PG8_LDA(At, 1, 1); PG8_STAGE(PG8_SB(1, 0), b3, voffB); PG8_STAGE(PG8_SB(1, 1), b3 + hstepB, voffB); PG8_STAGE(PG8_SA(1, 0), a3, voffA);
;             PG8_WAIT_V(8); PG8_WAIT_L(0); PG8_BAR; PG8_MMA(1, 0, At, B0); PG8_MMA(1, 1, At, B1); PG8_BAR; PG8_SCHED;
	s_add_i32 s34, s54, s20
	v_lshl_add_u64 v[216:217], v[216:217], 0, s[14:15]
	s_mov_b32 m0, s34
	ds_read_b128 v[184:187], v151 offset:49152
	ds_read_b128 v[188:191], v151 offset:50176
	ds_read_b128 v[192:195], v151 offset:51200
	ds_read_b128 v[196:199], v151 offset:52224
	ds_read_b128 v[200:203], v151 offset:53248
	ds_read_b128 v[204:207], v151 offset:54272
	ds_read_b128 v[208:211], v151 offset:55296
	ds_read_b128 v[212:215], v151 offset:56320
	global_load_lds_dwordx4 v[216:217], off
	s_add_i32 m0, s34, 0x2000
	s_add_u32 s34, s56, 0x40080
	v_lshl_add_u64 v[216:217], v[218:219], 0, s[14:15]
	s_addc_u32 s35, s57, 0
	s_add_i32 s54, s55, s20
	global_load_lds_dwordx4 v[216:217], off
	s_mov_b32 m0, s54
	s_nop 0
	global_load_lds_dwordx4 v130, s[34:35]
	s_add_i32 m0, s54, 0x2000
	s_nop 0
	global_load_lds_dwordx4 v134, s[34:35]
	v_lshl_add_u64 v[216:217], v[220:221], 0, s[14:15]
	s_mov_b32 m0, s45
	s_nop 0
	global_load_lds_dwordx4 v[216:217], off
	v_lshl_add_u64 v[216:217], v[222:223], 0, s[14:15]
	s_mov_b32 m0, s60
	s_nop 0
	global_load_lds_dwordx4 v[216:217], off
	s_waitcnt vmcnt(8)
	s_waitcnt lgkmcnt(0)
	s_barrier
	s_setprio 1
	s_waitcnt lgkmcnt(0)
	v_mfma_f32_16x16x32_bf16 v[60:63], v[152:155], v[184:187], v[60:63]
	v_mfma_f32_16x16x32_bf16 v[56:59], v[160:163], v[184:187], v[56:59]
	v_mfma_f32_16x16x32_bf16 v[52:55], v[152:155], v[192:195], v[52:55]
	v_mfma_f32_16x16x32_bf16 v[48:51], v[160:163], v[192:195], v[48:51]
	v_mfma_f32_16x16x32_bf16 v[36:39], v[152:155], v[200:203], v[36:39]
	v_mfma_f32_16x16x32_bf16 v[32:35], v[160:163], v[200:203], v[32:35]
	v_mfma_f32_16x16x32_bf16 v[20:23], v[152:155], v[208:211], v[20:23]
	v_mfma_f32_16x16x32_bf16 v[16:19], v[160:163], v[208:211], v[16:19]
	v_mfma_f32_16x16x32_bf16 v[60:63], v[156:159], v[188:191], v[60:63]
	v_mfma_f32_16x16x32_bf16 v[56:59], v[164:167], v[188:191], v[56:59]
	v_mfma_f32_16x16x32_bf16 v[52:55], v[156:159], v[196:199], v[52:55]
	v_mfma_f32_16x16x32_bf16 v[48:51], v[164:167], v[196:199], v[48:51]
	v_mfma_f32_16x16x32_bf16 v[36:39], v[156:159], v[204:207], v[36:39]
	v_mfma_f32_16x16x32_bf16 v[32:35], v[164:167], v[204:207], v[32:35]
	v_mfma_f32_16x16x32_bf16 v[20:23], v[156:159], v[212:215], v[20:23]
	v_mfma_f32_16x16x32_bf16 v[16:19], v[164:167], v[212:215], v[16:19]
	s_setprio 0
	s_setprio 1
	v_mfma_f32_16x16x32_bf16 v[44:47], v[168:171], v[184:187], v[44:47]
	v_mfma_f32_16x16x32_bf16 v[40:43], v[176:179], v[184:187], v[40:43]
	v_mfma_f32_16x16x32_bf16 v[28:31], v[168:171], v[192:195], v[28:31]
	v_mfma_f32_16x16x32_bf16 v[24:27], v[176:179], v[192:195], v[24:27]
	v_mfma_f32_16x16x32_bf16 v[12:15], v[168:171], v[200:203], v[12:15]
	v_mfma_f32_16x16x32_bf16 v[8:11], v[176:179], v[200:203], v[8:11]
	v_mfma_f32_16x16x32_bf16 v[4:7], v[168:171], v[208:211], v[4:7]
	v_mfma_f32_16x16x32_bf16 v[0:3], v[176:179], v[208:211], v[0:3]
	v_mfma_f32_16x16x32_bf16 v[44:47], v[172:175], v[188:191], v[44:47]
	v_mfma_f32_16x16x32_bf16 v[40:43], v[180:183], v[188:191], v[40:43]
	v_mfma_f32_16x16x32_bf16 v[28:31], v[172:175], v[196:199], v[28:31]
	v_mfma_f32_16x16x32_bf16 v[24:27], v[180:183], v[196:199], v[24:27]
	v_mfma_f32_16x16x32_bf16 v[12:15], v[172:175], v[204:207], v[12:15]
	v_mfma_f32_16x16x32_bf16 v[8:11], v[180:183], v[204:207], v[8:11]
	v_mfma_f32_16x16x32_bf16 v[4:7], v[172:175], v[212:215], v[4:7]
	v_mfma_f32_16x16x32_bf16 v[0:3], v[180:183], v[212:215], v[0:3]
	s_setprio 0
	s_barrier
	s_add_i32 s71, s71, 2
	s_add_u32 s69, s69, 0x100
	s_addc_u32 s70, s70, 0
	s_cmp_gt_u32 s71, 13
	s_mov_b64 s[54:55], s[10:11]
	s_cbranch_scc0 .LBB0_1612
	s_and_b64 vcc, exec, s[16:17]
	s_cbranch_vccz .LBB0_1615
	s_barrier

; #define PG8_STAGE(bufoff, gbase, voff) do { _Pragma("unroll") for (int _i = 0; _i < 2; ++_i) \
;         __builtin_amdgcn_global_load_lds((const unsigned*)((const char*)(gbase) + (voff)[_i]), (LAS unsigned*)(lds + (bufoff) + ldsw + _i * 8192), 16, 0, 0); } while (0)
; #define PG8_LDA(dst, b, h) do { _Pragma("unroll") for (int m = 0; m < 4; ++m) _Pragma("unroll") for (int k = 0; k < 2; ++k) dst[m][k] = *(const LAS bf16x8*)(lds + PG8_SA(b, h) + aoff + m * 2048 + k * 1024); } while (0)
; #define PG8_LDB(dst, b, h) do { _Pragma("unroll") for (int n = 0; n < 2; ++n) _Pragma("unroll") for (int k = 0; k < 2; ++k) dst[n][k] = *(const LAS bf16x8*)(lds + PG8_SB(b, h) + boff + n * 2048 + k * 1024); } while (0)
; #define PG8_MMA(ai, bj, At, Bt) do { __builtin_amdgcn_s_setprio(1); _Pragma("unroll") for (int m = 0; m < 4; ++m) _Pragma("unroll") for (int n = 0; n < 2; ++n) _Pragma("unroll") for (int k = 0; k < 2; ++k) \
;         acc[ai][bj][m][n] = __builtin_amdgcn_mfma_f32_16x16x32_bf16(Bt[n][k], At[m][k], acc[ai][bj][m][n], 0, 0, 0); __builtin_amdgcn_s_setprio(0); } while (0)
; #define PG8_WAIT_V(n) asm volatile("s_waitcnt vmcnt(" #n ")" ::: "memory")
; #define PG8_WAIT_L(n) asm volatile("s_waitcnt lgkmcnt(" #n ")" ::: "memory")
; #define PG8_BAR __builtin_amdgcn_s_barrier()
; template <class Epi, class Sched, bool ALIGN_EPI = false, bool SP2 = false>
; __device__ __forceinline__ void gemm_phase(LAS unsigned char* lds, const Gemm g, const Sched S, const Epi E) {
;     ...
;             const bool last = (t == nt - 2);
;             const char* a1 = cA + (size_t)(t + 1) * kstep;
;             const char* a2 = last ? nA : cA + (size_t)(t + 2) * kstep; const char* b2 = last ? nB : cB + (size_t)(t + 2) * kstep;
;             const char* a3 = a2 + kstep; const char* b3 = b2 + kstep;
;             if (last && has_next) S.a_ready(nxt);
;             if constexpr (SP2) {
;             PG8_LDB(B0, 0, 0); PG8_LDB(B1, 0, 1); PG8_SCHED; PG8_LDA(At, 0, 0); PG8_STAGE(PG8_SA(1, 1), a1 + hstepA, voffA);
;             PG8_WAIT_V(8); PG8_WAIT_L(0); PG8_BAR; PG8_MMA(0, 0, At, B0); PG8_MMA(0, 1, At, B1); PG8_BAR; PG8_SCHED;
;             PG8_LDA(At, 0, 1); PG8_STAGE(PG8_SB(0, 0), b2, voffB); PG8_STAGE(PG8_SB(0, 1), b2 + hstepB, voffB); PG8_STAGE(PG8_SA(0, 0), a2, voffA);
;             PG8_WAIT_V(8); PG8_WAIT_L(0); PG8_BAR; PG8_MMA(1, 0, At, B0); PG8_MMA(1, 1, At, B1); PG8_BAR; PG8_SCHED;
.LBB0_1688:
	ds_read_b128 v[128:131], v167
	ds_read_b128 v[132:135], v167 offset:1024
	ds_read_b128 v[152:155], v167 offset:2048
	ds_read_b128 v[156:159], v167 offset:3072
	ds_read_b128 v[160:163], v168
	ds_read_b128 v[172:175], v168 offset:1024
	ds_read_b128 v[176:179], v168 offset:2048
	ds_read_b128 v[180:183], v168 offset:3072
	s_add_u32 s34, s52, 0xfff80080
	s_addc_u32 s35, s53, -1
	s_cmp_eq_u32 s66, 12
	s_cselect_b32 s57, s19, s35
	s_cselect_b32 s56, s62, s34
	s_cselect_b32 s55, s17, s65
	s_cselect_b32 s54, s63, s64
	s_add_i32 m0, s5, 0xc000
	ds_read_b128 v[184:187], v169
	ds_read_b128 v[188:191], v169 offset:1024
	ds_read_b128 v[192:195], v169 offset:2048
	ds_read_b128 v[196:199], v169 offset:3072
	ds_read_b128 v[200:203], v169 offset:4096
	ds_read_b128 v[204:207], v169 offset:5120
	ds_read_b128 v[208:211], v169 offset:6144
	ds_read_b128 v[212:215], v169 offset:7168
	global_load_lds_dwordx4 v144, s[52:53]
	s_add_i32 m0, s5, 0xe000
	s_nop 0
	global_load_lds_dwordx4 v146, s[52:53]
	s_waitcnt vmcnt(8)
	s_waitcnt lgkmcnt(0)
	s_barrier
	s_setprio 1
	s_waitcnt lgkmcnt(0)
	v_mfma_f32_16x16x32_bf16 v[124:127], v[128:131], v[184:187], v[124:127]
	v_mfma_f32_16x16x32_bf16 v[120:123], v[152:155], v[184:187], v[120:123]
	v_mfma_f32_16x16x32_bf16 v[108:111], v[128:131], v[192:195], v[108:111]
	v_mfma_f32_16x16x32_bf16 v[104:107], v[152:155], v[192:195], v[104:107]
	v_mfma_f32_16x16x32_bf16 v[92:95], v[128:131], v[200:203], v[92:95]
	v_mfma_f32_16x16x32_bf16 v[88:91], v[152:155], v[200:203], v[88:91]
	v_mfma_f32_16x16x32_bf16 v[76:79], v[128:131], v[208:211], v[76:79]
	v_mfma_f32_16x16x32_bf16 v[72:75], v[152:155], v[208:211], v[72:75]
	v_mfma_f32_16x16x32_bf16 v[124:127], v[132:135], v[188:191], v[124:127]
	v_mfma_f32_16x16x32_bf16 v[120:123], v[156:159], v[188:191], v[120:123]
	v_mfma_f32_16x16x32_bf16 v[108:111], v[132:135], v[196:199], v[108:111]
	v_mfma_f32_16x16x32_bf16 v[104:107], v[156:159], v[196:199], v[104:107]
	v_mfma_f32_16x16x32_bf16 v[92:95], v[132:135], v[204:207], v[92:95]
	v_mfma_f32_16x16x32_bf16 v[88:91], v[156:159], v[204:207], v[88:91]
	v_mfma_f32_16x16x32_bf16 v[76:79], v[132:135], v[212:215], v[76:79]
	v_mfma_f32_16x16x32_bf16 v[72:75], v[156:159], v[212:215], v[72:75]
	s_setprio 0
	s_setprio 1
	v_mfma_f32_16x16x32_bf16 v[116:119], v[160:163], v[184:187], v[116:119]
	v_mfma_f32_16x16x32_bf16 v[112:115], v[176:179], v[184:187], v[112:115]
	v_mfma_f32_16x16x32_bf16 v[100:103], v[160:163], v[192:195], v[100:103]
	v_mfma_f32_16x16x32_bf16 v[96:99], v[176:179], v[192:195], v[96:99]
	v_mfma_f32_16x16x32_bf16 v[84:87], v[160:163], v[200:203], v[84:87]
	v_mfma_f32_16x16x32_bf16 v[80:83], v[176:179], v[200:203], v[80:83]
	v_mfma_f32_16x16x32_bf16 v[68:71], v[160:163], v[208:211], v[68:71]
	v_mfma_f32_16x16x32_bf16 v[64:67], v[176:179], v[208:211], v[64:67]
	v_mfma_f32_16x16x32_bf16 v[116:119], v[172:175], v[188:191], v[116:119]
	v_mfma_f32_16x16x32_bf16 v[112:115], v[180:183], v[188:191], v[112:115]
	v_mfma_f32_16x16x32_bf16 v[100:103], v[172:175], v[196:199], v[100:103]
	v_mfma_f32_16x16x32_bf16 v[96:99], v[180:183], v[196:199], v[96:99]
	v_mfma_f32_16x16x32_bf16 v[84:87], v[172:175], v[204:207], v[84:87]
	v_mfma_f32_16x16x32_bf16 v[80:83], v[180:183], v[204:207], v[80:83]
	v_mfma_f32_16x16x32_bf16 v[68:71], v[172:175], v[212:215], v[68:71]
	v_mfma_f32_16x16x32_bf16 v[64:67], v[180:183], v[212:215], v[64:67]
	s_setprio 0
	s_barrier
	s_add_i32 s34, s58, s4
	v_lshl_add_u64 v[216:217], s[54:55], 0, v[138:139]
	s_mov_b32 m0, s34
	ds_read_b128 v[184:187], v169 offset:16384
	ds_read_b128 v[188:191], v169 offset:17408
	ds_read_b128 v[192:195], v169 offset:18432
	ds_read_b128 v[196:199], v169 offset:19456
	ds_read_b128 v[200:203], v169 offset:20480
	ds_read_b128 v[204:207], v169 offset:21504
	ds_read_b128 v[208:211], v169 offset:22528
	ds_read_b128 v[212:215], v169 offset:23552
	global_load_lds_dwordx4 v[216:217], off
	s_add_i32 m0, s34, 0x2000
	s_add_u32 s34, s54, 0x40000
	v_lshl_add_u64 v[218:219], s[54:55], 0, v[142:143]
	s_addc_u32 s35, s55, 0
	s_add_i32 s67, s59, s4
	global_load_lds_dwordx4 v[218:219], off
	s_mov_b32 m0, s67
	v_lshl_add_u64 v[222:223], s[56:57], 0, v[140:141]
	global_load_lds_dwordx4 v138, s[34:35]
	s_add_i32 m0, s67, 0x2000
	s_nop 0
	global_load_lds_dwordx4 v142, s[34:35]
	v_lshl_add_u64 v[220:221], s[56:57], 0, v[136:137]
	s_mov_b32 m0, s5
	s_nop 0
	global_load_lds_dwordx4 v[220:221], off
	s_mov_b32 m0, s20
	s_nop 0
	global_load_lds_dwordx4 v[222:223], off
	s_waitcnt vmcnt(8)
	s_waitcnt lgkmcnt(0)
	s_barrier
; #define PG8_STAGE(bufoff, gbase, voff) do { _Pragma("unroll") for (int _i = 0; _i < 2; ++_i) \
;         __builtin_amdgcn_global_load_lds((const unsigned*)((const char*)(gbase) + (voff)[_i]), (LAS unsigned*)(lds + (bufoff) + ldsw + _i * 8192), 16, 0, 0); } while (0)
; #define PG8_LDA(dst, b, h) do { _Pragma("unroll") for (int m = 0; m < 4; ++m) _Pragma("unroll") for (int k = 0; k < 2; ++k) dst[m][k] = *(const LAS bf16x8*)(lds + PG8_SA(b, h) + aoff + m * 2048 + k * 1024); } while (0)
; #define PG8_LDB(dst, b, h) do { _Pragma("unroll") for (int n = 0; n < 2; ++n) _Pragma("unroll") for (int k = 0; k < 2; ++k) dst[n][k] = *(const LAS bf16x8*)(lds + PG8_SB(b, h) + boff + n * 2048 + k * 1024); } while (0)
; #define PG8_MMA(ai, bj, At, Bt) do { __builtin_amdgcn_s_setprio(1); _Pragma("unroll") for (int m = 0; m < 4; ++m) _Pragma("unroll") for (int n = 0; n < 2; ++n) _Pragma("unroll") for (int k = 0; k < 2; ++k) \
;         acc[ai][bj][m][n] = __builtin_amdgcn_mfma_f32_16x16x32_bf16(Bt[n][k], At[m][k], acc[ai][bj][m][n], 0, 0, 0); __builtin_amdgcn_s_setprio(0); } while (0)
; #define PG8_WAIT_V(n) asm volatile("s_waitcnt vmcnt(" #n ")" ::: "memory")
; #define PG8_WAIT_L(n) asm volatile("s_waitcnt lgkmcnt(" #n ")" ::: "memory")
; #define PG8_BAR __builtin_amdgcn_s_barrier()
; #define PG8_SCHED __builtin_amdgcn_sched_barrier(0)
; template <class Epi, class Sched, bool ALIGN_EPI = false, bool SP2 = false>
; __device__ __forceinline__ void gemm_phase(LAS unsigned char* lds, const Gemm g, const Sched S, const Epi E) {
;     ...
;             PG8_WAIT_V(8); PG8_WAIT_L(0); PG8_BAR; PG8_MMA(1, 0, At, B0); PG8_MMA(1, 1, At, B1); PG8_BAR; PG8_SCHED;
;             PG8_LDB(B0, 1, 0); PG8_LDB(B1, 1, 1); PG8_SCHED; PG8_LDA(At, 1, 0); PG8_STAGE(PG8_SA(0, 1), a2 + hstepA, voffA);
;             PG8_WAIT_V(8); PG8_WAIT_L(0); PG8_BAR; PG8_MMA(0, 0, At, B0); PG8_MMA(0, 1, At, B1); PG8_BAR; PG8_SCHED;
	s_setprio 1
	s_waitcnt lgkmcnt(0)
	v_mfma_f32_16x16x32_bf16 v[60:63], v[128:131], v[184:187], v[60:63]
	v_mfma_f32_16x16x32_bf16 v[56:59], v[152:155], v[184:187], v[56:59]
	v_mfma_f32_16x16x32_bf16 v[44:47], v[128:131], v[192:195], v[44:47]
	v_mfma_f32_16x16x32_bf16 v[40:43], v[152:155], v[192:195], v[40:43]
	v_mfma_f32_16x16x32_bf16 v[28:31], v[128:131], v[200:203], v[28:31]
	v_mfma_f32_16x16x32_bf16 v[24:27], v[152:155], v[200:203], v[24:27]
	v_mfma_f32_16x16x32_bf16 v[12:15], v[128:131], v[208:211], v[12:15]
	v_mfma_f32_16x16x32_bf16 v[8:11], v[152:155], v[208:211], v[8:11]
	v_mfma_f32_16x16x32_bf16 v[60:63], v[132:135], v[188:191], v[60:63]
	v_mfma_f32_16x16x32_bf16 v[56:59], v[156:159], v[188:191], v[56:59]
	v_mfma_f32_16x16x32_bf16 v[44:47], v[132:135], v[196:199], v[44:47]
	v_mfma_f32_16x16x32_bf16 v[40:43], v[156:159], v[196:199], v[40:43]
	v_mfma_f32_16x16x32_bf16 v[28:31], v[132:135], v[204:207], v[28:31]
	v_mfma_f32_16x16x32_bf16 v[24:27], v[156:159], v[204:207], v[24:27]
	v_mfma_f32_16x16x32_bf16 v[12:15], v[132:135], v[212:215], v[12:15]
	v_mfma_f32_16x16x32_bf16 v[8:11], v[156:159], v[212:215], v[8:11]
	s_setprio 0
	s_setprio 1
	v_mfma_f32_16x16x32_bf16 v[52:55], v[160:163], v[184:187], v[52:55]
	v_mfma_f32_16x16x32_bf16 v[48:51], v[176:179], v[184:187], v[48:51]
	v_mfma_f32_16x16x32_bf16 v[36:39], v[160:163], v[192:195], v[36:39]
	v_mfma_f32_16x16x32_bf16 v[32:35], v[176:179], v[192:195], v[32:35]
	v_mfma_f32_16x16x32_bf16 v[20:23], v[160:163], v[200:203], v[20:23]
	v_mfma_f32_16x16x32_bf16 v[16:19], v[176:179], v[200:203], v[16:19]
	v_mfma_f32_16x16x32_bf16 v[4:7], v[160:163], v[208:211], v[4:7]
	v_mfma_f32_16x16x32_bf16 v[0:3], v[176:179], v[208:211], v[0:3]
	v_mfma_f32_16x16x32_bf16 v[52:55], v[172:175], v[188:191], v[52:55]
	v_mfma_f32_16x16x32_bf16 v[48:51], v[180:183], v[188:191], v[48:51]
	v_mfma_f32_16x16x32_bf16 v[36:39], v[172:175], v[196:199], v[36:39]
	v_mfma_f32_16x16x32_bf16 v[32:35], v[180:183], v[196:199], v[32:35]
	v_mfma_f32_16x16x32_bf16 v[20:23], v[172:175], v[204:207], v[20:23]
	v_mfma_f32_16x16x32_bf16 v[16:19], v[180:183], v[204:207], v[16:19]
	v_mfma_f32_16x16x32_bf16 v[4:7], v[172:175], v[212:215], v[4:7]
	v_mfma_f32_16x16x32_bf16 v[0:3], v[180:183], v[212:215], v[0:3]
	s_setprio 0
	s_barrier
	s_add_i32 s67, 0, 0x18000
	s_add_i32 s68, 0, 0x1c000
	v_add_u32_e32 v156, s67, v165
	v_add_u32_e32 v171, s68, v165
	ds_read_b128 v[128:131], v156
	ds_read_b128 v[132:135], v156 offset:1024
	ds_read_b128 v[152:155], v156 offset:2048
	ds_read_b128 v[156:159], v156 offset:3072
	ds_read_b128 v[160:163], v171
	ds_read_b128 v[172:175], v171 offset:1024
	ds_read_b128 v[176:179], v171 offset:2048
	ds_read_b128 v[180:183], v171 offset:3072
	s_add_u32 s34, s56, 0x80000
	s_addc_u32 s35, s57, 0
	s_mov_b32 m0, s21
	ds_read_b128 v[184:187], v169 offset:32768
	ds_read_b128 v[188:191], v169 offset:33792
	ds_read_b128 v[192:195], v169 offset:34816
	ds_read_b128 v[196:199], v169 offset:35840
	ds_read_b128 v[200:203], v169 offset:36864
	ds_read_b128 v[204:207], v169 offset:37888
	ds_read_b128 v[208:211], v169 offset:38912
	ds_read_b128 v[212:215], v169 offset:39936
	global_load_lds_dwordx4 v136, s[34:35]
	s_mov_b32 m0, s29
	s_nop 0
	global_load_lds_dwordx4 v140, s[34:35]
	s_waitcnt vmcnt(8)
	s_waitcnt lgkmcnt(0)
	s_barrier
	s_setprio 1
	s_waitcnt lgkmcnt(0)
	v_mfma_f32_16x16x32_bf16 v[124:127], v[128:131], v[184:187], v[124:127]
	v_mfma_f32_16x16x32_bf16 v[120:123], v[152:155], v[184:187], v[120:123]
	v_mfma_f32_16x16x32_bf16 v[108:111], v[128:131], v[192:195], v[108:111]
	v_mfma_f32_16x16x32_bf16 v[104:107], v[152:155], v[192:195], v[104:107]
	v_mfma_f32_16x16x32_bf16 v[92:95], v[128:131], v[200:203], v[92:95]
	v_mfma_f32_16x16x32_bf16 v[88:91], v[152:155], v[200:203], v[88:91]
	v_mfma_f32_16x16x32_bf16 v[76:79], v[128:131], v[208:211], v[76:79]
	v_mfma_f32_16x16x32_bf16 v[72:75], v[152:155], v[208:211], v[72:75]
	v_mfma_f32_16x16x32_bf16 v[124:127], v[132:135], v[188:191], v[124:127]
	v_mfma_f32_16x16x32_bf16 v[120:123], v[156:159], v[188:191], v[120:123]
	v_mfma_f32_16x16x32_bf16 v[108:111], v[132:135], v[196:199], v[108:111]
	v_mfma_f32_16x16x32_bf16 v[104:107], v[156:159], v[196:199], v[104:107]
	v_mfma_f32_16x16x32_bf16 v[92:95], v[132:135], v[204:207], v[92:95]
	v_mfma_f32_16x16x32_bf16 v[88:91], v[156:159], v[204:207], v[88:91]
	v_mfma_f32_16x16x32_bf16 v[76:79], v[132:135], v[212:215], v[76:79]
	v_mfma_f32_16x16x32_bf16 v[72:75], v[156:159], v[212:215], v[72:75]
	s_setprio 0
	s_setprio 1
	v_mfma_f32_16x16x32_bf16 v[116:119], v[160:163], v[184:187], v[116:119]
	v_mfma_f32_16x16x32_bf16 v[112:115], v[176:179], v[184:187], v[112:115]
	v_mfma_f32_16x16x32_bf16 v[100:103], v[160:163], v[192:195], v[100:103]
	v_mfma_f32_16x16x32_bf16 v[96:99], v[176:179], v[192:195], v[96:99]
	v_mfma_f32_16x16x32_bf16 v[84:87], v[160:163], v[200:203], v[84:87]
	v_mfma_f32_16x16x32_bf16 v[80:83], v[176:179], v[200:203], v[80:83]
	v_mfma_f32_16x16x32_bf16 v[68:71], v[160:163], v[208:211], v[68:71]
	v_mfma_f32_16x16x32_bf16 v[64:67], v[176:179], v[208:211], v[64:67]
	v_mfma_f32_16x16x32_bf16 v[116:119], v[172:175], v[188:191], v[116:119]
	v_mfma_f32_16x16x32_bf16 v[112:115], v[180:183], v[188:191], v[112:115]
	v_mfma_f32_16x16x32_bf16 v[100:103], v[172:175], v[196:199], v[100:103]
	v_mfma_f32_16x16x32_bf16 v[96:99], v[180:183], v[196:199], v[96:99]
	v_mfma_f32_16x16x32_bf16 v[84:87], v[172:175], v[204:207], v[84:87]
	v_mfma_f32_16x16x32_bf16 v[80:83], v[180:183], v[204:207], v[80:83]
	v_mfma_f32_16x16x32_bf16 v[68:71], v[172:175], v[212:215], v[68:71]
	v_mfma_f32_16x16x32_bf16 v[64:67], v[180:183], v[212:215], v[64:67]
	s_setprio 0
	s_barrier
; #define PG8_STAGE(bufoff, gbase, voff) do { _Pragma("unroll") for (int _i = 0; _i < 2; ++_i) \
;         __builtin_amdgcn_global_load_lds((const unsigned*)((const char*)(gbase) + (voff)[_i]), (LAS unsigned*)(lds + (bufoff) + ldsw + _i * 8192), 16, 0, 0); } while (0)
; #define PG8_LDA(dst, b, h) do { _Pragma("unroll") for (int m = 0; m < 4; ++m) _Pragma("unroll") for (int k = 0; k < 2; ++k) dst[m][k] = *(const LAS bf16x8*)(lds + PG8_SA(b, h) + aoff + m * 2048 + k * 1024); } while (0)
; #define PG8_MMA(ai, bj, At, Bt) do { __builtin_amdgcn_s_setprio(1); _Pragma("unroll") for (int m = 0; m < 4; ++m) _Pragma("unroll") for (int n = 0; n < 2; ++n) _Pragma("unroll") for (int k = 0; k < 2; ++k) \
;         acc[ai][bj][m][n] = __builtin_amdgcn_mfma_f32_16x16x32_bf16(Bt[n][k], At[m][k], acc[ai][bj][m][n], 0, 0, 0); __builtin_amdgcn_s_setprio(0); } while (0)
; #define PG8_WAIT_V(n) asm volatile("s_waitcnt vmcnt(" #n ")" ::: "memory")
; #define PG8_WAIT_L(n) asm volatile("s_waitcnt lgkmcnt(" #n ")" ::: "memory")
; #define PG8_BAR __builtin_amdgcn_s_barrier()
; #define PG8_SCHED __builtin_amdgcn_sched_barrier(0)
; template <class Epi, class Sched, bool ALIGN_EPI = false, bool SP2 = false>
; __device__ __forceinline__ void gemm_phase(LAS unsigned char* lds, const Gemm g, const Sched S, const Epi E) {
;     ...
;             PG8_LDA(At, 1, 1); PG8_STAGE(PG8_SB(1, 0), b3, voffB); PG8_STAGE(PG8_SB(1, 1), b3 + hstepB, voffB); PG8_STAGE(PG8_SA(1, 0), a3, voffA);
;             PG8_WAIT_V(8); PG8_WAIT_L(0); PG8_BAR; PG8_MMA(1, 0, At, B0); PG8_MMA(1, 1, At, B1); PG8_BAR; PG8_SCHED;
	s_add_i32 s34, s67, s4
	v_lshl_add_u64 v[216:217], v[216:217], 0, s[12:13]
	s_mov_b32 m0, s34
	ds_read_b128 v[184:187], v169 offset:49152
	ds_read_b128 v[188:191], v169 offset:50176
	ds_read_b128 v[192:195], v169 offset:51200
	ds_read_b128 v[196:199], v169 offset:52224
	ds_read_b128 v[200:203], v169 offset:53248
	ds_read_b128 v[204:207], v169 offset:54272
	ds_read_b128 v[208:211], v169 offset:55296
	ds_read_b128 v[212:215], v169 offset:56320
	global_load_lds_dwordx4 v[216:217], off
	s_add_i32 m0, s34, 0x2000
	s_add_u32 s34, s54, 0x40080
	v_lshl_add_u64 v[216:217], v[218:219], 0, s[12:13]
	s_addc_u32 s35, s55, 0
	s_add_i32 s54, s68, s4
	global_load_lds_dwordx4 v[216:217], off
	s_mov_b32 m0, s54
	s_nop 0
	global_load_lds_dwordx4 v138, s[34:35]
	s_add_i32 m0, s54, 0x2000
	s_nop 0
	global_load_lds_dwordx4 v142, s[34:35]
	v_lshl_add_u64 v[216:217], v[220:221], 0, s[12:13]
	s_mov_b32 m0, s31
	s_nop 0
	global_load_lds_dwordx4 v[216:217], off
	v_lshl_add_u64 v[216:217], v[222:223], 0, s[12:13]
	s_mov_b32 m0, s33
	s_nop 0
	global_load_lds_dwordx4 v[216:217], off
	s_waitcnt vmcnt(8)
	s_waitcnt lgkmcnt(0)
	s_barrier
	s_setprio 1
	s_waitcnt lgkmcnt(0)
	v_mfma_f32_16x16x32_bf16 v[60:63], v[128:131], v[184:187], v[60:63]
	v_mfma_f32_16x16x32_bf16 v[56:59], v[152:155], v[184:187], v[56:59]
	v_mfma_f32_16x16x32_bf16 v[44:47], v[128:131], v[192:195], v[44:47]
	v_mfma_f32_16x16x32_bf16 v[40:43], v[152:155], v[192:195], v[40:43]
	v_mfma_f32_16x16x32_bf16 v[28:31], v[128:131], v[200:203], v[28:31]
	v_mfma_f32_16x16x32_bf16 v[24:27], v[152:155], v[200:203], v[24:27]
	v_mfma_f32_16x16x32_bf16 v[12:15], v[128:131], v[208:211], v[12:15]
	v_mfma_f32_16x16x32_bf16 v[8:11], v[152:155], v[208:211], v[8:11]
	v_mfma_f32_16x16x32_bf16 v[60:63], v[132:135], v[188:191], v[60:63]
	v_mfma_f32_16x16x32_bf16 v[56:59], v[156:159], v[188:191], v[56:59]
	v_mfma_f32_16x16x32_bf16 v[44:47], v[132:135], v[196:199], v[44:47]
	v_mfma_f32_16x16x32_bf16 v[40:43], v[156:159], v[196:199], v[40:43]
	v_mfma_f32_16x16x32_bf16 v[28:31], v[132:135], v[204:207], v[28:31]
	v_mfma_f32_16x16x32_bf16 v[24:27], v[156:159], v[204:207], v[24:27]
	v_mfma_f32_16x16x32_bf16 v[12:15], v[132:135], v[212:215], v[12:15]
	v_mfma_f32_16x16x32_bf16 v[8:11], v[156:159], v[212:215], v[8:11]
	s_setprio 0
	s_setprio 1
	v_mfma_f32_16x16x32_bf16 v[52:55], v[160:163], v[184:187], v[52:55]
	v_mfma_f32_16x16x32_bf16 v[48:51], v[176:179], v[184:187], v[48:51]
	v_mfma_f32_16x16x32_bf16 v[36:39], v[160:163], v[192:195], v[36:39]
	v_mfma_f32_16x16x32_bf16 v[32:35], v[176:179], v[192:195], v[32:35]
	v_mfma_f32_16x16x32_bf16 v[20:23], v[160:163], v[200:203], v[20:23]
	v_mfma_f32_16x16x32_bf16 v[16:19], v[176:179], v[200:203], v[16:19]
	v_mfma_f32_16x16x32_bf16 v[4:7], v[160:163], v[208:211], v[4:7]
	v_mfma_f32_16x16x32_bf16 v[0:3], v[176:179], v[208:211], v[0:3]
	v_mfma_f32_16x16x32_bf16 v[52:55], v[172:175], v[188:191], v[52:55]
	v_mfma_f32_16x16x32_bf16 v[48:51], v[180:183], v[188:191], v[48:51]
	v_mfma_f32_16x16x32_bf16 v[36:39], v[172:175], v[196:199], v[36:39]
	v_mfma_f32_16x16x32_bf16 v[32:35], v[180:183], v[196:199], v[32:35]
	v_mfma_f32_16x16x32_bf16 v[20:23], v[172:175], v[204:207], v[20:23]
	v_mfma_f32_16x16x32_bf16 v[16:19], v[180:183], v[204:207], v[16:19]
	v_mfma_f32_16x16x32_bf16 v[4:7], v[172:175], v[212:215], v[4:7]
	v_mfma_f32_16x16x32_bf16 v[0:3], v[180:183], v[212:215], v[0:3]
	s_setprio 0
	s_barrier
	s_add_i32 s66, s66, 2
	s_add_u32 s52, s52, 0x100
	s_addc_u32 s53, s53, 0
	s_add_u32 s64, s64, 0x100
	s_addc_u32 s65, s65, 0
	s_cmp_gt_u32 s66, 13
	s_cbranch_scc0 .LBB0_1688
	s_and_b64 vcc, exec, s[14:15]
	s_cbranch_vccz .LBB0_1691
	s_barrier

; #define PG8_STAGE(bufoff, gbase, voff) do { _Pragma("unroll") for (int _i = 0; _i < 2; ++_i) \
;         __builtin_amdgcn_global_load_lds((const unsigned*)((const char*)(gbase) + (voff)[_i]), (LAS unsigned*)(lds + (bufoff) + ldsw + _i * 8192), 16, 0, 0); } while (0)
; #define PG8_LDA(dst, b, h) do { _Pragma("unroll") for (int m = 0; m < 4; ++m) _Pragma("unroll") for (int k = 0; k < 2; ++k) dst[m][k] = *(const LAS bf16x8*)(lds + PG8_SA(b, h) + aoff + m * 2048 + k * 1024); } while (0)
; #define PG8_LDB(dst, b, h) do { _Pragma("unroll") for (int n = 0; n < 2; ++n) _Pragma("unroll") for (int k = 0; k < 2; ++k) dst[n][k] = *(const LAS bf16x8*)(lds + PG8_SB(b, h) + boff + n * 2048 + k * 1024); } while (0)
; #define PG8_MMA(ai, bj, At, Bt) do { __builtin_amdgcn_s_setprio(1); _Pragma("unroll") for (int m = 0; m < 4; ++m) _Pragma("unroll") for (int n = 0; n < 2; ++n) _Pragma("unroll") for (int k = 0; k < 2; ++k) \
;         acc[ai][bj][m][n] = __builtin_amdgcn_mfma_f32_16x16x32_bf16(Bt[n][k], At[m][k], acc[ai][bj][m][n], 0, 0, 0); __builtin_amdgcn_s_setprio(0); } while (0)
; #define PG8_WAIT_V(n) asm volatile("s_waitcnt vmcnt(" #n ")" ::: "memory")
; #define PG8_WAIT_L(n) asm volatile("s_waitcnt lgkmcnt(" #n ")" ::: "memory")
; #define PG8_BAR __builtin_amdgcn_s_barrier()
; template <class Epi, class Sched, bool ALIGN_EPI = false, bool SP2 = false>
; __device__ __forceinline__ void gemm_phase(LAS unsigned char* lds, const Gemm g, const Sched S, const Epi E) {
;     ...
;             const bool last = (t == nt - 2);
;             const char* a1 = cA + (size_t)(t + 1) * kstep;
;             const char* a2 = last ? nA : cA + (size_t)(t + 2) * kstep; const char* b2 = last ? nB : cB + (size_t)(t + 2) * kstep;
;             const char* a3 = a2 + kstep; const char* b3 = b2 + kstep;
;             if (last && has_next) S.a_ready(nxt);
;             if constexpr (SP2) {
;             PG8_LDB(B0, 0, 0); PG8_LDB(B1, 0, 1); PG8_SCHED; PG8_LDA(At, 0, 0); PG8_STAGE(PG8_SA(1, 1), a1 + hstepA, voffA);
;             PG8_WAIT_V(8); PG8_WAIT_L(0); PG8_BAR; PG8_MMA(0, 0, At, B0); PG8_MMA(0, 1, At, B1); PG8_BAR; PG8_SCHED;
;             PG8_LDA(At, 0, 1); PG8_STAGE(PG8_SB(0, 0), b2, voffB); PG8_STAGE(PG8_SB(0, 1), b2 + hstepB, voffB); PG8_STAGE(PG8_SA(0, 0), a2, voffA);
;             PG8_WAIT_V(8); PG8_WAIT_L(0); PG8_BAR; PG8_MMA(1, 0, At, B0); PG8_MMA(1, 1, At, B1); PG8_BAR; PG8_SCHED;
.LBB0_1766:
	ds_read_b128 v[128:131], v173
	ds_read_b128 v[132:135], v173 offset:1024
	ds_read_b128 v[136:139], v173 offset:2048
	ds_read_b128 v[140:143], v173 offset:3072
	ds_read_b128 v[160:163], v174
	ds_read_b128 v[164:167], v174 offset:1024
	ds_read_b128 v[178:181], v174 offset:2048
	ds_read_b128 v[182:185], v174 offset:3072
	s_add_u32 s34, s56, 0xfffc0080
	s_addc_u32 s35, s57, -1
	s_cmp_eq_u32 s66, 12
	s_cselect_b32 s61, s19, s35
	s_cselect_b32 s60, s53, s34
	s_cselect_b32 s59, s17, s65
	s_cselect_b32 s58, s63, s64
	s_add_i32 m0, s5, 0xc000
	ds_read_b128 v[186:189], v175
	ds_read_b128 v[190:193], v175 offset:1024
	ds_read_b128 v[194:197], v175 offset:2048
	ds_read_b128 v[198:201], v175 offset:3072
	ds_read_b128 v[202:205], v175 offset:4096
	ds_read_b128 v[206:209], v175 offset:5120
	ds_read_b128 v[210:213], v175 offset:6144
	ds_read_b128 v[214:217], v175 offset:7168
	global_load_lds_dwordx4 v152, s[56:57]
	s_add_i32 m0, s5, 0xe000
	s_nop 0
	global_load_lds_dwordx4 v154, s[56:57]
	s_waitcnt vmcnt(8)
	s_waitcnt lgkmcnt(0)
	s_barrier
	s_setprio 1
	s_waitcnt lgkmcnt(0)
	v_mfma_f32_16x16x32_bf16 v[124:127], v[128:131], v[186:189], v[124:127]
	v_mfma_f32_16x16x32_bf16 v[120:123], v[136:139], v[186:189], v[120:123]
	v_mfma_f32_16x16x32_bf16 v[108:111], v[128:131], v[194:197], v[108:111]
	v_mfma_f32_16x16x32_bf16 v[104:107], v[136:139], v[194:197], v[104:107]
	v_mfma_f32_16x16x32_bf16 v[92:95], v[128:131], v[202:205], v[92:95]
	v_mfma_f32_16x16x32_bf16 v[88:91], v[136:139], v[202:205], v[88:91]
	v_mfma_f32_16x16x32_bf16 v[76:79], v[128:131], v[210:213], v[76:79]
	v_mfma_f32_16x16x32_bf16 v[72:75], v[136:139], v[210:213], v[72:75]
	v_mfma_f32_16x16x32_bf16 v[124:127], v[132:135], v[190:193], v[124:127]
	v_mfma_f32_16x16x32_bf16 v[120:123], v[140:143], v[190:193], v[120:123]
	v_mfma_f32_16x16x32_bf16 v[108:111], v[132:135], v[198:201], v[108:111]
	v_mfma_f32_16x16x32_bf16 v[104:107], v[140:143], v[198:201], v[104:107]
	v_mfma_f32_16x16x32_bf16 v[92:95], v[132:135], v[206:209], v[92:95]
	v_mfma_f32_16x16x32_bf16 v[88:91], v[140:143], v[206:209], v[88:91]
	v_mfma_f32_16x16x32_bf16 v[76:79], v[132:135], v[214:217], v[76:79]
	v_mfma_f32_16x16x32_bf16 v[72:75], v[140:143], v[214:217], v[72:75]
	s_setprio 0
	s_setprio 1
	v_mfma_f32_16x16x32_bf16 v[116:119], v[160:163], v[186:189], v[116:119]
	v_mfma_f32_16x16x32_bf16 v[112:115], v[178:181], v[186:189], v[112:115]
	v_mfma_f32_16x16x32_bf16 v[100:103], v[160:163], v[194:197], v[100:103]
	v_mfma_f32_16x16x32_bf16 v[96:99], v[178:181], v[194:197], v[96:99]
	v_mfma_f32_16x16x32_bf16 v[84:87], v[160:163], v[202:205], v[84:87]
	v_mfma_f32_16x16x32_bf16 v[80:83], v[178:181], v[202:205], v[80:83]
	v_mfma_f32_16x16x32_bf16 v[68:71], v[160:163], v[210:213], v[68:71]
	v_mfma_f32_16x16x32_bf16 v[64:67], v[178:181], v[210:213], v[64:67]
	v_mfma_f32_16x16x32_bf16 v[116:119], v[164:167], v[190:193], v[116:119]
	v_mfma_f32_16x16x32_bf16 v[112:115], v[182:185], v[190:193], v[112:115]
	v_mfma_f32_16x16x32_bf16 v[100:103], v[164:167], v[198:201], v[100:103]
	v_mfma_f32_16x16x32_bf16 v[96:99], v[182:185], v[198:201], v[96:99]
	v_mfma_f32_16x16x32_bf16 v[84:87], v[164:167], v[206:209], v[84:87]
	v_mfma_f32_16x16x32_bf16 v[80:83], v[182:185], v[206:209], v[80:83]
	v_mfma_f32_16x16x32_bf16 v[68:71], v[164:167], v[214:217], v[68:71]
	v_mfma_f32_16x16x32_bf16 v[64:67], v[182:185], v[214:217], v[64:67]
	s_setprio 0
	s_barrier
	s_add_i32 s34, s55, s4
	v_lshl_add_u64 v[168:169], s[58:59], 0, v[146:147]
	s_mov_b32 m0, s34
	ds_read_b128 v[186:189], v175 offset:16384
	ds_read_b128 v[190:193], v175 offset:17408
	ds_read_b128 v[194:197], v175 offset:18432
	ds_read_b128 v[198:201], v175 offset:19456
	ds_read_b128 v[202:205], v175 offset:20480
	ds_read_b128 v[206:209], v175 offset:21504
	ds_read_b128 v[210:213], v175 offset:22528
	ds_read_b128 v[214:217], v175 offset:23552
	global_load_lds_dwordx4 v[168:169], off
	s_add_i32 m0, s34, 0x2000
	s_add_u32 s34, s58, 0x40000
	v_lshl_add_u64 v[218:219], s[58:59], 0, v[150:151]
	s_addc_u32 s35, s59, 0
	s_add_i32 s67, s62, s4
	global_load_lds_dwordx4 v[218:219], off
	s_mov_b32 m0, s67
	v_lshl_add_u64 v[222:223], s[60:61], 0, v[148:149]
	global_load_lds_dwordx4 v146, s[34:35]
	s_add_i32 m0, s67, 0x2000
	s_nop 0
	global_load_lds_dwordx4 v150, s[34:35]
	v_lshl_add_u64 v[220:221], s[60:61], 0, v[144:145]
	s_mov_b32 m0, s5
	s_nop 0
	global_load_lds_dwordx4 v[220:221], off
	s_mov_b32 m0, s20
	s_nop 0
	global_load_lds_dwordx4 v[222:223], off
	s_waitcnt vmcnt(8)
	s_waitcnt lgkmcnt(0)
	s_barrier
; #define PG8_STAGE(bufoff, gbase, voff) do { _Pragma("unroll") for (int _i = 0; _i < 2; ++_i) \
;         __builtin_amdgcn_global_load_lds((const unsigned*)((const char*)(gbase) + (voff)[_i]), (LAS unsigned*)(lds + (bufoff) + ldsw + _i * 8192), 16, 0, 0); } while (0)
; #define PG8_LDA(dst, b, h) do { _Pragma("unroll") for (int m = 0; m < 4; ++m) _Pragma("unroll") for (int k = 0; k < 2; ++k) dst[m][k] = *(const LAS bf16x8*)(lds + PG8_SA(b, h) + aoff + m * 2048 + k * 1024); } while (0)
; #define PG8_LDB(dst, b, h) do { _Pragma("unroll") for (int n = 0; n < 2; ++n) _Pragma("unroll") for (int k = 0; k < 2; ++k) dst[n][k] = *(const LAS bf16x8*)(lds + PG8_SB(b, h) + boff + n * 2048 + k * 1024); } while (0)
; #define PG8_MMA(ai, bj, At, Bt) do { __builtin_amdgcn_s_setprio(1); _Pragma("unroll") for (int m = 0; m < 4; ++m) _Pragma("unroll") for (int n = 0; n < 2; ++n) _Pragma("unroll") for (int k = 0; k < 2; ++k) \
;         acc[ai][bj][m][n] = __builtin_amdgcn_mfma_f32_16x16x32_bf16(Bt[n][k], At[m][k], acc[ai][bj][m][n], 0, 0, 0); __builtin_amdgcn_s_setprio(0); } while (0)
; #define PG8_WAIT_V(n) asm volatile("s_waitcnt vmcnt(" #n ")" ::: "memory")
; #define PG8_WAIT_L(n) asm volatile("s_waitcnt lgkmcnt(" #n ")" ::: "memory")
; #define PG8_BAR __builtin_amdgcn_s_barrier()
; #define PG8_SCHED __builtin_amdgcn_sched_barrier(0)
; template <class Epi, class Sched, bool ALIGN_EPI = false, bool SP2 = false>
; __device__ __forceinline__ void gemm_phase(LAS unsigned char* lds, const Gemm g, const Sched S, const Epi E) {
;     ...
;             PG8_WAIT_V(8); PG8_WAIT_L(0); PG8_BAR; PG8_MMA(1, 0, At, B0); PG8_MMA(1, 1, At, B1); PG8_BAR; PG8_SCHED;
;             PG8_LDB(B0, 1, 0); PG8_LDB(B1, 1, 1); PG8_SCHED; PG8_LDA(At, 1, 0); PG8_STAGE(PG8_SA(0, 1), a2 + hstepA, voffA);
;             PG8_WAIT_V(8); PG8_WAIT_L(0); PG8_BAR; PG8_MMA(0, 0, At, B0); PG8_MMA(0, 1, At, B1); PG8_BAR; PG8_SCHED;
	s_setprio 1
	s_waitcnt lgkmcnt(0)
	v_mfma_f32_16x16x32_bf16 v[60:63], v[128:131], v[186:189], v[60:63]
	v_mfma_f32_16x16x32_bf16 v[56:59], v[136:139], v[186:189], v[56:59]
	v_mfma_f32_16x16x32_bf16 v[44:47], v[128:131], v[194:197], v[44:47]
	v_mfma_f32_16x16x32_bf16 v[40:43], v[136:139], v[194:197], v[40:43]
	v_mfma_f32_16x16x32_bf16 v[28:31], v[128:131], v[202:205], v[28:31]
	v_mfma_f32_16x16x32_bf16 v[24:27], v[136:139], v[202:205], v[24:27]
	v_mfma_f32_16x16x32_bf16 v[12:15], v[128:131], v[210:213], v[12:15]
	v_mfma_f32_16x16x32_bf16 v[8:11], v[136:139], v[210:213], v[8:11]
	v_mfma_f32_16x16x32_bf16 v[60:63], v[132:135], v[190:193], v[60:63]
	v_mfma_f32_16x16x32_bf16 v[56:59], v[140:143], v[190:193], v[56:59]
	v_mfma_f32_16x16x32_bf16 v[44:47], v[132:135], v[198:201], v[44:47]
	v_mfma_f32_16x16x32_bf16 v[40:43], v[140:143], v[198:201], v[40:43]
	v_mfma_f32_16x16x32_bf16 v[28:31], v[132:135], v[206:209], v[28:31]
	v_mfma_f32_16x16x32_bf16 v[24:27], v[140:143], v[206:209], v[24:27]
	v_mfma_f32_16x16x32_bf16 v[12:15], v[132:135], v[214:217], v[12:15]
	v_mfma_f32_16x16x32_bf16 v[8:11], v[140:143], v[214:217], v[8:11]
	s_setprio 0
	s_setprio 1
	v_mfma_f32_16x16x32_bf16 v[52:55], v[160:163], v[186:189], v[52:55]
	v_mfma_f32_16x16x32_bf16 v[48:51], v[178:181], v[186:189], v[48:51]
	v_mfma_f32_16x16x32_bf16 v[36:39], v[160:163], v[194:197], v[36:39]
	v_mfma_f32_16x16x32_bf16 v[32:35], v[178:181], v[194:197], v[32:35]
	v_mfma_f32_16x16x32_bf16 v[20:23], v[160:163], v[202:205], v[20:23]
	v_mfma_f32_16x16x32_bf16 v[16:19], v[178:181], v[202:205], v[16:19]
	v_mfma_f32_16x16x32_bf16 v[4:7], v[160:163], v[210:213], v[4:7]
	v_mfma_f32_16x16x32_bf16 v[0:3], v[178:181], v[210:213], v[0:3]
	v_mfma_f32_16x16x32_bf16 v[52:55], v[164:167], v[190:193], v[52:55]
	v_mfma_f32_16x16x32_bf16 v[48:51], v[182:185], v[190:193], v[48:51]
	v_mfma_f32_16x16x32_bf16 v[36:39], v[164:167], v[198:201], v[36:39]
	v_mfma_f32_16x16x32_bf16 v[32:35], v[182:185], v[198:201], v[32:35]
	v_mfma_f32_16x16x32_bf16 v[20:23], v[164:167], v[206:209], v[20:23]
	v_mfma_f32_16x16x32_bf16 v[16:19], v[182:185], v[206:209], v[16:19]
	v_mfma_f32_16x16x32_bf16 v[4:7], v[164:167], v[214:217], v[4:7]
	v_mfma_f32_16x16x32_bf16 v[0:3], v[182:185], v[214:217], v[0:3]
	s_setprio 0
	s_barrier
	s_add_i32 s67, 0, 0x18000
	s_add_i32 s68, 0, 0x1c000
	v_add_u32_e32 v140, s67, v171
	v_add_u32_e32 v177, s68, v171
	ds_read_b128 v[128:131], v140
	ds_read_b128 v[132:135], v140 offset:1024
	ds_read_b128 v[136:139], v140 offset:2048
	ds_read_b128 v[140:143], v140 offset:3072
	ds_read_b128 v[160:163], v177
	ds_read_b128 v[164:167], v177 offset:1024
	ds_read_b128 v[178:181], v177 offset:2048
	ds_read_b128 v[182:185], v177 offset:3072
	s_add_u32 s34, s60, 0x40000
	s_addc_u32 s35, s61, 0
	s_mov_b32 m0, s21
	ds_read_b128 v[186:189], v175 offset:32768
	ds_read_b128 v[190:193], v175 offset:33792
	ds_read_b128 v[194:197], v175 offset:34816
	ds_read_b128 v[198:201], v175 offset:35840
	ds_read_b128 v[202:205], v175 offset:36864
	ds_read_b128 v[206:209], v175 offset:37888
	ds_read_b128 v[210:213], v175 offset:38912
	ds_read_b128 v[214:217], v175 offset:39936
	global_load_lds_dwordx4 v144, s[34:35]
	s_mov_b32 m0, s29
	s_nop 0
	global_load_lds_dwordx4 v148, s[34:35]
	s_waitcnt vmcnt(8)
	s_waitcnt lgkmcnt(0)
	s_barrier
	s_setprio 1
	s_waitcnt lgkmcnt(0)
	v_mfma_f32_16x16x32_bf16 v[124:127], v[128:131], v[186:189], v[124:127]
	v_mfma_f32_16x16x32_bf16 v[120:123], v[136:139], v[186:189], v[120:123]
	v_mfma_f32_16x16x32_bf16 v[108:111], v[128:131], v[194:197], v[108:111]
	v_mfma_f32_16x16x32_bf16 v[104:107], v[136:139], v[194:197], v[104:107]
	v_mfma_f32_16x16x32_bf16 v[92:95], v[128:131], v[202:205], v[92:95]
	v_mfma_f32_16x16x32_bf16 v[88:91], v[136:139], v[202:205], v[88:91]
	v_mfma_f32_16x16x32_bf16 v[76:79], v[128:131], v[210:213], v[76:79]
	v_mfma_f32_16x16x32_bf16 v[72:75], v[136:139], v[210:213], v[72:75]
	v_mfma_f32_16x16x32_bf16 v[124:127], v[132:135], v[190:193], v[124:127]
	v_mfma_f32_16x16x32_bf16 v[120:123], v[140:143], v[190:193], v[120:123]
	v_mfma_f32_16x16x32_bf16 v[108:111], v[132:135], v[198:201], v[108:111]
	v_mfma_f32_16x16x32_bf16 v[104:107], v[140:143], v[198:201], v[104:107]
	v_mfma_f32_16x16x32_bf16 v[92:95], v[132:135], v[206:209], v[92:95]
	v_mfma_f32_16x16x32_bf16 v[88:91], v[140:143], v[206:209], v[88:91]
	v_mfma_f32_16x16x32_bf16 v[76:79], v[132:135], v[214:217], v[76:79]
	v_mfma_f32_16x16x32_bf16 v[72:75], v[140:143], v[214:217], v[72:75]
	s_setprio 0
	s_setprio 1
	v_mfma_f32_16x16x32_bf16 v[116:119], v[160:163], v[186:189], v[116:119]
	v_mfma_f32_16x16x32_bf16 v[112:115], v[178:181], v[186:189], v[112:115]
	v_mfma_f32_16x16x32_bf16 v[100:103], v[160:163], v[194:197], v[100:103]
	v_mfma_f32_16x16x32_bf16 v[96:99], v[178:181], v[194:197], v[96:99]
	v_mfma_f32_16x16x32_bf16 v[84:87], v[160:163], v[202:205], v[84:87]
	v_mfma_f32_16x16x32_bf16 v[80:83], v[178:181], v[202:205], v[80:83]
	v_mfma_f32_16x16x32_bf16 v[68:71], v[160:163], v[210:213], v[68:71]
	v_mfma_f32_16x16x32_bf16 v[64:67], v[178:181], v[210:213], v[64:67]
	v_mfma_f32_16x16x32_bf16 v[116:119], v[164:167], v[190:193], v[116:119]
	v_mfma_f32_16x16x32_bf16 v[112:115], v[182:185], v[190:193], v[112:115]
	v_mfma_f32_16x16x32_bf16 v[100:103], v[164:167], v[198:201], v[100:103]
	v_mfma_f32_16x16x32_bf16 v[96:99], v[182:185], v[198:201], v[96:99]
	v_mfma_f32_16x16x32_bf16 v[84:87], v[164:167], v[206:209], v[84:87]
	v_mfma_f32_16x16x32_bf16 v[80:83], v[182:185], v[206:209], v[80:83]
	v_mfma_f32_16x16x32_bf16 v[68:71], v[164:167], v[214:217], v[68:71]
	v_mfma_f32_16x16x32_bf16 v[64:67], v[182:185], v[214:217], v[64:67]
	s_setprio 0
	s_barrier
; #define PG8_STAGE(bufoff, gbase, voff) do { _Pragma("unroll") for (int _i = 0; _i < 2; ++_i) \
;         __builtin_amdgcn_global_load_lds((const unsigned*)((const char*)(gbase) + (voff)[_i]), (LAS unsigned*)(lds + (bufoff) + ldsw + _i * 8192), 16, 0, 0); } while (0)
; #define PG8_LDA(dst, b, h) do { _Pragma("unroll") for (int m = 0; m < 4; ++m) _Pragma("unroll") for (int k = 0; k < 2; ++k) dst[m][k] = *(const LAS bf16x8*)(lds + PG8_SA(b, h) + aoff + m * 2048 + k * 1024); } while (0)
; #define PG8_MMA(ai, bj, At, Bt) do { __builtin_amdgcn_s_setprio(1); _Pragma("unroll") for (int m = 0; m < 4; ++m) _Pragma("unroll") for (int n = 0; n < 2; ++n) _Pragma("unroll") for (int k = 0; k < 2; ++k) \
;         acc[ai][bj][m][n] = __builtin_amdgcn_mfma_f32_16x16x32_bf16(Bt[n][k], At[m][k], acc[ai][bj][m][n], 0, 0, 0); __builtin_amdgcn_s_setprio(0); } while (0)
; #define PG8_WAIT_V(n) asm volatile("s_waitcnt vmcnt(" #n ")" ::: "memory")
; #define PG8_WAIT_L(n) asm volatile("s_waitcnt lgkmcnt(" #n ")" ::: "memory")
; #define PG8_BAR __builtin_amdgcn_s_barrier()
; #define PG8_SCHED __builtin_amdgcn_sched_barrier(0)
; template <class Epi, class Sched, bool ALIGN_EPI = false, bool SP2 = false>
; __device__ __forceinline__ void gemm_phase(LAS unsigned char* lds, const Gemm g, const Sched S, const Epi E) {
;     ...
;             PG8_LDA(At, 1, 1); PG8_STAGE(PG8_SB(1, 0), b3, voffB); PG8_STAGE(PG8_SB(1, 1), b3 + hstepB, voffB); PG8_STAGE(PG8_SA(1, 0), a3, voffA);
;             PG8_WAIT_V(8); PG8_WAIT_L(0); PG8_BAR; PG8_MMA(1, 0, At, B0); PG8_MMA(1, 1, At, B1); PG8_BAR; PG8_SCHED;
	s_add_i32 s34, s67, s4
	v_lshl_add_u64 v[168:169], v[168:169], 0, s[12:13]
	s_mov_b32 m0, s34
	ds_read_b128 v[186:189], v175 offset:49152
	ds_read_b128 v[190:193], v175 offset:50176
	ds_read_b128 v[194:197], v175 offset:51200
	ds_read_b128 v[198:201], v175 offset:52224
	ds_read_b128 v[202:205], v175 offset:53248
	ds_read_b128 v[206:209], v175 offset:54272
	ds_read_b128 v[210:213], v175 offset:55296
	ds_read_b128 v[214:217], v175 offset:56320
	global_load_lds_dwordx4 v[168:169], off
	s_add_i32 m0, s34, 0x2000
	s_add_u32 s34, s58, 0x40080
	v_lshl_add_u64 v[168:169], v[218:219], 0, s[12:13]
	s_addc_u32 s35, s59, 0
	s_add_i32 s58, s68, s4
	global_load_lds_dwordx4 v[168:169], off
	s_mov_b32 m0, s58
	s_nop 0
	global_load_lds_dwordx4 v146, s[34:35]
	s_add_i32 m0, s58, 0x2000
	s_nop 0
	global_load_lds_dwordx4 v150, s[34:35]
	v_lshl_add_u64 v[168:169], v[220:221], 0, s[12:13]
	s_mov_b32 m0, s31
	s_nop 0
	global_load_lds_dwordx4 v[168:169], off
	v_lshl_add_u64 v[168:169], v[222:223], 0, s[12:13]
	s_mov_b32 m0, s33
	s_nop 0
	global_load_lds_dwordx4 v[168:169], off
	s_waitcnt vmcnt(8)
	s_waitcnt lgkmcnt(0)
	s_barrier
	s_setprio 1
	s_waitcnt lgkmcnt(0)
	v_mfma_f32_16x16x32_bf16 v[60:63], v[128:131], v[186:189], v[60:63]
	v_mfma_f32_16x16x32_bf16 v[56:59], v[136:139], v[186:189], v[56:59]
	v_mfma_f32_16x16x32_bf16 v[44:47], v[128:131], v[194:197], v[44:47]
	v_mfma_f32_16x16x32_bf16 v[40:43], v[136:139], v[194:197], v[40:43]
	v_mfma_f32_16x16x32_bf16 v[28:31], v[128:131], v[202:205], v[28:31]
	v_mfma_f32_16x16x32_bf16 v[24:27], v[136:139], v[202:205], v[24:27]
	v_mfma_f32_16x16x32_bf16 v[12:15], v[128:131], v[210:213], v[12:15]
	v_mfma_f32_16x16x32_bf16 v[8:11], v[136:139], v[210:213], v[8:11]
	v_mfma_f32_16x16x32_bf16 v[60:63], v[132:135], v[190:193], v[60:63]
	v_mfma_f32_16x16x32_bf16 v[56:59], v[140:143], v[190:193], v[56:59]
	v_mfma_f32_16x16x32_bf16 v[44:47], v[132:135], v[198:201], v[44:47]
	v_mfma_f32_16x16x32_bf16 v[40:43], v[140:143], v[198:201], v[40:43]
	v_mfma_f32_16x16x32_bf16 v[28:31], v[132:135], v[206:209], v[28:31]
	v_mfma_f32_16x16x32_bf16 v[24:27], v[140:143], v[206:209], v[24:27]
	v_mfma_f32_16x16x32_bf16 v[12:15], v[132:135], v[214:217], v[12:15]
	v_mfma_f32_16x16x32_bf16 v[8:11], v[140:143], v[214:217], v[8:11]
	s_setprio 0
	s_setprio 1
	v_mfma_f32_16x16x32_bf16 v[52:55], v[160:163], v[186:189], v[52:55]
	v_mfma_f32_16x16x32_bf16 v[48:51], v[178:181], v[186:189], v[48:51]
	v_mfma_f32_16x16x32_bf16 v[36:39], v[160:163], v[194:197], v[36:39]
	v_mfma_f32_16x16x32_bf16 v[32:35], v[178:181], v[194:197], v[32:35]
	v_mfma_f32_16x16x32_bf16 v[20:23], v[160:163], v[202:205], v[20:23]
	v_mfma_f32_16x16x32_bf16 v[16:19], v[178:181], v[202:205], v[16:19]
	v_mfma_f32_16x16x32_bf16 v[4:7], v[160:163], v[210:213], v[4:7]
	v_mfma_f32_16x16x32_bf16 v[0:3], v[178:181], v[210:213], v[0:3]
	v_mfma_f32_16x16x32_bf16 v[52:55], v[164:167], v[190:193], v[52:55]
	v_mfma_f32_16x16x32_bf16 v[48:51], v[182:185], v[190:193], v[48:51]
	v_mfma_f32_16x16x32_bf16 v[36:39], v[164:167], v[198:201], v[36:39]
	v_mfma_f32_16x16x32_bf16 v[32:35], v[182:185], v[198:201], v[32:35]
	v_mfma_f32_16x16x32_bf16 v[20:23], v[164:167], v[206:209], v[20:23]
	v_mfma_f32_16x16x32_bf16 v[16:19], v[182:185], v[206:209], v[16:19]
	v_mfma_f32_16x16x32_bf16 v[4:7], v[164:167], v[214:217], v[4:7]
	v_mfma_f32_16x16x32_bf16 v[0:3], v[182:185], v[214:217], v[0:3]
	s_setprio 0
	s_barrier
	s_add_i32 s66, s66, 2
	s_add_u32 s56, s56, 0x100
	s_addc_u32 s57, s57, 0
	s_add_u32 s64, s64, 0x100
	s_addc_u32 s65, s65, 0
	s_cmp_gt_u32 s66, 13
	s_cbranch_scc0 .LBB0_1766
	s_and_b64 vcc, exec, s[14:15]
	s_cbranch_vccz .LBB0_1769
	s_barrier

; #define PG8_STAGE(bufoff, gbase, voff) do { _Pragma("unroll") for (int _i = 0; _i < 2; ++_i) \
;         __builtin_amdgcn_global_load_lds((const unsigned*)((const char*)(gbase) + (voff)[_i]), (LAS unsigned*)(lds + (bufoff) + ldsw + _i * 8192), 16, 0, 0); } while (0)
; #define PG8_LDA(dst, b, h) do { _Pragma("unroll") for (int m = 0; m < 4; ++m) _Pragma("unroll") for (int k = 0; k < 2; ++k) dst[m][k] = *(const LAS bf16x8*)(lds + PG8_SA(b, h) + aoff + m * 2048 + k * 1024); } while (0)
; #define PG8_LDB(dst, b, h) do { _Pragma("unroll") for (int n = 0; n < 2; ++n) _Pragma("unroll") for (int k = 0; k < 2; ++k) dst[n][k] = *(const LAS bf16x8*)(lds + PG8_SB(b, h) + boff + n * 2048 + k * 1024); } while (0)
; #define PG8_MMA(ai, bj, At, Bt) do { __builtin_amdgcn_s_setprio(1); _Pragma("unroll") for (int m = 0; m < 4; ++m) _Pragma("unroll") for (int n = 0; n < 2; ++n) _Pragma("unroll") for (int k = 0; k < 2; ++k) \
;         acc[ai][bj][m][n] = __builtin_amdgcn_mfma_f32_16x16x32_bf16(Bt[n][k], At[m][k], acc[ai][bj][m][n], 0, 0, 0); __builtin_amdgcn_s_setprio(0); } while (0)
; #define PG8_WAIT_V(n) asm volatile("s_waitcnt vmcnt(" #n ")" ::: "memory")
; #define PG8_WAIT_L(n) asm volatile("s_waitcnt lgkmcnt(" #n ")" ::: "memory")
; #define PG8_BAR __builtin_amdgcn_s_barrier()
; template <class Epi, class Sched, bool ALIGN_EPI = false, bool SP2 = false>
; __device__ __forceinline__ void gemm_phase(LAS unsigned char* lds, const Gemm g, const Sched S, const Epi E) {
;     ...
;             const bool last = (t == nt - 2);
;             const char* a1 = cA + (size_t)(t + 1) * kstep;
;             const char* a2 = last ? nA : cA + (size_t)(t + 2) * kstep; const char* b2 = last ? nB : cB + (size_t)(t + 2) * kstep;
;             const char* a3 = a2 + kstep; const char* b3 = b2 + kstep;
;             if (last && has_next) S.a_ready(nxt);
;             if constexpr (SP2) {
;             PG8_LDB(B0, 0, 0); PG8_LDB(B1, 0, 1); PG8_SCHED; PG8_LDA(At, 0, 0); PG8_STAGE(PG8_SA(1, 1), a1 + hstepA, voffA);
;             PG8_WAIT_V(8); PG8_WAIT_L(0); PG8_BAR; PG8_MMA(0, 0, At, B0); PG8_MMA(0, 1, At, B1); PG8_BAR; PG8_SCHED;
;             PG8_LDA(At, 0, 1); PG8_STAGE(PG8_SB(0, 0), b2, voffB); PG8_STAGE(PG8_SB(0, 1), b2 + hstepB, voffB); PG8_STAGE(PG8_SA(0, 0), a2, voffA);
;             PG8_WAIT_V(8); PG8_WAIT_L(0); PG8_BAR; PG8_MMA(1, 0, At, B0); PG8_MMA(1, 1, At, B1); PG8_BAR; PG8_SCHED;
.LBB0_1850:
	ds_read_b128 v[166:169], v155
	ds_read_b128 v[170:173], v155 offset:1024
	ds_read_b128 v[174:177], v155 offset:2048
	ds_read_b128 v[178:181], v155 offset:3072
	ds_read_b128 v[182:185], v159
	ds_read_b128 v[186:189], v159 offset:1024
	ds_read_b128 v[190:193], v159 offset:2048
	ds_read_b128 v[194:197], v159 offset:3072
	s_add_u32 s12, s10, 0xfff80080
	s_addc_u32 s13, s11, -1
	s_cmp_eq_u32 s51, 12
	s_cselect_b32 s15, s16, s13
	s_cselect_b32 s14, s17, s12
	s_cselect_b32 s13, s18, s23
	s_cselect_b32 s12, s19, s22
	s_add_i32 m0, s20, 0xc000
	ds_read_b128 v[198:201], v163
	ds_read_b128 v[202:205], v163 offset:1024
	ds_read_b128 v[206:209], v163 offset:2048
	ds_read_b128 v[210:213], v163 offset:3072
	ds_read_b128 v[214:217], v163 offset:4096
	ds_read_b128 v[218:221], v163 offset:5120
	ds_read_b128 v[222:225], v163 offset:6144
	ds_read_b128 v[226:229], v163 offset:7168
	global_load_lds_dwordx4 v136, s[10:11]
	s_add_i32 m0, s20, 0xe000
	s_nop 0
	global_load_lds_dwordx4 v138, s[10:11]
	s_waitcnt vmcnt(8)
	s_waitcnt lgkmcnt(0)
	s_barrier
	s_setprio 1
	s_waitcnt lgkmcnt(0)
	v_mfma_f32_16x16x32_bf16 v[124:127], v[166:169], v[198:201], v[124:127]
	v_mfma_f32_16x16x32_bf16 v[120:123], v[174:177], v[198:201], v[120:123]
	v_mfma_f32_16x16x32_bf16 v[108:111], v[166:169], v[206:209], v[108:111]
	v_mfma_f32_16x16x32_bf16 v[104:107], v[174:177], v[206:209], v[104:107]
	v_mfma_f32_16x16x32_bf16 v[92:95], v[166:169], v[214:217], v[92:95]
	v_mfma_f32_16x16x32_bf16 v[88:91], v[174:177], v[214:217], v[88:91]
	v_mfma_f32_16x16x32_bf16 v[76:79], v[166:169], v[222:225], v[76:79]
	v_mfma_f32_16x16x32_bf16 v[72:75], v[174:177], v[222:225], v[72:75]
	v_mfma_f32_16x16x32_bf16 v[124:127], v[170:173], v[202:205], v[124:127]
	v_mfma_f32_16x16x32_bf16 v[120:123], v[178:181], v[202:205], v[120:123]
	v_mfma_f32_16x16x32_bf16 v[108:111], v[170:173], v[210:213], v[108:111]
	v_mfma_f32_16x16x32_bf16 v[104:107], v[178:181], v[210:213], v[104:107]
	v_mfma_f32_16x16x32_bf16 v[92:95], v[170:173], v[218:221], v[92:95]
	v_mfma_f32_16x16x32_bf16 v[88:91], v[178:181], v[218:221], v[88:91]
	v_mfma_f32_16x16x32_bf16 v[76:79], v[170:173], v[226:229], v[76:79]
	v_mfma_f32_16x16x32_bf16 v[72:75], v[178:181], v[226:229], v[72:75]
	s_setprio 0
	s_setprio 1
	v_mfma_f32_16x16x32_bf16 v[116:119], v[182:185], v[198:201], v[116:119]
	v_mfma_f32_16x16x32_bf16 v[112:115], v[190:193], v[198:201], v[112:115]
	v_mfma_f32_16x16x32_bf16 v[100:103], v[182:185], v[206:209], v[100:103]
	v_mfma_f32_16x16x32_bf16 v[96:99], v[190:193], v[206:209], v[96:99]
	v_mfma_f32_16x16x32_bf16 v[84:87], v[182:185], v[214:217], v[84:87]
	v_mfma_f32_16x16x32_bf16 v[80:83], v[190:193], v[214:217], v[80:83]
	v_mfma_f32_16x16x32_bf16 v[68:71], v[182:185], v[222:225], v[68:71]
	v_mfma_f32_16x16x32_bf16 v[64:67], v[190:193], v[222:225], v[64:67]
	v_mfma_f32_16x16x32_bf16 v[116:119], v[186:189], v[202:205], v[116:119]
	v_mfma_f32_16x16x32_bf16 v[112:115], v[194:197], v[202:205], v[112:115]
	v_mfma_f32_16x16x32_bf16 v[100:103], v[186:189], v[210:213], v[100:103]
	v_mfma_f32_16x16x32_bf16 v[96:99], v[194:197], v[210:213], v[96:99]
	v_mfma_f32_16x16x32_bf16 v[84:87], v[186:189], v[218:221], v[84:87]
	v_mfma_f32_16x16x32_bf16 v[80:83], v[194:197], v[218:221], v[80:83]
	v_mfma_f32_16x16x32_bf16 v[68:71], v[186:189], v[226:229], v[68:71]
	v_mfma_f32_16x16x32_bf16 v[64:67], v[194:197], v[226:229], v[64:67]
	s_setprio 0
	s_barrier
	s_add_i32 s34, s61, s4
	v_lshl_add_u64 v[144:145], s[12:13], 0, v[132:133]
	s_mov_b32 m0, s34
	ds_read_b128 v[198:201], v163 offset:16384
	ds_read_b128 v[202:205], v163 offset:17408
	ds_read_b128 v[206:209], v163 offset:18432
	ds_read_b128 v[210:213], v163 offset:19456
	ds_read_b128 v[214:217], v163 offset:20480
	ds_read_b128 v[218:221], v163 offset:21504
	ds_read_b128 v[222:225], v163 offset:22528
	ds_read_b128 v[226:229], v163 offset:23552
	global_load_lds_dwordx4 v[144:145], off
	s_add_i32 m0, s34, 0x2000
	s_add_u32 s34, s12, 0x40000
	v_lshl_add_u64 v[152:153], s[12:13], 0, v[128:129]
	s_addc_u32 s35, s13, 0
	s_add_i32 s53, s62, s4
	global_load_lds_dwordx4 v[152:153], off
	s_mov_b32 m0, s53
	v_lshl_add_u64 v[160:161], s[14:15], 0, v[130:131]
	global_load_lds_dwordx4 v132, s[34:35]
	s_add_i32 m0, s53, 0x2000
	s_nop 0
	global_load_lds_dwordx4 v128, s[34:35]
	v_lshl_add_u64 v[156:157], s[14:15], 0, v[134:135]
	s_mov_b32 m0, s20
	s_nop 0
	global_load_lds_dwordx4 v[156:157], off
	s_mov_b32 m0, s21
	s_nop 0
	global_load_lds_dwordx4 v[160:161], off
	s_waitcnt vmcnt(8)
	s_waitcnt lgkmcnt(0)
	s_barrier
; #define PG8_STAGE(bufoff, gbase, voff) do { _Pragma("unroll") for (int _i = 0; _i < 2; ++_i) \
;         __builtin_amdgcn_global_load_lds((const unsigned*)((const char*)(gbase) + (voff)[_i]), (LAS unsigned*)(lds + (bufoff) + ldsw + _i * 8192), 16, 0, 0); } while (0)
; #define PG8_LDA(dst, b, h) do { _Pragma("unroll") for (int m = 0; m < 4; ++m) _Pragma("unroll") for (int k = 0; k < 2; ++k) dst[m][k] = *(const LAS bf16x8*)(lds + PG8_SA(b, h) + aoff + m * 2048 + k * 1024); } while (0)
; #define PG8_LDB(dst, b, h) do { _Pragma("unroll") for (int n = 0; n < 2; ++n) _Pragma("unroll") for (int k = 0; k < 2; ++k) dst[n][k] = *(const LAS bf16x8*)(lds + PG8_SB(b, h) + boff + n * 2048 + k * 1024); } while (0)
; #define PG8_MMA(ai, bj, At, Bt) do { __builtin_amdgcn_s_setprio(1); _Pragma("unroll") for (int m = 0; m < 4; ++m) _Pragma("unroll") for (int n = 0; n < 2; ++n) _Pragma("unroll") for (int k = 0; k < 2; ++k) \
;         acc[ai][bj][m][n] = __builtin_amdgcn_mfma_f32_16x16x32_bf16(Bt[n][k], At[m][k], acc[ai][bj][m][n], 0, 0, 0); __builtin_amdgcn_s_setprio(0); } while (0)
; #define PG8_WAIT_V(n) asm volatile("s_waitcnt vmcnt(" #n ")" ::: "memory")
; #define PG8_WAIT_L(n) asm volatile("s_waitcnt lgkmcnt(" #n ")" ::: "memory")
; #define PG8_BAR __builtin_amdgcn_s_barrier()
; #define PG8_SCHED __builtin_amdgcn_sched_barrier(0)
; template <class Epi, class Sched, bool ALIGN_EPI = false, bool SP2 = false>
; __device__ __forceinline__ void gemm_phase(LAS unsigned char* lds, const Gemm g, const Sched S, const Epi E) {
;     ...
;             PG8_WAIT_V(8); PG8_WAIT_L(0); PG8_BAR; PG8_MMA(1, 0, At, B0); PG8_MMA(1, 1, At, B1); PG8_BAR; PG8_SCHED;
;             PG8_LDB(B0, 1, 0); PG8_LDB(B1, 1, 1); PG8_SCHED; PG8_LDA(At, 1, 0); PG8_STAGE(PG8_SA(0, 1), a2 + hstepA, voffA);
;             PG8_WAIT_V(8); PG8_WAIT_L(0); PG8_BAR; PG8_MMA(0, 0, At, B0); PG8_MMA(0, 1, At, B1); PG8_BAR; PG8_SCHED;
	s_setprio 1
	s_waitcnt lgkmcnt(0)
	v_mfma_f32_16x16x32_bf16 v[60:63], v[166:169], v[198:201], v[60:63]
	v_mfma_f32_16x16x32_bf16 v[56:59], v[174:177], v[198:201], v[56:59]
	v_mfma_f32_16x16x32_bf16 v[44:47], v[166:169], v[206:209], v[44:47]
	v_mfma_f32_16x16x32_bf16 v[40:43], v[174:177], v[206:209], v[40:43]
	v_mfma_f32_16x16x32_bf16 v[28:31], v[166:169], v[214:217], v[28:31]
	v_mfma_f32_16x16x32_bf16 v[24:27], v[174:177], v[214:217], v[24:27]
	v_mfma_f32_16x16x32_bf16 v[12:15], v[166:169], v[222:225], v[12:15]
	v_mfma_f32_16x16x32_bf16 v[8:11], v[174:177], v[222:225], v[8:11]
	v_mfma_f32_16x16x32_bf16 v[60:63], v[170:173], v[202:205], v[60:63]
	v_mfma_f32_16x16x32_bf16 v[56:59], v[178:181], v[202:205], v[56:59]
	v_mfma_f32_16x16x32_bf16 v[44:47], v[170:173], v[210:213], v[44:47]
	v_mfma_f32_16x16x32_bf16 v[40:43], v[178:181], v[210:213], v[40:43]
	v_mfma_f32_16x16x32_bf16 v[28:31], v[170:173], v[218:221], v[28:31]
	v_mfma_f32_16x16x32_bf16 v[24:27], v[178:181], v[218:221], v[24:27]
	v_mfma_f32_16x16x32_bf16 v[12:15], v[170:173], v[226:229], v[12:15]
	v_mfma_f32_16x16x32_bf16 v[8:11], v[178:181], v[226:229], v[8:11]
	s_setprio 0
	s_setprio 1
	v_mfma_f32_16x16x32_bf16 v[52:55], v[182:185], v[198:201], v[52:55]
	v_mfma_f32_16x16x32_bf16 v[48:51], v[190:193], v[198:201], v[48:51]
	v_mfma_f32_16x16x32_bf16 v[36:39], v[182:185], v[206:209], v[36:39]
	v_mfma_f32_16x16x32_bf16 v[32:35], v[190:193], v[206:209], v[32:35]
	v_mfma_f32_16x16x32_bf16 v[20:23], v[182:185], v[214:217], v[20:23]
	v_mfma_f32_16x16x32_bf16 v[16:19], v[190:193], v[214:217], v[16:19]
	v_mfma_f32_16x16x32_bf16 v[4:7], v[182:185], v[222:225], v[4:7]
	v_mfma_f32_16x16x32_bf16 v[0:3], v[190:193], v[222:225], v[0:3]
	v_mfma_f32_16x16x32_bf16 v[52:55], v[186:189], v[202:205], v[52:55]
	v_mfma_f32_16x16x32_bf16 v[48:51], v[194:197], v[202:205], v[48:51]
	v_mfma_f32_16x16x32_bf16 v[36:39], v[186:189], v[210:213], v[36:39]
	v_mfma_f32_16x16x32_bf16 v[32:35], v[194:197], v[210:213], v[32:35]
	v_mfma_f32_16x16x32_bf16 v[20:23], v[186:189], v[218:221], v[20:23]
	v_mfma_f32_16x16x32_bf16 v[16:19], v[194:197], v[218:221], v[16:19]
	v_mfma_f32_16x16x32_bf16 v[4:7], v[186:189], v[226:229], v[4:7]
	v_mfma_f32_16x16x32_bf16 v[0:3], v[194:197], v[226:229], v[0:3]
	s_setprio 0
	s_barrier
	s_add_i32 s34, 0, 0x18000
	v_add_u32_e32 v146, s34, v149
	s_add_i32 s35, 0, 0x1c000
	ds_read_b128 v[166:169], v146
	ds_read_b128 v[170:173], v146 offset:1024
	ds_read_b128 v[174:177], v146 offset:2048
	ds_read_b128 v[178:181], v146 offset:3072
	v_add_u32_e32 v146, s35, v149
	ds_read_b128 v[182:185], v146
	ds_read_b128 v[186:189], v146 offset:1024
	ds_read_b128 v[190:193], v146 offset:2048
	ds_read_b128 v[194:197], v146 offset:3072
	s_add_u32 s14, s14, 0x80000
	s_addc_u32 s15, s15, 0
	s_mov_b32 m0, s29
	ds_read_b128 v[198:201], v163 offset:32768
	ds_read_b128 v[202:205], v163 offset:33792
	ds_read_b128 v[206:209], v163 offset:34816
	ds_read_b128 v[210:213], v163 offset:35840
	ds_read_b128 v[214:217], v163 offset:36864
	ds_read_b128 v[218:221], v163 offset:37888
	ds_read_b128 v[222:225], v163 offset:38912
	ds_read_b128 v[226:229], v163 offset:39936
	global_load_lds_dwordx4 v134, s[14:15]
	s_mov_b32 m0, s30
	s_nop 0
	global_load_lds_dwordx4 v130, s[14:15]
	s_waitcnt vmcnt(8)
	s_waitcnt lgkmcnt(0)
	s_barrier
	s_setprio 1
	s_waitcnt lgkmcnt(0)
	v_mfma_f32_16x16x32_bf16 v[124:127], v[166:169], v[198:201], v[124:127]
	v_mfma_f32_16x16x32_bf16 v[120:123], v[174:177], v[198:201], v[120:123]
	v_mfma_f32_16x16x32_bf16 v[108:111], v[166:169], v[206:209], v[108:111]
	v_mfma_f32_16x16x32_bf16 v[104:107], v[174:177], v[206:209], v[104:107]
	v_mfma_f32_16x16x32_bf16 v[92:95], v[166:169], v[214:217], v[92:95]
	v_mfma_f32_16x16x32_bf16 v[88:91], v[174:177], v[214:217], v[88:91]
	v_mfma_f32_16x16x32_bf16 v[76:79], v[166:169], v[222:225], v[76:79]
	v_mfma_f32_16x16x32_bf16 v[72:75], v[174:177], v[222:225], v[72:75]
	v_mfma_f32_16x16x32_bf16 v[124:127], v[170:173], v[202:205], v[124:127]
	v_mfma_f32_16x16x32_bf16 v[120:123], v[178:181], v[202:205], v[120:123]
	v_mfma_f32_16x16x32_bf16 v[108:111], v[170:173], v[210:213], v[108:111]
	v_mfma_f32_16x16x32_bf16 v[104:107], v[178:181], v[210:213], v[104:107]
	v_mfma_f32_16x16x32_bf16 v[92:95], v[170:173], v[218:221], v[92:95]
	v_mfma_f32_16x16x32_bf16 v[88:91], v[178:181], v[218:221], v[88:91]
	v_mfma_f32_16x16x32_bf16 v[76:79], v[170:173], v[226:229], v[76:79]
	v_mfma_f32_16x16x32_bf16 v[72:75], v[178:181], v[226:229], v[72:75]
	s_setprio 0
	s_setprio 1
	v_mfma_f32_16x16x32_bf16 v[116:119], v[182:185], v[198:201], v[116:119]
	v_mfma_f32_16x16x32_bf16 v[112:115], v[190:193], v[198:201], v[112:115]
	v_mfma_f32_16x16x32_bf16 v[100:103], v[182:185], v[206:209], v[100:103]
	v_mfma_f32_16x16x32_bf16 v[96:99], v[190:193], v[206:209], v[96:99]
	v_mfma_f32_16x16x32_bf16 v[84:87], v[182:185], v[214:217], v[84:87]
	v_mfma_f32_16x16x32_bf16 v[80:83], v[190:193], v[214:217], v[80:83]
	v_mfma_f32_16x16x32_bf16 v[68:71], v[182:185], v[222:225], v[68:71]
	v_mfma_f32_16x16x32_bf16 v[64:67], v[190:193], v[222:225], v[64:67]
	v_mfma_f32_16x16x32_bf16 v[116:119], v[186:189], v[202:205], v[116:119]
	v_mfma_f32_16x16x32_bf16 v[112:115], v[194:197], v[202:205], v[112:115]
	v_mfma_f32_16x16x32_bf16 v[100:103], v[186:189], v[210:213], v[100:103]
	v_mfma_f32_16x16x32_bf16 v[96:99], v[194:197], v[210:213], v[96:99]
	v_mfma_f32_16x16x32_bf16 v[84:87], v[186:189], v[218:221], v[84:87]
	v_mfma_f32_16x16x32_bf16 v[80:83], v[194:197], v[218:221], v[80:83]
	v_mfma_f32_16x16x32_bf16 v[68:71], v[186:189], v[226:229], v[68:71]
	v_mfma_f32_16x16x32_bf16 v[64:67], v[194:197], v[226:229], v[64:67]
	s_setprio 0
	s_barrier
; #define PG8_STAGE(bufoff, gbase, voff) do { _Pragma("unroll") for (int _i = 0; _i < 2; ++_i) \
;         __builtin_amdgcn_global_load_lds((const unsigned*)((const char*)(gbase) + (voff)[_i]), (LAS unsigned*)(lds + (bufoff) + ldsw + _i * 8192), 16, 0, 0); } while (0)
; #define PG8_LDA(dst, b, h) do { _Pragma("unroll") for (int m = 0; m < 4; ++m) _Pragma("unroll") for (int k = 0; k < 2; ++k) dst[m][k] = *(const LAS bf16x8*)(lds + PG8_SA(b, h) + aoff + m * 2048 + k * 1024); } while (0)
; #define PG8_MMA(ai, bj, At, Bt) do { __builtin_amdgcn_s_setprio(1); _Pragma("unroll") for (int m = 0; m < 4; ++m) _Pragma("unroll") for (int n = 0; n < 2; ++n) _Pragma("unroll") for (int k = 0; k < 2; ++k) \
;         acc[ai][bj][m][n] = __builtin_amdgcn_mfma_f32_16x16x32_bf16(Bt[n][k], At[m][k], acc[ai][bj][m][n], 0, 0, 0); __builtin_amdgcn_s_setprio(0); } while (0)
; #define PG8_WAIT_V(n) asm volatile("s_waitcnt vmcnt(" #n ")" ::: "memory")
; #define PG8_WAIT_L(n) asm volatile("s_waitcnt lgkmcnt(" #n ")" ::: "memory")
; #define PG8_BAR __builtin_amdgcn_s_barrier()
; #define PG8_SCHED __builtin_amdgcn_sched_barrier(0)
; template <class Epi, class Sched, bool ALIGN_EPI = false, bool SP2 = false>
; __device__ __forceinline__ void gemm_phase(LAS unsigned char* lds, const Gemm g, const Sched S, const Epi E) {
;     ...
;             PG8_LDA(At, 1, 1); PG8_STAGE(PG8_SB(1, 0), b3, voffB); PG8_STAGE(PG8_SB(1, 1), b3 + hstepB, voffB); PG8_STAGE(PG8_SA(1, 0), a3, voffA);
;             PG8_WAIT_V(8); PG8_WAIT_L(0); PG8_BAR; PG8_MMA(1, 0, At, B0); PG8_MMA(1, 1, At, B1); PG8_BAR; PG8_SCHED;
	s_add_i32 s14, s34, s4
	v_lshl_add_u64 v[144:145], v[144:145], 0, s[46:47]
	s_mov_b32 m0, s14
	ds_read_b128 v[198:201], v163 offset:49152
	ds_read_b128 v[202:205], v163 offset:50176
	ds_read_b128 v[206:209], v163 offset:51200
	ds_read_b128 v[210:213], v163 offset:52224
	ds_read_b128 v[214:217], v163 offset:53248
	ds_read_b128 v[218:221], v163 offset:54272
	ds_read_b128 v[222:225], v163 offset:55296
	ds_read_b128 v[226:229], v163 offset:56320
	global_load_lds_dwordx4 v[144:145], off
	s_add_i32 m0, s14, 0x2000
	s_add_u32 s12, s12, 0x40080
	v_lshl_add_u64 v[144:145], v[152:153], 0, s[46:47]
	s_addc_u32 s13, s13, 0
	s_add_i32 s14, s35, s4
	global_load_lds_dwordx4 v[144:145], off
	s_mov_b32 m0, s14
	s_nop 0
	global_load_lds_dwordx4 v132, s[12:13]
	s_add_i32 m0, s14, 0x2000
	s_nop 0
	global_load_lds_dwordx4 v128, s[12:13]
	v_lshl_add_u64 v[144:145], v[156:157], 0, s[46:47]
	s_mov_b32 m0, s33
	s_nop 0
	global_load_lds_dwordx4 v[144:145], off
	v_lshl_add_u64 v[144:145], v[160:161], 0, s[46:47]
	s_mov_b32 m0, s58
	s_nop 0
	global_load_lds_dwordx4 v[144:145], off
	s_waitcnt vmcnt(8)
	s_waitcnt lgkmcnt(0)
	s_barrier
	s_setprio 1
	s_waitcnt lgkmcnt(0)
	v_mfma_f32_16x16x32_bf16 v[60:63], v[166:169], v[198:201], v[60:63]
	v_mfma_f32_16x16x32_bf16 v[56:59], v[174:177], v[198:201], v[56:59]
	v_mfma_f32_16x16x32_bf16 v[44:47], v[166:169], v[206:209], v[44:47]
	v_mfma_f32_16x16x32_bf16 v[40:43], v[174:177], v[206:209], v[40:43]
	v_mfma_f32_16x16x32_bf16 v[28:31], v[166:169], v[214:217], v[28:31]
	v_mfma_f32_16x16x32_bf16 v[24:27], v[174:177], v[214:217], v[24:27]
	v_mfma_f32_16x16x32_bf16 v[12:15], v[166:169], v[222:225], v[12:15]
	v_mfma_f32_16x16x32_bf16 v[8:11], v[174:177], v[222:225], v[8:11]
	v_mfma_f32_16x16x32_bf16 v[60:63], v[170:173], v[202:205], v[60:63]
	v_mfma_f32_16x16x32_bf16 v[56:59], v[178:181], v[202:205], v[56:59]
	v_mfma_f32_16x16x32_bf16 v[44:47], v[170:173], v[210:213], v[44:47]
	v_mfma_f32_16x16x32_bf16 v[40:43], v[178:181], v[210:213], v[40:43]
	v_mfma_f32_16x16x32_bf16 v[28:31], v[170:173], v[218:221], v[28:31]
	v_mfma_f32_16x16x32_bf16 v[24:27], v[178:181], v[218:221], v[24:27]
	v_mfma_f32_16x16x32_bf16 v[12:15], v[170:173], v[226:229], v[12:15]
	v_mfma_f32_16x16x32_bf16 v[8:11], v[178:181], v[226:229], v[8:11]
	s_setprio 0
	s_setprio 1
	v_mfma_f32_16x16x32_bf16 v[52:55], v[182:185], v[198:201], v[52:55]
	v_mfma_f32_16x16x32_bf16 v[48:51], v[190:193], v[198:201], v[48:51]
	v_mfma_f32_16x16x32_bf16 v[36:39], v[182:185], v[206:209], v[36:39]
	v_mfma_f32_16x16x32_bf16 v[32:35], v[190:193], v[206:209], v[32:35]
	v_mfma_f32_16x16x32_bf16 v[20:23], v[182:185], v[214:217], v[20:23]
	v_mfma_f32_16x16x32_bf16 v[16:19], v[190:193], v[214:217], v[16:19]
	v_mfma_f32_16x16x32_bf16 v[4:7], v[182:185], v[222:225], v[4:7]
	v_mfma_f32_16x16x32_bf16 v[0:3], v[190:193], v[222:225], v[0:3]
	v_mfma_f32_16x16x32_bf16 v[52:55], v[186:189], v[202:205], v[52:55]
	v_mfma_f32_16x16x32_bf16 v[48:51], v[194:197], v[202:205], v[48:51]
	v_mfma_f32_16x16x32_bf16 v[36:39], v[186:189], v[210:213], v[36:39]
	v_mfma_f32_16x16x32_bf16 v[32:35], v[194:197], v[210:213], v[32:35]
	v_mfma_f32_16x16x32_bf16 v[20:23], v[186:189], v[218:221], v[20:23]
	v_mfma_f32_16x16x32_bf16 v[16:19], v[194:197], v[218:221], v[16:19]
	v_mfma_f32_16x16x32_bf16 v[4:7], v[186:189], v[226:229], v[4:7]
	v_mfma_f32_16x16x32_bf16 v[0:3], v[194:197], v[226:229], v[0:3]
	s_setprio 0
	s_barrier
	s_add_i32 s51, s51, 2
	s_add_u32 s10, s10, 0x100
	s_addc_u32 s11, s11, 0
	s_add_u32 s22, s22, 0x100
	s_addc_u32 s23, s23, 0
	s_cmp_gt_u32 s51, 13
	s_cbranch_scc0 .LBB0_1850
	s_and_b64 vcc, exec, s[48:49]
	s_cbranch_vccz .LBB0_1853
	s_barrier

; #define PG8_STAGE(bufoff, gbase, voff) do { _Pragma("unroll") for (int _i = 0; _i < 2; ++_i) \
;         __builtin_amdgcn_global_load_lds((const unsigned*)((const char*)(gbase) + (voff)[_i]), (LAS unsigned*)(lds + (bufoff) + ldsw + _i * 8192), 16, 0, 0); } while (0)
; #define PG8_LDA(dst, b, h) do { _Pragma("unroll") for (int m = 0; m < 4; ++m) _Pragma("unroll") for (int k = 0; k < 2; ++k) dst[m][k] = *(const LAS bf16x8*)(lds + PG8_SA(b, h) + aoff + m * 2048 + k * 1024); } while (0)
; #define PG8_LDB(dst, b, h) do { _Pragma("unroll") for (int n = 0; n < 2; ++n) _Pragma("unroll") for (int k = 0; k < 2; ++k) dst[n][k] = *(const LAS bf16x8*)(lds + PG8_SB(b, h) + boff + n * 2048 + k * 1024); } while (0)
; #define PG8_MMA(ai, bj, At, Bt) do { __builtin_amdgcn_s_setprio(1); _Pragma("unroll") for (int m = 0; m < 4; ++m) _Pragma("unroll") for (int n = 0; n < 2; ++n) _Pragma("unroll") for (int k = 0; k < 2; ++k) \
;         acc[ai][bj][m][n] = __builtin_amdgcn_mfma_f32_16x16x32_bf16(Bt[n][k], At[m][k], acc[ai][bj][m][n], 0, 0, 0); __builtin_amdgcn_s_setprio(0); } while (0)
; #define PG8_WAIT_V(n) asm volatile("s_waitcnt vmcnt(" #n ")" ::: "memory")
; #define PG8_WAIT_L(n) asm volatile("s_waitcnt lgkmcnt(" #n ")" ::: "memory")
; #define PG8_BAR __builtin_amdgcn_s_barrier()
; template <class Epi, class Sched, bool ALIGN_EPI = false, bool SP2 = false>
; __device__ __forceinline__ void gemm_phase(LAS unsigned char* lds, const Gemm g, const Sched S, const Epi E) {
;     ...
;             const bool last = (t == nt - 2);
;             const char* a1 = cA + (size_t)(t + 1) * kstep;
;             const char* a2 = last ? nA : cA + (size_t)(t + 2) * kstep; const char* b2 = last ? nB : cB + (size_t)(t + 2) * kstep;
;             const char* a3 = a2 + kstep; const char* b3 = b2 + kstep;
;             if (last && has_next) S.a_ready(nxt);
;             if constexpr (SP2) {
;             PG8_LDB(B0, 0, 0); PG8_LDB(B1, 0, 1); PG8_SCHED; PG8_LDA(At, 0, 0); PG8_STAGE(PG8_SA(1, 1), a1 + hstepA, voffA);
;             PG8_WAIT_V(8); PG8_WAIT_L(0); PG8_BAR; PG8_MMA(0, 0, At, B0); PG8_MMA(0, 1, At, B1); PG8_BAR; PG8_SCHED;
;             PG8_LDA(At, 0, 1); PG8_STAGE(PG8_SB(0, 0), b2, voffB); PG8_STAGE(PG8_SB(0, 1), b2 + hstepB, voffB); PG8_STAGE(PG8_SA(0, 0), a2, voffA);
;             PG8_WAIT_V(8); PG8_WAIT_L(0); PG8_BAR; PG8_MMA(1, 0, At, B0); PG8_MMA(1, 1, At, B1); PG8_BAR; PG8_SCHED;
.LBB0_1930:
	ds_read_b128 v[144:147], v155
	ds_read_b128 v[148:151], v155 offset:1024
	ds_read_b128 v[158:161], v155 offset:2048
	ds_read_b128 v[162:165], v155 offset:3072
	ds_read_b128 v[166:169], v156
	ds_read_b128 v[170:173], v156 offset:1024
	ds_read_b128 v[174:177], v156 offset:2048
	ds_read_b128 v[178:181], v156 offset:3072
	s_add_u32 s44, s42, 0x100
	s_addc_u32 s45, s43, 0
	s_cmp_eq_u32 s66, 40
	s_cselect_b32 s49, s7, s45
	s_cselect_b32 s48, s6, s44
	s_cselect_b32 s47, s39, s65
	s_cselect_b32 s46, s38, s64
	s_add_i32 m0, s21, 0xc000
	ds_read_b128 v[182:185], v157
	ds_read_b128 v[186:189], v157 offset:1024
	ds_read_b128 v[190:193], v157 offset:2048
	ds_read_b128 v[194:197], v157 offset:3072
	ds_read_b128 v[198:201], v157 offset:4096
	ds_read_b128 v[202:205], v157 offset:5120
	ds_read_b128 v[206:209], v157 offset:6144
	ds_read_b128 v[210:213], v157 offset:7168
	global_load_lds_dwordx4 v136, s[42:43]
	s_add_i32 m0, s21, 0xe000
	s_nop 0
	global_load_lds_dwordx4 v138, s[42:43]
	s_waitcnt vmcnt(8)
	s_waitcnt lgkmcnt(0)
	s_barrier
	s_setprio 1
	s_waitcnt lgkmcnt(0)
	v_mfma_f32_16x16x32_bf16 v[124:127], v[144:147], v[182:185], v[124:127]
	v_mfma_f32_16x16x32_bf16 v[120:123], v[158:161], v[182:185], v[120:123]
	v_mfma_f32_16x16x32_bf16 v[108:111], v[144:147], v[190:193], v[108:111]
	v_mfma_f32_16x16x32_bf16 v[104:107], v[158:161], v[190:193], v[104:107]
	v_mfma_f32_16x16x32_bf16 v[92:95], v[144:147], v[198:201], v[92:95]
	v_mfma_f32_16x16x32_bf16 v[88:91], v[158:161], v[198:201], v[88:91]
	v_mfma_f32_16x16x32_bf16 v[76:79], v[144:147], v[206:209], v[76:79]
	v_mfma_f32_16x16x32_bf16 v[72:75], v[158:161], v[206:209], v[72:75]
	v_mfma_f32_16x16x32_bf16 v[124:127], v[148:151], v[186:189], v[124:127]
	v_mfma_f32_16x16x32_bf16 v[120:123], v[162:165], v[186:189], v[120:123]
	v_mfma_f32_16x16x32_bf16 v[108:111], v[148:151], v[194:197], v[108:111]
	v_mfma_f32_16x16x32_bf16 v[104:107], v[162:165], v[194:197], v[104:107]
	v_mfma_f32_16x16x32_bf16 v[92:95], v[148:151], v[202:205], v[92:95]
	v_mfma_f32_16x16x32_bf16 v[88:91], v[162:165], v[202:205], v[88:91]
	v_mfma_f32_16x16x32_bf16 v[76:79], v[148:151], v[210:213], v[76:79]
	v_mfma_f32_16x16x32_bf16 v[72:75], v[162:165], v[210:213], v[72:75]
	s_setprio 0
	s_setprio 1
	v_mfma_f32_16x16x32_bf16 v[116:119], v[166:169], v[182:185], v[116:119]
	v_mfma_f32_16x16x32_bf16 v[112:115], v[174:177], v[182:185], v[112:115]
	v_mfma_f32_16x16x32_bf16 v[100:103], v[166:169], v[190:193], v[100:103]
	v_mfma_f32_16x16x32_bf16 v[96:99], v[174:177], v[190:193], v[96:99]
	v_mfma_f32_16x16x32_bf16 v[84:87], v[166:169], v[198:201], v[84:87]
	v_mfma_f32_16x16x32_bf16 v[80:83], v[174:177], v[198:201], v[80:83]
	v_mfma_f32_16x16x32_bf16 v[68:71], v[166:169], v[206:209], v[68:71]
	v_mfma_f32_16x16x32_bf16 v[64:67], v[174:177], v[206:209], v[64:67]
	v_mfma_f32_16x16x32_bf16 v[116:119], v[170:173], v[186:189], v[116:119]
	v_mfma_f32_16x16x32_bf16 v[112:115], v[178:181], v[186:189], v[112:115]
	v_mfma_f32_16x16x32_bf16 v[100:103], v[170:173], v[194:197], v[100:103]
	v_mfma_f32_16x16x32_bf16 v[96:99], v[178:181], v[194:197], v[96:99]
	v_mfma_f32_16x16x32_bf16 v[84:87], v[170:173], v[202:205], v[84:87]
	v_mfma_f32_16x16x32_bf16 v[80:83], v[178:181], v[202:205], v[80:83]
	v_mfma_f32_16x16x32_bf16 v[68:71], v[170:173], v[210:213], v[68:71]
	v_mfma_f32_16x16x32_bf16 v[64:67], v[178:181], v[210:213], v[64:67]
	s_setprio 0
	s_barrier
	s_add_i32 s34, s54, s20
	v_lshl_add_u64 v[214:215], s[46:47], 0, v[130:131]
	s_mov_b32 m0, s34
	ds_read_b128 v[182:185], v157 offset:16384
	ds_read_b128 v[186:189], v157 offset:17408
	ds_read_b128 v[190:193], v157 offset:18432
	ds_read_b128 v[194:197], v157 offset:19456
	ds_read_b128 v[198:201], v157 offset:20480
	ds_read_b128 v[202:205], v157 offset:21504
	ds_read_b128 v[206:209], v157 offset:22528
	ds_read_b128 v[210:213], v157 offset:23552
	global_load_lds_dwordx4 v[214:215], off
	s_add_i32 m0, s34, 0x2000
	s_add_u32 s34, s46, 0xb0000
	v_lshl_add_u64 v[216:217], s[46:47], 0, v[134:135]
	s_addc_u32 s35, s47, 0
	s_add_i32 s42, s55, s20
	global_load_lds_dwordx4 v[216:217], off
	s_mov_b32 m0, s42
	v_lshl_add_u64 v[220:221], s[48:49], 0, v[132:133]
	global_load_lds_dwordx4 v130, s[34:35]
	s_add_i32 m0, s42, 0x2000
	s_nop 0
	global_load_lds_dwordx4 v134, s[34:35]
	v_lshl_add_u64 v[218:219], s[48:49], 0, v[128:129]
	s_mov_b32 m0, s21
	s_nop 0
	global_load_lds_dwordx4 v[218:219], off
	s_mov_b32 m0, s29
	s_nop 0
	global_load_lds_dwordx4 v[220:221], off
	s_waitcnt vmcnt(8)
	s_waitcnt lgkmcnt(0)
	s_barrier
; #define PG8_STAGE(bufoff, gbase, voff) do { _Pragma("unroll") for (int _i = 0; _i < 2; ++_i) \
;         __builtin_amdgcn_global_load_lds((const unsigned*)((const char*)(gbase) + (voff)[_i]), (LAS unsigned*)(lds + (bufoff) + ldsw + _i * 8192), 16, 0, 0); } while (0)
; #define PG8_LDA(dst, b, h) do { _Pragma("unroll") for (int m = 0; m < 4; ++m) _Pragma("unroll") for (int k = 0; k < 2; ++k) dst[m][k] = *(const LAS bf16x8*)(lds + PG8_SA(b, h) + aoff + m * 2048 + k * 1024); } while (0)
; #define PG8_LDB(dst, b, h) do { _Pragma("unroll") for (int n = 0; n < 2; ++n) _Pragma("unroll") for (int k = 0; k < 2; ++k) dst[n][k] = *(const LAS bf16x8*)(lds + PG8_SB(b, h) + boff + n * 2048 + k * 1024); } while (0)
; #define PG8_MMA(ai, bj, At, Bt) do { __builtin_amdgcn_s_setprio(1); _Pragma("unroll") for (int m = 0; m < 4; ++m) _Pragma("unroll") for (int n = 0; n < 2; ++n) _Pragma("unroll") for (int k = 0; k < 2; ++k) \
;         acc[ai][bj][m][n] = __builtin_amdgcn_mfma_f32_16x16x32_bf16(Bt[n][k], At[m][k], acc[ai][bj][m][n], 0, 0, 0); __builtin_amdgcn_s_setprio(0); } while (0)
; #define PG8_WAIT_V(n) asm volatile("s_waitcnt vmcnt(" #n ")" ::: "memory")
; #define PG8_WAIT_L(n) asm volatile("s_waitcnt lgkmcnt(" #n ")" ::: "memory")
; #define PG8_BAR __builtin_amdgcn_s_barrier()
; #define PG8_SCHED __builtin_amdgcn_sched_barrier(0)
; template <class Epi, class Sched, bool ALIGN_EPI = false, bool SP2 = false>
; __device__ __forceinline__ void gemm_phase(LAS unsigned char* lds, const Gemm g, const Sched S, const Epi E) {
;     ...
;             PG8_WAIT_V(8); PG8_WAIT_L(0); PG8_BAR; PG8_MMA(1, 0, At, B0); PG8_MMA(1, 1, At, B1); PG8_BAR; PG8_SCHED;
;             PG8_LDB(B0, 1, 0); PG8_LDB(B1, 1, 1); PG8_SCHED; PG8_LDA(At, 1, 0); PG8_STAGE(PG8_SA(0, 1), a2 + hstepA, voffA);
;             PG8_WAIT_V(8); PG8_WAIT_L(0); PG8_BAR; PG8_MMA(0, 0, At, B0); PG8_MMA(0, 1, At, B1); PG8_BAR; PG8_SCHED;
	s_setprio 1
	s_waitcnt lgkmcnt(0)
	v_mfma_f32_16x16x32_bf16 v[60:63], v[144:147], v[182:185], v[60:63]
	v_mfma_f32_16x16x32_bf16 v[56:59], v[158:161], v[182:185], v[56:59]
	v_mfma_f32_16x16x32_bf16 v[44:47], v[144:147], v[190:193], v[44:47]
	v_mfma_f32_16x16x32_bf16 v[40:43], v[158:161], v[190:193], v[40:43]
	v_mfma_f32_16x16x32_bf16 v[28:31], v[144:147], v[198:201], v[28:31]
	v_mfma_f32_16x16x32_bf16 v[24:27], v[158:161], v[198:201], v[24:27]
	v_mfma_f32_16x16x32_bf16 v[12:15], v[144:147], v[206:209], v[12:15]
	v_mfma_f32_16x16x32_bf16 v[8:11], v[158:161], v[206:209], v[8:11]
	v_mfma_f32_16x16x32_bf16 v[60:63], v[148:151], v[186:189], v[60:63]
	v_mfma_f32_16x16x32_bf16 v[56:59], v[162:165], v[186:189], v[56:59]
	v_mfma_f32_16x16x32_bf16 v[44:47], v[148:151], v[194:197], v[44:47]
	v_mfma_f32_16x16x32_bf16 v[40:43], v[162:165], v[194:197], v[40:43]
	v_mfma_f32_16x16x32_bf16 v[28:31], v[148:151], v[202:205], v[28:31]
	v_mfma_f32_16x16x32_bf16 v[24:27], v[162:165], v[202:205], v[24:27]
	v_mfma_f32_16x16x32_bf16 v[12:15], v[148:151], v[210:213], v[12:15]
	v_mfma_f32_16x16x32_bf16 v[8:11], v[162:165], v[210:213], v[8:11]
	s_setprio 0
	s_setprio 1
	v_mfma_f32_16x16x32_bf16 v[52:55], v[166:169], v[182:185], v[52:55]
	v_mfma_f32_16x16x32_bf16 v[48:51], v[174:177], v[182:185], v[48:51]
	v_mfma_f32_16x16x32_bf16 v[36:39], v[166:169], v[190:193], v[36:39]
	v_mfma_f32_16x16x32_bf16 v[32:35], v[174:177], v[190:193], v[32:35]
	v_mfma_f32_16x16x32_bf16 v[20:23], v[166:169], v[198:201], v[20:23]
	v_mfma_f32_16x16x32_bf16 v[16:19], v[174:177], v[198:201], v[16:19]
	v_mfma_f32_16x16x32_bf16 v[4:7], v[166:169], v[206:209], v[4:7]
	v_mfma_f32_16x16x32_bf16 v[0:3], v[174:177], v[206:209], v[0:3]
	v_mfma_f32_16x16x32_bf16 v[52:55], v[170:173], v[186:189], v[52:55]
	v_mfma_f32_16x16x32_bf16 v[48:51], v[178:181], v[186:189], v[48:51]
	v_mfma_f32_16x16x32_bf16 v[36:39], v[170:173], v[194:197], v[36:39]
	v_mfma_f32_16x16x32_bf16 v[32:35], v[178:181], v[194:197], v[32:35]
	v_mfma_f32_16x16x32_bf16 v[20:23], v[170:173], v[202:205], v[20:23]
	v_mfma_f32_16x16x32_bf16 v[16:19], v[178:181], v[202:205], v[16:19]
	v_mfma_f32_16x16x32_bf16 v[4:7], v[170:173], v[210:213], v[4:7]
	v_mfma_f32_16x16x32_bf16 v[0:3], v[178:181], v[210:213], v[0:3]
	s_setprio 0
	s_barrier
	s_add_i32 s42, 0, 0x18000
	s_add_i32 s43, 0, 0x1c000
	v_add_u32_e32 v162, s42, v153
	v_add_u32_e32 v178, s43, v153
	ds_read_b128 v[144:147], v162
	ds_read_b128 v[148:151], v162 offset:1024
	ds_read_b128 v[158:161], v162 offset:2048
	ds_read_b128 v[162:165], v162 offset:3072
	ds_read_b128 v[166:169], v178
	ds_read_b128 v[170:173], v178 offset:1024
	ds_read_b128 v[174:177], v178 offset:2048
	ds_read_b128 v[178:181], v178 offset:3072
	s_add_u32 s34, s48, 0xb0000
	s_addc_u32 s35, s49, 0
	s_mov_b32 m0, s30
	ds_read_b128 v[182:185], v157 offset:32768
	ds_read_b128 v[186:189], v157 offset:33792
	ds_read_b128 v[190:193], v157 offset:34816
	ds_read_b128 v[194:197], v157 offset:35840
	ds_read_b128 v[198:201], v157 offset:36864
	ds_read_b128 v[202:205], v157 offset:37888
	ds_read_b128 v[206:209], v157 offset:38912
	ds_read_b128 v[210:213], v157 offset:39936
	global_load_lds_dwordx4 v128, s[34:35]
	s_mov_b32 m0, s31
	s_nop 0
	global_load_lds_dwordx4 v132, s[34:35]
	s_waitcnt vmcnt(8)
	s_waitcnt lgkmcnt(0)
	s_barrier
	s_setprio 1
	s_waitcnt lgkmcnt(0)
	v_mfma_f32_16x16x32_bf16 v[124:127], v[144:147], v[182:185], v[124:127]
	v_mfma_f32_16x16x32_bf16 v[120:123], v[158:161], v[182:185], v[120:123]
	v_mfma_f32_16x16x32_bf16 v[108:111], v[144:147], v[190:193], v[108:111]
	v_mfma_f32_16x16x32_bf16 v[104:107], v[158:161], v[190:193], v[104:107]
	v_mfma_f32_16x16x32_bf16 v[92:95], v[144:147], v[198:201], v[92:95]
	v_mfma_f32_16x16x32_bf16 v[88:91], v[158:161], v[198:201], v[88:91]
	v_mfma_f32_16x16x32_bf16 v[76:79], v[144:147], v[206:209], v[76:79]
	v_mfma_f32_16x16x32_bf16 v[72:75], v[158:161], v[206:209], v[72:75]
	v_mfma_f32_16x16x32_bf16 v[124:127], v[148:151], v[186:189], v[124:127]
	v_mfma_f32_16x16x32_bf16 v[120:123], v[162:165], v[186:189], v[120:123]
	v_mfma_f32_16x16x32_bf16 v[108:111], v[148:151], v[194:197], v[108:111]
	v_mfma_f32_16x16x32_bf16 v[104:107], v[162:165], v[194:197], v[104:107]
	v_mfma_f32_16x16x32_bf16 v[92:95], v[148:151], v[202:205], v[92:95]
	v_mfma_f32_16x16x32_bf16 v[88:91], v[162:165], v[202:205], v[88:91]
	v_mfma_f32_16x16x32_bf16 v[76:79], v[148:151], v[210:213], v[76:79]
	v_mfma_f32_16x16x32_bf16 v[72:75], v[162:165], v[210:213], v[72:75]
	s_setprio 0
	s_setprio 1
	v_mfma_f32_16x16x32_bf16 v[116:119], v[166:169], v[182:185], v[116:119]
	v_mfma_f32_16x16x32_bf16 v[112:115], v[174:177], v[182:185], v[112:115]
	v_mfma_f32_16x16x32_bf16 v[100:103], v[166:169], v[190:193], v[100:103]
	v_mfma_f32_16x16x32_bf16 v[96:99], v[174:177], v[190:193], v[96:99]
	v_mfma_f32_16x16x32_bf16 v[84:87], v[166:169], v[198:201], v[84:87]
	v_mfma_f32_16x16x32_bf16 v[80:83], v[174:177], v[198:201], v[80:83]
	v_mfma_f32_16x16x32_bf16 v[68:71], v[166:169], v[206:209], v[68:71]
	v_mfma_f32_16x16x32_bf16 v[64:67], v[174:177], v[206:209], v[64:67]
	v_mfma_f32_16x16x32_bf16 v[116:119], v[170:173], v[186:189], v[116:119]
	v_mfma_f32_16x16x32_bf16 v[112:115], v[178:181], v[186:189], v[112:115]
	v_mfma_f32_16x16x32_bf16 v[100:103], v[170:173], v[194:197], v[100:103]
	v_mfma_f32_16x16x32_bf16 v[96:99], v[178:181], v[194:197], v[96:99]
	v_mfma_f32_16x16x32_bf16 v[84:87], v[170:173], v[202:205], v[84:87]
	v_mfma_f32_16x16x32_bf16 v[80:83], v[178:181], v[202:205], v[80:83]
	v_mfma_f32_16x16x32_bf16 v[68:71], v[170:173], v[210:213], v[68:71]
	v_mfma_f32_16x16x32_bf16 v[64:67], v[178:181], v[210:213], v[64:67]
	s_setprio 0
	s_barrier
; #define PG8_STAGE(bufoff, gbase, voff) do { _Pragma("unroll") for (int _i = 0; _i < 2; ++_i) \
;         __builtin_amdgcn_global_load_lds((const unsigned*)((const char*)(gbase) + (voff)[_i]), (LAS unsigned*)(lds + (bufoff) + ldsw + _i * 8192), 16, 0, 0); } while (0)
; #define PG8_LDA(dst, b, h) do { _Pragma("unroll") for (int m = 0; m < 4; ++m) _Pragma("unroll") for (int k = 0; k < 2; ++k) dst[m][k] = *(const LAS bf16x8*)(lds + PG8_SA(b, h) + aoff + m * 2048 + k * 1024); } while (0)
; #define PG8_MMA(ai, bj, At, Bt) do { __builtin_amdgcn_s_setprio(1); _Pragma("unroll") for (int m = 0; m < 4; ++m) _Pragma("unroll") for (int n = 0; n < 2; ++n) _Pragma("unroll") for (int k = 0; k < 2; ++k) \
;         acc[ai][bj][m][n] = __builtin_amdgcn_mfma_f32_16x16x32_bf16(Bt[n][k], At[m][k], acc[ai][bj][m][n], 0, 0, 0); __builtin_amdgcn_s_setprio(0); } while (0)
; #define PG8_WAIT_V(n) asm volatile("s_waitcnt vmcnt(" #n ")" ::: "memory")
; #define PG8_WAIT_L(n) asm volatile("s_waitcnt lgkmcnt(" #n ")" ::: "memory")
; #define PG8_BAR __builtin_amdgcn_s_barrier()
; #define PG8_SCHED __builtin_amdgcn_sched_barrier(0)
; template <class Epi, class Sched, bool ALIGN_EPI = false, bool SP2 = false>
; __device__ __forceinline__ void gemm_phase(LAS unsigned char* lds, const Gemm g, const Sched S, const Epi E) {
;     ...
;             PG8_LDA(At, 1, 1); PG8_STAGE(PG8_SB(1, 0), b3, voffB); PG8_STAGE(PG8_SB(1, 1), b3 + hstepB, voffB); PG8_STAGE(PG8_SA(1, 0), a3, voffA);
;             PG8_WAIT_V(8); PG8_WAIT_L(0); PG8_BAR; PG8_MMA(1, 0, At, B0); PG8_MMA(1, 1, At, B1); PG8_BAR; PG8_SCHED;
	s_add_i32 s34, s42, s20
	v_lshl_add_u64 v[214:215], v[214:215], 0, s[12:13]
	s_mov_b32 m0, s34
	ds_read_b128 v[182:185], v157 offset:49152
	ds_read_b128 v[186:189], v157 offset:50176
	ds_read_b128 v[190:193], v157 offset:51200
	ds_read_b128 v[194:197], v157 offset:52224
	ds_read_b128 v[198:201], v157 offset:53248
	ds_read_b128 v[202:205], v157 offset:54272
	ds_read_b128 v[206:209], v157 offset:55296
	ds_read_b128 v[210:213], v157 offset:56320
	global_load_lds_dwordx4 v[214:215], off
	s_add_i32 m0, s34, 0x2000
	s_add_u32 s34, s46, 0xb0080
	v_lshl_add_u64 v[214:215], v[216:217], 0, s[12:13]
	s_addc_u32 s35, s47, 0
	s_add_i32 s42, s43, s20
	global_load_lds_dwordx4 v[214:215], off
	s_mov_b32 m0, s42
	s_nop 0
	global_load_lds_dwordx4 v130, s[34:35]
	s_add_i32 m0, s42, 0x2000
	s_nop 0
	global_load_lds_dwordx4 v134, s[34:35]
	v_lshl_add_u64 v[214:215], v[218:219], 0, s[12:13]
	s_mov_b32 m0, s50
	s_nop 0
	global_load_lds_dwordx4 v[214:215], off
	v_lshl_add_u64 v[214:215], v[220:221], 0, s[12:13]
	s_mov_b32 m0, s51
	s_nop 0
	global_load_lds_dwordx4 v[214:215], off
	s_waitcnt vmcnt(8)
	s_waitcnt lgkmcnt(0)
	s_barrier
	s_setprio 1
	s_waitcnt lgkmcnt(0)
	v_mfma_f32_16x16x32_bf16 v[60:63], v[144:147], v[182:185], v[60:63]
	v_mfma_f32_16x16x32_bf16 v[56:59], v[158:161], v[182:185], v[56:59]
	v_mfma_f32_16x16x32_bf16 v[44:47], v[144:147], v[190:193], v[44:47]
	v_mfma_f32_16x16x32_bf16 v[40:43], v[158:161], v[190:193], v[40:43]
	v_mfma_f32_16x16x32_bf16 v[28:31], v[144:147], v[198:201], v[28:31]
	v_mfma_f32_16x16x32_bf16 v[24:27], v[158:161], v[198:201], v[24:27]
	v_mfma_f32_16x16x32_bf16 v[12:15], v[144:147], v[206:209], v[12:15]
	v_mfma_f32_16x16x32_bf16 v[8:11], v[158:161], v[206:209], v[8:11]
	v_mfma_f32_16x16x32_bf16 v[60:63], v[148:151], v[186:189], v[60:63]
	v_mfma_f32_16x16x32_bf16 v[56:59], v[162:165], v[186:189], v[56:59]
	v_mfma_f32_16x16x32_bf16 v[44:47], v[148:151], v[194:197], v[44:47]
	v_mfma_f32_16x16x32_bf16 v[40:43], v[162:165], v[194:197], v[40:43]
	v_mfma_f32_16x16x32_bf16 v[28:31], v[148:151], v[202:205], v[28:31]
	v_mfma_f32_16x16x32_bf16 v[24:27], v[162:165], v[202:205], v[24:27]
	v_mfma_f32_16x16x32_bf16 v[12:15], v[148:151], v[210:213], v[12:15]
	v_mfma_f32_16x16x32_bf16 v[8:11], v[162:165], v[210:213], v[8:11]
	s_setprio 0
	s_setprio 1
	v_mfma_f32_16x16x32_bf16 v[52:55], v[166:169], v[182:185], v[52:55]
	v_mfma_f32_16x16x32_bf16 v[48:51], v[174:177], v[182:185], v[48:51]
	v_mfma_f32_16x16x32_bf16 v[36:39], v[166:169], v[190:193], v[36:39]
	v_mfma_f32_16x16x32_bf16 v[32:35], v[174:177], v[190:193], v[32:35]
	v_mfma_f32_16x16x32_bf16 v[20:23], v[166:169], v[198:201], v[20:23]
	v_mfma_f32_16x16x32_bf16 v[16:19], v[174:177], v[198:201], v[16:19]
	v_mfma_f32_16x16x32_bf16 v[4:7], v[166:169], v[206:209], v[4:7]
	v_mfma_f32_16x16x32_bf16 v[0:3], v[174:177], v[206:209], v[0:3]
	v_mfma_f32_16x16x32_bf16 v[52:55], v[170:173], v[186:189], v[52:55]
	v_mfma_f32_16x16x32_bf16 v[48:51], v[178:181], v[186:189], v[48:51]
	v_mfma_f32_16x16x32_bf16 v[36:39], v[170:173], v[194:197], v[36:39]
	v_mfma_f32_16x16x32_bf16 v[32:35], v[178:181], v[194:197], v[32:35]
	v_mfma_f32_16x16x32_bf16 v[20:23], v[170:173], v[202:205], v[20:23]
	v_mfma_f32_16x16x32_bf16 v[16:19], v[178:181], v[202:205], v[16:19]
	v_mfma_f32_16x16x32_bf16 v[4:7], v[170:173], v[210:213], v[4:7]
	v_mfma_f32_16x16x32_bf16 v[0:3], v[178:181], v[210:213], v[0:3]
	s_setprio 0
	s_barrier
	s_add_i32 s66, s66, 2
	s_add_u32 s64, s64, 0x100
	s_addc_u32 s65, s65, 0
	s_cmp_gt_u32 s66, 41
	s_mov_b64 s[42:43], s[44:45]
	s_cbranch_scc0 .LBB0_1930
	s_and_b64 vcc, exec, s[14:15]
	s_cbranch_vccz .LBB0_1933
	s_barrier
